# GLA sample: non-temporal hint on the once-read / once-written f32 state stream (on top of new P7 small-tile loop)
# baseline (speedup 1.0000x reference)
; __device__ __forceinline__ void gla_sample_unit(const Args& a, unsigned char* lds, int unit, int tid) {
;     ...
;     f32x4 sb[2][8];
; #pragma unroll
;     for (int i = 0; i < 8; ++i) sb[0][i] = *(const f32x4*)(S0 + (size_t)(i * 4 + kq) * 512 + vc);
; #pragma unroll
;     for (int g = 0; g < 8; ++g) {
;         if (g + 1 < 8) {
; #pragma unroll
;             for (int i = 0; i < 8; ++i) sb[(g + 1) & 1][i] = *(const f32x4*)(S0 + (size_t)(((g + 1) * 8 + i) * 4 + kq) * 512 + vc); }
; #pragma unroll
;         for (int i = 0; i < 8; ++i) { const int k = (g * 8 + i) * 4 + kq; const f32x4 s = sb[g & 1][i];
;             const f32x4 qv = *(const f32x4*)(Q4 + k * 4), kd = *(const f32x4*)(KD4 + k * 4); const float dec = DECS[k];
;             f32x4 sn = s * dec;
; #pragma unroll
;             for (int t = 0; t < 4; ++t) { sn += vr[t] * kd[t]; o[t] += s * qv[t]; }
;             *(f32x4*)(SN + (size_t)k * 512 + vc) = sn; } }
.LBB0_390:
	s_or_b64 exec, exec, s[0:1]
	v_lshl_add_u64 v[110:111], v[102:103], 0, v[100:101]
	v_add_co_u32_e32 v16, vcc, 0x2000, v110
	ds_read_b128 v[12:15], v140 offset:13440
	ds_read_b128 v[8:11], v140 offset:15488
	ds_read_b128 v[4:7], v140 offset:17536
	s_waitcnt lgkmcnt(3)
	ds_read_b128 v[0:3], v140 offset:19584
	v_addc_co_u32_e32 v17, vcc, 0, v111, vcc
	global_load_dwordx4 v[76:79], v[110:111], off nt
	global_load_dwordx4 v[64:67], v[16:17], off nt
	v_add_co_u32_e32 v16, vcc, 0x4000, v110
	v_add_u32_e32 v107, 0x3000, v141
	s_nop 0
	v_addc_co_u32_e32 v17, vcc, 0, v111, vcc
	v_add_co_u32_e32 v18, vcc, 0x6000, v110
	s_mov_b32 s0, 0xb600000
	s_nop 0
	v_addc_co_u32_e32 v19, vcc, 0, v111, vcc
	global_load_dwordx4 v[56:59], v[16:17], off nt
	global_load_dwordx4 v[48:51], v[18:19], off nt
	v_add_co_u32_e32 v16, vcc, 0x8000, v110
	s_nop 1
	v_addc_co_u32_e32 v17, vcc, 0, v111, vcc
	v_add_co_u32_e32 v18, vcc, 0xa000, v110
	s_nop 1
	v_addc_co_u32_e32 v19, vcc, 0, v111, vcc
	global_load_dwordx4 v[40:43], v[16:17], off nt
	global_load_dwordx4 v[32:35], v[18:19], off nt
	v_add_co_u32_e32 v16, vcc, 0xc000, v110
	s_nop 1
	v_addc_co_u32_e32 v17, vcc, 0, v111, vcc
	v_add_co_u32_e32 v18, vcc, 0xe000, v110
	s_nop 1
	v_addc_co_u32_e32 v19, vcc, 0, v111, vcc
	global_load_dwordx4 v[24:27], v[16:17], off nt
	s_nop 0
	global_load_dwordx4 v[16:19], v[18:19], off nt
	v_add_co_u32_e32 v20, vcc, 0x10000, v110
	s_nop 1
	v_addc_co_u32_e32 v21, vcc, 0, v111, vcc
	v_add_co_u32_e32 v22, vcc, 0x12000, v110
	s_nop 1
	v_addc_co_u32_e32 v23, vcc, 0, v111, vcc
	global_load_dwordx4 v[72:75], v[20:21], off nt
	global_load_dwordx4 v[68:71], v[22:23], off nt
	v_add_co_u32_e32 v20, vcc, 0x14000, v110
	s_nop 1
	v_addc_co_u32_e32 v21, vcc, 0, v111, vcc
	v_add_co_u32_e32 v22, vcc, 0x16000, v110
	s_nop 1
	v_addc_co_u32_e32 v23, vcc, 0, v111, vcc
	global_load_dwordx4 v[60:63], v[20:21], off nt
	global_load_dwordx4 v[52:55], v[22:23], off nt
	v_add_co_u32_e32 v20, vcc, 0x18000, v110
	s_nop 1
	v_addc_co_u32_e32 v21, vcc, 0, v111, vcc
	v_add_co_u32_e32 v22, vcc, 0x1a000, v110
	s_nop 1
	v_addc_co_u32_e32 v23, vcc, 0, v111, vcc
	global_load_dwordx4 v[44:47], v[20:21], off nt
	global_load_dwordx4 v[36:39], v[22:23], off nt
	ds_read2_b32 v[116:117], v107 offset1:4
	ds_read_b128 v[80:83], v138
	ds_read_b128 v[112:115], v138 offset:4096
	v_add_co_u32_e32 v20, vcc, 0x1c000, v110
	s_waitcnt vmcnt(13) lgkmcnt(2)
	v_pk_mul_f32 v[108:109], v[76:77], v[116:117] op_sel_hi:[1,0]
	v_pk_mul_f32 v[118:119], v[78:79], v[116:117] op_sel_hi:[1,0]
	s_waitcnt lgkmcnt(0)
	v_pk_fma_f32 v[108:109], v[12:13], v[112:113], v[108:109] op_sel_hi:[1,0,1]
	v_pk_fma_f32 v[118:119], v[14:15], v[112:113], v[118:119] op_sel_hi:[1,0,1]
	v_addc_co_u32_e32 v21, vcc, 0, v111, vcc
	v_pk_fma_f32 v[108:109], v[8:9], v[112:113], v[108:109] op_sel:[0,1,0]
	v_pk_fma_f32 v[112:113], v[10:11], v[112:113], v[118:119] op_sel:[0,1,0]
	v_add_co_u32_e32 v22, vcc, 0x1e000, v110
	v_pk_fma_f32 v[120:121], v[78:79], v[80:81], 0 op_sel_hi:[1,0,0]
	v_pk_fma_f32 v[122:123], v[76:77], v[80:81], 0 op_sel_hi:[1,0,0]
	v_pk_fma_f32 v[118:119], v[78:79], v[80:81], 0 op_sel:[0,1,0] op_sel_hi:[1,1,0]
	v_pk_fma_f32 v[222:223], v[76:77], v[80:81], 0 op_sel:[0,1,0] op_sel_hi:[1,1,0]
	v_pk_fma_f32 v[80:81], v[6:7], v[114:115], v[112:113] op_sel_hi:[1,0,1]
	v_pk_fma_f32 v[108:109], v[4:5], v[114:115], v[108:109] op_sel_hi:[1,0,1]
	v_pk_fma_f32 v[224:225], v[78:79], v[82:83], 0 op_sel_hi:[1,0,0]
	v_pk_fma_f32 v[226:227], v[76:77], v[82:83], 0 op_sel_hi:[1,0,0]
	v_mov_b32_e32 v82, v115
	v_addc_co_u32_e32 v23, vcc, 0, v111, vcc
	v_pk_fma_f32 v[112:113], v[0:1], v[82:83], v[108:109] op_sel_hi:[1,0,1]
	v_pk_fma_f32 v[114:115], v[2:3], v[82:83], v[80:81] op_sel_hi:[1,0,1]
	v_mov_b32_e32 v80, v83
	v_lshl_add_u64 v[108:109], v[104:105], 0, v[100:101]
	v_pk_fma_f32 v[228:229], v[78:79], v[80:81], 0 op_sel_hi:[1,0,0]
	v_add_co_u32_e32 v78, vcc, s0, v108
	global_load_dwordx4 v[28:31], v[20:21], off nt
	s_nop 0
	global_load_dwordx4 v[20:23], v[22:23], off nt
	v_addc_co_u32_e32 v79, vcc, 0, v109, vcc
	global_store_dwordx4 v[78:79], v[112:115], off nt
	v_pk_fma_f32 v[76:77], v[76:77], v[80:81], 0 op_sel_hi:[1,0,0]
	ds_read_b128 v[80:83], v142
	ds_read_b128 v[112:115], v142 offset:4096
	ds_read2_b32 v[230:231], v107 offset0:8 offset1:12
	ds_read2_b32 v[78:79], v107 offset0:16 offset1:20
	v_mov_b32_e32 v116, v117
	s_waitcnt vmcnt(15)
	v_pk_mul_f32 v[232:233], v[66:67], v[116:117] op_sel_hi:[1,0]
	v_pk_mul_f32 v[116:117], v[64:65], v[116:117] op_sel_hi:[1,0]
	s_waitcnt lgkmcnt(2)
	v_pk_fma_f32 v[232:233], v[14:15], v[112:113], v[232:233] op_sel_hi:[1,0,1]
	v_pk_fma_f32 v[116:117], v[12:13], v[112:113], v[116:117] op_sel_hi:[1,0,1]
	v_pk_fma_f32 v[232:233], v[10:11], v[112:113], v[232:233] op_sel:[0,1,0]
	v_pk_fma_f32 v[120:121], v[66:67], v[80:81], v[120:121] op_sel_hi:[1,0,1]
	v_pk_fma_f32 v[122:123], v[64:65], v[80:81], v[122:123] op_sel_hi:[1,0,1]
	v_pk_fma_f32 v[112:113], v[8:9], v[112:113], v[116:117] op_sel:[0,1,0]
	v_pk_fma_f32 v[116:117], v[66:67], v[80:81], v[118:119] op_sel:[0,1,0]
	v_pk_fma_f32 v[118:119], v[64:65], v[80:81], v[222:223] op_sel:[0,1,0]
	v_pk_fma_f32 v[80:81], v[6:7], v[114:115], v[232:233] op_sel_hi:[1,0,1]
	v_pk_fma_f32 v[222:223], v[64:65], v[82:83], v[226:227] op_sel_hi:[1,0,1]
	v_pk_fma_f32 v[224:225], v[66:67], v[82:83], v[224:225] op_sel_hi:[1,0,1]
	v_mov_b32_e32 v82, v115
	v_pk_fma_f32 v[112:113], v[4:5], v[114:115], v[112:113] op_sel_hi:[1,0,1]
	v_pk_fma_f32 v[114:115], v[2:3], v[82:83], v[80:81] op_sel_hi:[1,0,1]
	v_mov_b32_e32 v80, v83
	v_pk_fma_f32 v[112:113], v[0:1], v[82:83], v[112:113] op_sel_hi:[1,0,1]
	v_pk_fma_f32 v[76:77], v[64:65], v[80:81], v[76:77] op_sel_hi:[1,0,1]
	v_pk_fma_f32 v[226:227], v[66:67], v[80:81], v[228:229] op_sel_hi:[1,0,1]
	ds_read_b128 v[64:67], v143
	ds_read_b128 v[80:83], v143 offset:4096
	s_mov_b32 s0, 0xb602000
	v_add_co_u32_e32 v228, vcc, s0, v108
	s_waitcnt vmcnt(14) lgkmcnt(1)
; __device__ __forceinline__ void gla_sample_unit(const Args& a, unsigned char* lds, int unit, int tid) {
;     ...
;         for (int i = 0; i < 8; ++i) { const int k = (g * 8 + i) * 4 + kq; const f32x4 s = sb[g & 1][i];
;             const f32x4 qv = *(const f32x4*)(Q4 + k * 4), kd = *(const f32x4*)(KD4 + k * 4); const float dec = DECS[k];
;             f32x4 sn = s * dec;
; #pragma unroll
;             for (int t = 0; t < 4; ++t) { sn += vr[t] * kd[t]; o[t] += s * qv[t]; }
;             *(f32x4*)(SN + (size_t)k * 512 + vc) = sn; } }
	v_pk_fma_f32 v[120:121], v[58:59], v[64:65], v[120:121] op_sel_hi:[1,0,1]
	v_addc_co_u32_e32 v229, vcc, 0, v109, vcc
	global_store_dwordx4 v[228:229], v[112:115], off nt
	v_pk_fma_f32 v[122:123], v[56:57], v[64:65], v[122:123] op_sel_hi:[1,0,1]
	s_mov_b32 s0, 0xb604000
	v_pk_mul_f32 v[112:113], v[58:59], v[230:231] op_sel_hi:[1,0]
	v_pk_mul_f32 v[114:115], v[56:57], v[230:231] op_sel_hi:[1,0]
	s_waitcnt lgkmcnt(0)
	v_pk_fma_f32 v[112:113], v[14:15], v[80:81], v[112:113] op_sel_hi:[1,0,1]
	v_pk_fma_f32 v[114:115], v[12:13], v[80:81], v[114:115] op_sel_hi:[1,0,1]
	v_pk_fma_f32 v[112:113], v[10:11], v[80:81], v[112:113] op_sel:[0,1,0]
	v_pk_fma_f32 v[80:81], v[8:9], v[80:81], v[114:115] op_sel:[0,1,0]
	v_pk_fma_f32 v[114:115], v[58:59], v[64:65], v[116:117] op_sel:[0,1,0]
	v_pk_fma_f32 v[116:117], v[56:57], v[64:65], v[118:119] op_sel:[0,1,0]
	v_pk_fma_f32 v[64:65], v[6:7], v[82:83], v[112:113] op_sel_hi:[1,0,1]
	v_pk_fma_f32 v[112:113], v[58:59], v[66:67], v[224:225] op_sel_hi:[1,0,1]
	v_pk_fma_f32 v[118:119], v[56:57], v[66:67], v[222:223] op_sel_hi:[1,0,1]
	v_mov_b32_e32 v66, v83
	v_pk_fma_f32 v[80:81], v[4:5], v[82:83], v[80:81] op_sel_hi:[1,0,1]
	v_pk_fma_f32 v[82:83], v[2:3], v[66:67], v[64:65] op_sel_hi:[1,0,1]
	v_mov_b32_e32 v64, v67
	v_pk_fma_f32 v[80:81], v[0:1], v[66:67], v[80:81] op_sel_hi:[1,0,1]
	v_pk_fma_f32 v[222:223], v[58:59], v[64:65], v[226:227] op_sel_hi:[1,0,1]
	v_pk_fma_f32 v[76:77], v[56:57], v[64:65], v[76:77] op_sel_hi:[1,0,1]
	ds_read_b128 v[56:59], v144
	ds_read_b128 v[64:67], v144 offset:4096
	v_add_co_u32_e32 v224, vcc, s0, v108
	s_mov_b32 s0, 0xb606000
	s_nop 0
	v_addc_co_u32_e32 v225, vcc, 0, v109, vcc
	global_store_dwordx4 v[224:225], v[80:83], off nt
	s_waitcnt vmcnt(15) lgkmcnt(1)
	v_pk_fma_f32 v[120:121], v[50:51], v[56:57], v[120:121] op_sel_hi:[1,0,1]
	v_pk_fma_f32 v[122:123], v[48:49], v[56:57], v[122:123] op_sel_hi:[1,0,1]
	v_mov_b32_e32 v80, v231
	v_pk_mul_f32 v[82:83], v[50:51], v[80:81] op_sel_hi:[1,0]
	v_pk_mul_f32 v[80:81], v[48:49], v[80:81] op_sel_hi:[1,0]
	s_waitcnt lgkmcnt(0)
	v_pk_fma_f32 v[82:83], v[14:15], v[64:65], v[82:83] op_sel_hi:[1,0,1]
	v_pk_fma_f32 v[80:81], v[12:13], v[64:65], v[80:81] op_sel_hi:[1,0,1]
	v_pk_fma_f32 v[82:83], v[10:11], v[64:65], v[82:83] op_sel:[0,1,0]
	v_pk_fma_f32 v[64:65], v[8:9], v[64:65], v[80:81] op_sel:[0,1,0]
	v_pk_fma_f32 v[80:81], v[50:51], v[56:57], v[114:115] op_sel:[0,1,0]
	v_pk_fma_f32 v[114:115], v[48:49], v[56:57], v[116:117] op_sel:[0,1,0]
	v_pk_fma_f32 v[56:57], v[6:7], v[66:67], v[82:83] op_sel_hi:[1,0,1]
	v_pk_fma_f32 v[82:83], v[50:51], v[58:59], v[112:113] op_sel_hi:[1,0,1]
	v_pk_fma_f32 v[112:113], v[48:49], v[58:59], v[118:119] op_sel_hi:[1,0,1]
	v_mov_b32_e32 v58, v67
	v_pk_fma_f32 v[64:65], v[4:5], v[66:67], v[64:65] op_sel_hi:[1,0,1]
	v_pk_fma_f32 v[66:67], v[2:3], v[58:59], v[56:57] op_sel_hi:[1,0,1]
	v_mov_b32_e32 v56, v59
	v_pk_fma_f32 v[64:65], v[0:1], v[58:59], v[64:65] op_sel_hi:[1,0,1]
	v_pk_fma_f32 v[116:117], v[50:51], v[56:57], v[222:223] op_sel_hi:[1,0,1]
	v_pk_fma_f32 v[76:77], v[48:49], v[56:57], v[76:77] op_sel_hi:[1,0,1]
	ds_read_b128 v[48:51], v145
	ds_read_b128 v[56:59], v145 offset:4096
	v_add_co_u32_e32 v118, vcc, s0, v108
	s_mov_b32 s0, 0xb608000
	s_nop 0
	v_addc_co_u32_e32 v119, vcc, 0, v109, vcc
	global_store_dwordx4 v[118:119], v[64:67], off nt
	s_waitcnt vmcnt(15) lgkmcnt(1)
	v_pk_fma_f32 v[118:119], v[42:43], v[48:49], v[120:121] op_sel_hi:[1,0,1]
	v_pk_fma_f32 v[120:121], v[40:41], v[48:49], v[122:123] op_sel_hi:[1,0,1]
	v_pk_mul_f32 v[64:65], v[42:43], v[78:79] op_sel_hi:[1,0]
	v_pk_mul_f32 v[66:67], v[40:41], v[78:79] op_sel_hi:[1,0]
	s_waitcnt lgkmcnt(0)
	v_pk_fma_f32 v[64:65], v[14:15], v[56:57], v[64:65] op_sel_hi:[1,0,1]
	v_pk_fma_f32 v[66:67], v[12:13], v[56:57], v[66:67] op_sel_hi:[1,0,1]
	v_pk_fma_f32 v[64:65], v[10:11], v[56:57], v[64:65] op_sel:[0,1,0]
	v_pk_fma_f32 v[56:57], v[8:9], v[56:57], v[66:67] op_sel:[0,1,0]
	v_pk_fma_f32 v[66:67], v[42:43], v[48:49], v[80:81] op_sel:[0,1,0]
	v_pk_fma_f32 v[80:81], v[40:41], v[48:49], v[114:115] op_sel:[0,1,0]
	v_pk_fma_f32 v[48:49], v[6:7], v[58:59], v[64:65] op_sel_hi:[1,0,1]
	v_pk_fma_f32 v[64:65], v[42:43], v[50:51], v[82:83] op_sel_hi:[1,0,1]
	v_pk_fma_f32 v[82:83], v[40:41], v[50:51], v[112:113] op_sel_hi:[1,0,1]
	v_mov_b32_e32 v50, v59
	v_pk_fma_f32 v[56:57], v[4:5], v[58:59], v[56:57] op_sel_hi:[1,0,1]
	v_pk_fma_f32 v[58:59], v[2:3], v[50:51], v[48:49] op_sel_hi:[1,0,1]
	v_mov_b32_e32 v48, v51
	v_pk_fma_f32 v[114:115], v[40:41], v[48:49], v[76:77] op_sel_hi:[1,0,1]
	v_add_co_u32_e32 v40, vcc, s0, v108
	v_pk_fma_f32 v[56:57], v[0:1], v[50:51], v[56:57] op_sel_hi:[1,0,1]
	s_nop 0
	v_addc_co_u32_e32 v41, vcc, 0, v109, vcc
	global_store_dwordx4 v[40:41], v[56:59], off nt
	v_pk_fma_f32 v[112:113], v[42:43], v[48:49], v[116:117] op_sel_hi:[1,0,1]
	ds_read_b128 v[40:43], v146
	ds_read_b128 v[48:51], v146 offset:4096
	ds_read2_b32 v[56:57], v107 offset0:24 offset1:28
	ds_read2_b32 v[76:77], v107 offset0:32 offset1:36
	v_mov_b32_e32 v58, v79
	s_waitcnt vmcnt(15)
	v_pk_mul_f32 v[78:79], v[34:35], v[58:59] op_sel_hi:[1,0]
	v_pk_mul_f32 v[58:59], v[32:33], v[58:59] op_sel_hi:[1,0]
	s_waitcnt lgkmcnt(2)
; __device__ __forceinline__ void gla_sample_unit(const Args& a, unsigned char* lds, int unit, int tid) {
;     ...
;     f32x4 sb[2][8];
; #pragma unroll
;     for (int i = 0; i < 8; ++i) sb[0][i] = *(const f32x4*)(S0 + (size_t)(i * 4 + kq) * 512 + vc);
; #pragma unroll
;     for (int g = 0; g < 8; ++g) {
;         if (g + 1 < 8) {
; #pragma unroll
;             for (int i = 0; i < 8; ++i) sb[(g + 1) & 1][i] = *(const f32x4*)(S0 + (size_t)(((g + 1) * 8 + i) * 4 + kq) * 512 + vc); }
; #pragma unroll
;         for (int i = 0; i < 8; ++i) { const int k = (g * 8 + i) * 4 + kq; const f32x4 s = sb[g & 1][i];
;             const f32x4 qv = *(const f32x4*)(Q4 + k * 4), kd = *(const f32x4*)(KD4 + k * 4); const float dec = DECS[k];
;             f32x4 sn = s * dec;
; #pragma unroll
;             for (int t = 0; t < 4; ++t) { sn += vr[t] * kd[t]; o[t] += s * qv[t]; }
;             *(f32x4*)(SN + (size_t)k * 512 + vc) = sn; } }
	v_pk_fma_f32 v[78:79], v[14:15], v[48:49], v[78:79] op_sel_hi:[1,0,1]
	v_pk_fma_f32 v[58:59], v[12:13], v[48:49], v[58:59] op_sel_hi:[1,0,1]
	v_pk_fma_f32 v[78:79], v[10:11], v[48:49], v[78:79] op_sel:[0,1,0]
	v_pk_fma_f32 v[116:117], v[34:35], v[40:41], v[118:119] op_sel_hi:[1,0,1]
	v_pk_fma_f32 v[118:119], v[32:33], v[40:41], v[120:121] op_sel_hi:[1,0,1]
	v_pk_fma_f32 v[48:49], v[8:9], v[48:49], v[58:59] op_sel:[0,1,0]
	v_pk_fma_f32 v[58:59], v[34:35], v[40:41], v[66:67] op_sel:[0,1,0]
	v_pk_fma_f32 v[66:67], v[32:33], v[40:41], v[80:81] op_sel:[0,1,0]
	v_pk_fma_f32 v[40:41], v[6:7], v[50:51], v[78:79] op_sel_hi:[1,0,1]
	v_pk_fma_f32 v[64:65], v[34:35], v[42:43], v[64:65] op_sel_hi:[1,0,1]
	v_pk_fma_f32 v[78:79], v[32:33], v[42:43], v[82:83] op_sel_hi:[1,0,1]
	v_mov_b32_e32 v42, v51
	v_pk_fma_f32 v[48:49], v[4:5], v[50:51], v[48:49] op_sel_hi:[1,0,1]
	v_pk_fma_f32 v[50:51], v[2:3], v[42:43], v[40:41] op_sel_hi:[1,0,1]
	v_mov_b32_e32 v40, v43
	v_pk_fma_f32 v[48:49], v[0:1], v[42:43], v[48:49] op_sel_hi:[1,0,1]
	v_pk_fma_f32 v[80:81], v[34:35], v[40:41], v[112:113] op_sel_hi:[1,0,1]
	v_pk_fma_f32 v[82:83], v[32:33], v[40:41], v[114:115] op_sel_hi:[1,0,1]
	ds_read_b128 v[32:35], v147
	ds_read_b128 v[40:43], v147 offset:4096
	s_mov_b32 s0, 0xb60a000
	v_add_co_u32_e32 v112, vcc, s0, v108
	s_waitcnt vmcnt(14) lgkmcnt(1)
	v_pk_fma_f32 v[114:115], v[24:25], v[32:33], v[118:119] op_sel_hi:[1,0,1]
	v_addc_co_u32_e32 v113, vcc, 0, v109, vcc
	global_store_dwordx4 v[112:113], v[48:51], off nt
	v_pk_fma_f32 v[112:113], v[26:27], v[32:33], v[116:117] op_sel_hi:[1,0,1]
	s_mov_b32 s0, 0xb60c000
	v_pk_mul_f32 v[48:49], v[26:27], v[56:57] op_sel_hi:[1,0]
	v_pk_mul_f32 v[50:51], v[24:25], v[56:57] op_sel_hi:[1,0]
	s_waitcnt lgkmcnt(0)
	v_pk_fma_f32 v[48:49], v[14:15], v[40:41], v[48:49] op_sel_hi:[1,0,1]
	v_pk_fma_f32 v[50:51], v[12:13], v[40:41], v[50:51] op_sel_hi:[1,0,1]
	v_pk_fma_f32 v[48:49], v[10:11], v[40:41], v[48:49] op_sel:[0,1,0]
	v_pk_fma_f32 v[40:41], v[8:9], v[40:41], v[50:51] op_sel:[0,1,0]
	v_pk_fma_f32 v[50:51], v[26:27], v[32:33], v[58:59] op_sel:[0,1,0]
	v_pk_fma_f32 v[58:59], v[24:25], v[32:33], v[66:67] op_sel:[0,1,0]
	v_pk_fma_f32 v[32:33], v[6:7], v[42:43], v[48:49] op_sel_hi:[1,0,1]
	v_pk_fma_f32 v[48:49], v[26:27], v[34:35], v[64:65] op_sel_hi:[1,0,1]
	v_pk_fma_f32 v[64:65], v[24:25], v[34:35], v[78:79] op_sel_hi:[1,0,1]
	v_mov_b32_e32 v34, v43
	v_pk_fma_f32 v[40:41], v[4:5], v[42:43], v[40:41] op_sel_hi:[1,0,1]
	v_pk_fma_f32 v[42:43], v[2:3], v[34:35], v[32:33] op_sel_hi:[1,0,1]
	v_mov_b32_e32 v32, v35
	v_pk_fma_f32 v[40:41], v[0:1], v[34:35], v[40:41] op_sel_hi:[1,0,1]
	v_pk_fma_f32 v[66:67], v[26:27], v[32:33], v[80:81] op_sel_hi:[1,0,1]
	v_pk_fma_f32 v[78:79], v[24:25], v[32:33], v[82:83] op_sel_hi:[1,0,1]
	ds_read_b128 v[24:27], v149
	ds_read_b128 v[32:35], v149 offset:4096
	v_add_co_u32_e32 v80, vcc, s0, v108
	s_mov_b32 s0, 0xb60e000
	s_nop 0
	v_addc_co_u32_e32 v81, vcc, 0, v109, vcc
	global_store_dwordx4 v[80:81], v[40:43], off nt
	s_waitcnt vmcnt(15) lgkmcnt(1)
	v_pk_fma_f32 v[120:121], v[18:19], v[24:25], v[112:113] op_sel_hi:[1,0,1]
	v_pk_fma_f32 v[122:123], v[16:17], v[24:25], v[114:115] op_sel_hi:[1,0,1]
	v_mov_b32_e32 v40, v57
	v_pk_mul_f32 v[42:43], v[18:19], v[40:41] op_sel_hi:[1,0]
	v_pk_mul_f32 v[40:41], v[16:17], v[40:41] op_sel_hi:[1,0]
	s_waitcnt lgkmcnt(0)
	v_pk_fma_f32 v[42:43], v[14:15], v[32:33], v[42:43] op_sel_hi:[1,0,1]
	v_pk_fma_f32 v[40:41], v[12:13], v[32:33], v[40:41] op_sel_hi:[1,0,1]
	v_pk_fma_f32 v[42:43], v[10:11], v[32:33], v[42:43] op_sel:[0,1,0]
	v_pk_fma_f32 v[32:33], v[8:9], v[32:33], v[40:41] op_sel:[0,1,0]
	v_pk_fma_f32 v[222:223], v[18:19], v[24:25], v[50:51] op_sel:[0,1,0]
	v_pk_fma_f32 v[224:225], v[16:17], v[24:25], v[58:59] op_sel:[0,1,0]
	v_pk_fma_f32 v[24:25], v[6:7], v[34:35], v[42:43] op_sel_hi:[1,0,1]
	v_pk_fma_f32 v[226:227], v[18:19], v[26:27], v[48:49] op_sel_hi:[1,0,1]
	v_pk_fma_f32 v[228:229], v[16:17], v[26:27], v[64:65] op_sel_hi:[1,0,1]
	v_mov_b32_e32 v26, v35
	v_pk_fma_f32 v[32:33], v[4:5], v[34:35], v[32:33] op_sel_hi:[1,0,1]
	v_pk_fma_f32 v[34:35], v[2:3], v[26:27], v[24:25] op_sel_hi:[1,0,1]
	v_mov_b32_e32 v24, v27
	v_pk_fma_f32 v[78:79], v[16:17], v[24:25], v[78:79] op_sel_hi:[1,0,1]
	v_add_co_u32_e32 v16, vcc, s0, v108
	v_pk_fma_f32 v[32:33], v[0:1], v[26:27], v[32:33] op_sel_hi:[1,0,1]
	s_nop 0
	v_addc_co_u32_e32 v17, vcc, 0, v109, vcc
	s_mov_b32 s0, 0x20000
	global_store_dwordx4 v[16:17], v[32:35], off nt
	v_add_co_u32_e32 v16, vcc, s0, v110
	s_mov_b32 s0, 0x22000
	s_nop 0
	v_addc_co_u32_e32 v17, vcc, 0, v111, vcc
	v_pk_fma_f32 v[230:231], v[18:19], v[24:25], v[66:67] op_sel_hi:[1,0,1]
	v_add_co_u32_e32 v18, vcc, s0, v110
	s_mov_b32 s0, 0x24000
	s_nop 0
	v_addc_co_u32_e32 v19, vcc, 0, v111, vcc
	global_load_dwordx4 v[80:83], v[16:17], off nt
	global_load_dwordx4 v[64:67], v[18:19], off nt
	v_add_co_u32_e32 v16, vcc, s0, v110
	s_mov_b32 s0, 0x26000
	s_nop 0
	v_addc_co_u32_e32 v17, vcc, 0, v111, vcc
	v_add_co_u32_e32 v18, vcc, s0, v110
	s_mov_b32 s0, 0x28000
	s_nop 0
	v_addc_co_u32_e32 v19, vcc, 0, v111, vcc
	global_load_dwordx4 v[56:59], v[16:17], off nt
	global_load_dwordx4 v[48:51], v[18:19], off nt
	v_add_co_u32_e32 v16, vcc, s0, v110
	s_mov_b32 s0, 0x2a000
	s_nop 0
	v_addc_co_u32_e32 v17, vcc, 0, v111, vcc
	v_add_co_u32_e32 v18, vcc, s0, v110
	s_mov_b32 s0, 0x2c000
	s_nop 0
	v_addc_co_u32_e32 v19, vcc, 0, v111, vcc
	global_load_dwordx4 v[40:43], v[16:17], off nt
	global_load_dwordx4 v[32:35], v[18:19], off nt
	ds_read_b128 v[112:115], v150
	ds_read_b128 v[116:119], v150 offset:4096
	s_waitcnt vmcnt(21)
; __device__ __forceinline__ void gla_sample_unit(const Args& a, unsigned char* lds, int unit, int tid) {
;     ...
;     f32x4 sb[2][8];
; #pragma unroll
;     for (int i = 0; i < 8; ++i) sb[0][i] = *(const f32x4*)(S0 + (size_t)(i * 4 + kq) * 512 + vc);
; #pragma unroll
;     for (int g = 0; g < 8; ++g) {
;         if (g + 1 < 8) {
; #pragma unroll
;             for (int i = 0; i < 8; ++i) sb[(g + 1) & 1][i] = *(const f32x4*)(S0 + (size_t)(((g + 1) * 8 + i) * 4 + kq) * 512 + vc); }
; #pragma unroll
;         for (int i = 0; i < 8; ++i) { const int k = (g * 8 + i) * 4 + kq; const f32x4 s = sb[g & 1][i];
;             const f32x4 qv = *(const f32x4*)(Q4 + k * 4), kd = *(const f32x4*)(KD4 + k * 4); const float dec = DECS[k];
;             f32x4 sn = s * dec;
; #pragma unroll
;             for (int t = 0; t < 4; ++t) { sn += vr[t] * kd[t]; o[t] += s * qv[t]; }
;             *(f32x4*)(SN + (size_t)k * 512 + vc) = sn; } }
	v_pk_mul_f32 v[232:233], v[74:75], v[76:77] op_sel_hi:[1,0]
	v_pk_mul_f32 v[234:235], v[72:73], v[76:77] op_sel_hi:[1,0]
	v_add_co_u32_e32 v16, vcc, s0, v110
	s_waitcnt lgkmcnt(0)
	v_pk_fma_f32 v[232:233], v[14:15], v[116:117], v[232:233] op_sel_hi:[1,0,1]
	v_pk_fma_f32 v[234:235], v[12:13], v[116:117], v[234:235] op_sel_hi:[1,0,1]
	v_addc_co_u32_e32 v17, vcc, 0, v111, vcc
	s_mov_b32 s0, 0x2e000
	v_pk_fma_f32 v[232:233], v[10:11], v[116:117], v[232:233] op_sel:[0,1,0]
	v_pk_fma_f32 v[116:117], v[8:9], v[116:117], v[234:235] op_sel:[0,1,0]
	v_add_co_u32_e32 v18, vcc, s0, v110
	v_pk_fma_f32 v[120:121], v[74:75], v[112:113], v[120:121] op_sel_hi:[1,0,1]
	v_pk_fma_f32 v[122:123], v[72:73], v[112:113], v[122:123] op_sel_hi:[1,0,1]
	v_pk_fma_f32 v[222:223], v[74:75], v[112:113], v[222:223] op_sel:[0,1,0]
	v_pk_fma_f32 v[224:225], v[72:73], v[112:113], v[224:225] op_sel:[0,1,0]
	v_pk_fma_f32 v[112:113], v[6:7], v[118:119], v[232:233] op_sel_hi:[1,0,1]
	v_pk_fma_f32 v[116:117], v[4:5], v[118:119], v[116:117] op_sel_hi:[1,0,1]
	v_mov_b32_e32 v76, v119
	v_addc_co_u32_e32 v19, vcc, 0, v111, vcc
	v_pk_fma_f32 v[118:119], v[2:3], v[76:77], v[112:113] op_sel_hi:[1,0,1]
	v_pk_fma_f32 v[116:117], v[0:1], v[76:77], v[116:117] op_sel_hi:[1,0,1]
	v_mov_b32_e32 v76, v115
	global_load_dwordx4 v[24:27], v[16:17], off nt
	s_nop 0
	global_load_dwordx4 v[16:19], v[18:19], off nt
	v_pk_fma_f32 v[226:227], v[74:75], v[114:115], v[226:227] op_sel_hi:[1,0,1]
	v_pk_fma_f32 v[228:229], v[72:73], v[114:115], v[228:229] op_sel_hi:[1,0,1]
	v_pk_fma_f32 v[230:231], v[74:75], v[76:77], v[230:231] op_sel_hi:[1,0,1]
	v_pk_fma_f32 v[232:233], v[72:73], v[76:77], v[78:79] op_sel_hi:[1,0,1]
	ds_read_b128 v[72:75], v151
	ds_read_b128 v[112:115], v151 offset:4096
	s_mov_b32 s0, 0xb610000
	v_add_co_u32_e32 v78, vcc, s0, v108
	v_mov_b32_e32 v76, v77
	s_nop 0
	v_addc_co_u32_e32 v79, vcc, 0, v109, vcc
	global_store_dwordx4 v[78:79], v[116:119], off nt
	s_waitcnt vmcnt(23)
	v_pk_mul_f32 v[78:79], v[70:71], v[76:77] op_sel_hi:[1,0]
	v_pk_mul_f32 v[76:77], v[68:69], v[76:77] op_sel_hi:[1,0]
	s_waitcnt lgkmcnt(0)
	v_pk_fma_f32 v[78:79], v[14:15], v[112:113], v[78:79] op_sel_hi:[1,0,1]
	v_pk_fma_f32 v[76:77], v[12:13], v[112:113], v[76:77] op_sel_hi:[1,0,1]
	v_pk_fma_f32 v[78:79], v[10:11], v[112:113], v[78:79] op_sel:[0,1,0]
	v_pk_fma_f32 v[116:117], v[70:71], v[72:73], v[120:121] op_sel_hi:[1,0,1]
	v_pk_fma_f32 v[118:119], v[68:69], v[72:73], v[122:123] op_sel_hi:[1,0,1]
	v_pk_fma_f32 v[76:77], v[8:9], v[112:113], v[76:77] op_sel:[0,1,0]
	v_pk_fma_f32 v[112:113], v[70:71], v[72:73], v[222:223] op_sel:[0,1,0]
	v_pk_fma_f32 v[120:121], v[68:69], v[72:73], v[224:225] op_sel:[0,1,0]
	v_pk_fma_f32 v[72:73], v[6:7], v[114:115], v[78:79] op_sel_hi:[1,0,1]
	v_pk_fma_f32 v[122:123], v[70:71], v[74:75], v[226:227] op_sel_hi:[1,0,1]
	v_pk_fma_f32 v[222:223], v[68:69], v[74:75], v[228:229] op_sel_hi:[1,0,1]
	v_mov_b32_e32 v74, v115
	v_pk_fma_f32 v[76:77], v[4:5], v[114:115], v[76:77] op_sel_hi:[1,0,1]
	v_pk_fma_f32 v[78:79], v[2:3], v[74:75], v[72:73] op_sel_hi:[1,0,1]
	v_mov_b32_e32 v72, v75
	v_pk_fma_f32 v[76:77], v[0:1], v[74:75], v[76:77] op_sel_hi:[1,0,1]
	v_pk_fma_f32 v[114:115], v[70:71], v[72:73], v[230:231] op_sel_hi:[1,0,1]
	v_pk_fma_f32 v[224:225], v[68:69], v[72:73], v[232:233] op_sel_hi:[1,0,1]
	ds_read_b128 v[68:71], v152
	ds_read_b128 v[72:75], v152 offset:4096
	ds_read2_b32 v[226:227], v107 offset0:40 offset1:44
	s_mov_b32 s0, 0xb612000
	v_add_co_u32_e32 v228, vcc, s0, v108
	s_waitcnt vmcnt(22) lgkmcnt(2)
	v_pk_fma_f32 v[116:117], v[62:63], v[68:69], v[116:117] op_sel_hi:[1,0,1]
	v_addc_co_u32_e32 v229, vcc, 0, v109, vcc
	global_store_dwordx4 v[228:229], v[76:79], off nt
	v_pk_fma_f32 v[118:119], v[60:61], v[68:69], v[118:119] op_sel_hi:[1,0,1]
	s_mov_b32 s0, 0xb614000
	s_waitcnt lgkmcnt(0)
	v_pk_mul_f32 v[76:77], v[62:63], v[226:227] op_sel_hi:[1,0]
	v_pk_mul_f32 v[78:79], v[60:61], v[226:227] op_sel_hi:[1,0]
	v_pk_fma_f32 v[76:77], v[14:15], v[72:73], v[76:77] op_sel_hi:[1,0,1]
	v_pk_fma_f32 v[78:79], v[12:13], v[72:73], v[78:79] op_sel_hi:[1,0,1]
	v_pk_fma_f32 v[76:77], v[10:11], v[72:73], v[76:77] op_sel:[0,1,0]
	v_pk_fma_f32 v[72:73], v[8:9], v[72:73], v[78:79] op_sel:[0,1,0]
	v_pk_fma_f32 v[78:79], v[62:63], v[68:69], v[112:113] op_sel:[0,1,0]
	v_pk_fma_f32 v[112:113], v[60:61], v[68:69], v[120:121] op_sel:[0,1,0]
	v_pk_fma_f32 v[68:69], v[6:7], v[74:75], v[76:77] op_sel_hi:[1,0,1]
	v_pk_fma_f32 v[76:77], v[62:63], v[70:71], v[122:123] op_sel_hi:[1,0,1]
	v_pk_fma_f32 v[120:121], v[60:61], v[70:71], v[222:223] op_sel_hi:[1,0,1]
	v_mov_b32_e32 v70, v75
	v_pk_fma_f32 v[72:73], v[4:5], v[74:75], v[72:73] op_sel_hi:[1,0,1]
	v_pk_fma_f32 v[74:75], v[2:3], v[70:71], v[68:69] op_sel_hi:[1,0,1]
	v_mov_b32_e32 v68, v71
	v_pk_fma_f32 v[72:73], v[0:1], v[70:71], v[72:73] op_sel_hi:[1,0,1]
	v_pk_fma_f32 v[114:115], v[62:63], v[68:69], v[114:115] op_sel_hi:[1,0,1]
	v_pk_fma_f32 v[122:123], v[60:61], v[68:69], v[224:225] op_sel_hi:[1,0,1]
	ds_read_b128 v[60:63], v153
	ds_read_b128 v[68:71], v153 offset:4096
	v_add_co_u32_e32 v222, vcc, s0, v108
	s_mov_b32 s0, 0xb616000
	s_nop 0
	v_addc_co_u32_e32 v223, vcc, 0, v109, vcc
	global_store_dwordx4 v[222:223], v[72:75], off nt
	s_waitcnt vmcnt(23) lgkmcnt(1)
	v_pk_fma_f32 v[116:117], v[54:55], v[60:61], v[116:117] op_sel_hi:[1,0,1]
	v_pk_fma_f32 v[118:119], v[52:53], v[60:61], v[118:119] op_sel_hi:[1,0,1]
	v_mov_b32_e32 v72, v227
	v_pk_mul_f32 v[74:75], v[54:55], v[72:73] op_sel_hi:[1,0]
	v_pk_mul_f32 v[72:73], v[52:53], v[72:73] op_sel_hi:[1,0]
	s_waitcnt lgkmcnt(0)
; __device__ __forceinline__ void gla_sample_unit(const Args& a, unsigned char* lds, int unit, int tid) {
;     ...
;     f32x4 sb[2][8];
; #pragma unroll
;     for (int i = 0; i < 8; ++i) sb[0][i] = *(const f32x4*)(S0 + (size_t)(i * 4 + kq) * 512 + vc);
; #pragma unroll
;     for (int g = 0; g < 8; ++g) {
;         if (g + 1 < 8) {
; #pragma unroll
;             for (int i = 0; i < 8; ++i) sb[(g + 1) & 1][i] = *(const f32x4*)(S0 + (size_t)(((g + 1) * 8 + i) * 4 + kq) * 512 + vc); }
; #pragma unroll
;         for (int i = 0; i < 8; ++i) { const int k = (g * 8 + i) * 4 + kq; const f32x4 s = sb[g & 1][i];
;             const f32x4 qv = *(const f32x4*)(Q4 + k * 4), kd = *(const f32x4*)(KD4 + k * 4); const float dec = DECS[k];
;             f32x4 sn = s * dec;
; #pragma unroll
;             for (int t = 0; t < 4; ++t) { sn += vr[t] * kd[t]; o[t] += s * qv[t]; }
;             *(f32x4*)(SN + (size_t)k * 512 + vc) = sn; } }
	v_pk_fma_f32 v[74:75], v[14:15], v[68:69], v[74:75] op_sel_hi:[1,0,1]
	v_pk_fma_f32 v[72:73], v[12:13], v[68:69], v[72:73] op_sel_hi:[1,0,1]
	v_pk_fma_f32 v[74:75], v[10:11], v[68:69], v[74:75] op_sel:[0,1,0]
	v_pk_fma_f32 v[68:69], v[8:9], v[68:69], v[72:73] op_sel:[0,1,0]
	v_pk_fma_f32 v[72:73], v[54:55], v[60:61], v[78:79] op_sel:[0,1,0]
	v_pk_fma_f32 v[78:79], v[52:53], v[60:61], v[112:113] op_sel:[0,1,0]
	v_pk_fma_f32 v[60:61], v[6:7], v[70:71], v[74:75] op_sel_hi:[1,0,1]
	v_pk_fma_f32 v[74:75], v[54:55], v[62:63], v[76:77] op_sel_hi:[1,0,1]
	v_pk_fma_f32 v[76:77], v[52:53], v[62:63], v[120:121] op_sel_hi:[1,0,1]
	v_mov_b32_e32 v62, v71
	v_pk_fma_f32 v[68:69], v[4:5], v[70:71], v[68:69] op_sel_hi:[1,0,1]
	v_pk_fma_f32 v[70:71], v[2:3], v[62:63], v[60:61] op_sel_hi:[1,0,1]
	v_mov_b32_e32 v60, v63
	v_pk_fma_f32 v[68:69], v[0:1], v[62:63], v[68:69] op_sel_hi:[1,0,1]
	v_pk_fma_f32 v[112:113], v[54:55], v[60:61], v[114:115] op_sel_hi:[1,0,1]
	v_pk_fma_f32 v[114:115], v[52:53], v[60:61], v[122:123] op_sel_hi:[1,0,1]
	ds_read_b128 v[52:55], v154
	ds_read_b128 v[60:63], v154 offset:4096
	ds_read2_b32 v[120:121], v107 offset0:48 offset1:52
	v_add_co_u32_e32 v122, vcc, s0, v108
	s_waitcnt vmcnt(22) lgkmcnt(2)
	v_pk_fma_f32 v[116:117], v[46:47], v[52:53], v[116:117] op_sel_hi:[1,0,1]
	v_addc_co_u32_e32 v123, vcc, 0, v109, vcc
	global_store_dwordx4 v[122:123], v[68:71], off nt
	v_pk_fma_f32 v[118:119], v[44:45], v[52:53], v[118:119] op_sel_hi:[1,0,1]
	s_mov_b32 s0, 0xb618000
	s_waitcnt lgkmcnt(0)
	v_pk_mul_f32 v[68:69], v[46:47], v[120:121] op_sel_hi:[1,0]
	v_pk_mul_f32 v[70:71], v[44:45], v[120:121] op_sel_hi:[1,0]
	v_pk_fma_f32 v[68:69], v[14:15], v[60:61], v[68:69] op_sel_hi:[1,0,1]
	v_pk_fma_f32 v[70:71], v[12:13], v[60:61], v[70:71] op_sel_hi:[1,0,1]
	v_pk_fma_f32 v[68:69], v[10:11], v[60:61], v[68:69] op_sel:[0,1,0]
	v_pk_fma_f32 v[60:61], v[8:9], v[60:61], v[70:71] op_sel:[0,1,0]
	v_pk_fma_f32 v[70:71], v[46:47], v[52:53], v[72:73] op_sel:[0,1,0]
	v_pk_fma_f32 v[72:73], v[44:45], v[52:53], v[78:79] op_sel:[0,1,0]
	v_pk_fma_f32 v[52:53], v[6:7], v[62:63], v[68:69] op_sel_hi:[1,0,1]
	v_pk_fma_f32 v[68:69], v[46:47], v[54:55], v[74:75] op_sel_hi:[1,0,1]
	v_pk_fma_f32 v[74:75], v[44:45], v[54:55], v[76:77] op_sel_hi:[1,0,1]
	v_mov_b32_e32 v54, v63
	v_pk_fma_f32 v[60:61], v[4:5], v[62:63], v[60:61] op_sel_hi:[1,0,1]
	v_pk_fma_f32 v[62:63], v[2:3], v[54:55], v[52:53] op_sel_hi:[1,0,1]
	v_mov_b32_e32 v52, v55
	v_pk_fma_f32 v[60:61], v[0:1], v[54:55], v[60:61] op_sel_hi:[1,0,1]
	v_pk_fma_f32 v[76:77], v[46:47], v[52:53], v[112:113] op_sel_hi:[1,0,1]
	v_pk_fma_f32 v[78:79], v[44:45], v[52:53], v[114:115] op_sel_hi:[1,0,1]
	ds_read_b128 v[44:47], v155
	ds_read_b128 v[52:55], v155 offset:4096
	v_add_co_u32_e32 v112, vcc, s0, v108
	s_mov_b32 s0, 0xb61a000
	s_nop 0
	v_addc_co_u32_e32 v113, vcc, 0, v109, vcc
	global_store_dwordx4 v[112:113], v[60:63], off nt
	s_waitcnt vmcnt(23) lgkmcnt(1)
	v_pk_fma_f32 v[112:113], v[38:39], v[44:45], v[116:117] op_sel_hi:[1,0,1]
	v_pk_fma_f32 v[114:115], v[36:37], v[44:45], v[118:119] op_sel_hi:[1,0,1]
	v_mov_b32_e32 v60, v121
	v_pk_mul_f32 v[62:63], v[38:39], v[60:61] op_sel_hi:[1,0]
	v_pk_mul_f32 v[60:61], v[36:37], v[60:61] op_sel_hi:[1,0]
	s_waitcnt lgkmcnt(0)
	v_pk_fma_f32 v[62:63], v[14:15], v[52:53], v[62:63] op_sel_hi:[1,0,1]
	v_pk_fma_f32 v[60:61], v[12:13], v[52:53], v[60:61] op_sel_hi:[1,0,1]
	v_pk_fma_f32 v[62:63], v[10:11], v[52:53], v[62:63] op_sel:[0,1,0]
	v_pk_fma_f32 v[52:53], v[8:9], v[52:53], v[60:61] op_sel:[0,1,0]
	v_pk_fma_f32 v[60:61], v[38:39], v[44:45], v[70:71] op_sel:[0,1,0]
	v_pk_fma_f32 v[70:71], v[36:37], v[44:45], v[72:73] op_sel:[0,1,0]
	v_pk_fma_f32 v[44:45], v[6:7], v[54:55], v[62:63] op_sel_hi:[1,0,1]
	v_pk_fma_f32 v[62:63], v[38:39], v[46:47], v[68:69] op_sel_hi:[1,0,1]
	v_pk_fma_f32 v[68:69], v[36:37], v[46:47], v[74:75] op_sel_hi:[1,0,1]
	v_mov_b32_e32 v46, v55
	v_pk_fma_f32 v[52:53], v[4:5], v[54:55], v[52:53] op_sel_hi:[1,0,1]
	v_pk_fma_f32 v[54:55], v[2:3], v[46:47], v[44:45] op_sel_hi:[1,0,1]
	v_mov_b32_e32 v44, v47
	v_pk_fma_f32 v[52:53], v[0:1], v[46:47], v[52:53] op_sel_hi:[1,0,1]
	v_pk_fma_f32 v[72:73], v[38:39], v[44:45], v[76:77] op_sel_hi:[1,0,1]
	v_pk_fma_f32 v[74:75], v[36:37], v[44:45], v[78:79] op_sel_hi:[1,0,1]
	ds_read_b128 v[36:39], v156
	ds_read_b128 v[44:47], v156 offset:4096
	ds_read2_b32 v[76:77], v107 offset0:56 offset1:60
	v_add_co_u32_e32 v78, vcc, s0, v108
	s_mov_b32 s0, 0xb61c000
	s_nop 0
	v_addc_co_u32_e32 v79, vcc, 0, v109, vcc
	global_store_dwordx4 v[78:79], v[52:55], off nt
	s_waitcnt vmcnt(23) lgkmcnt(2)
	v_pk_fma_f32 v[78:79], v[30:31], v[36:37], v[112:113] op_sel_hi:[1,0,1]
	v_pk_fma_f32 v[112:113], v[28:29], v[36:37], v[114:115] op_sel_hi:[1,0,1]
	s_waitcnt lgkmcnt(0)
	v_pk_mul_f32 v[52:53], v[30:31], v[76:77] op_sel_hi:[1,0]
	v_pk_mul_f32 v[54:55], v[28:29], v[76:77] op_sel_hi:[1,0]
	v_pk_fma_f32 v[52:53], v[14:15], v[44:45], v[52:53] op_sel_hi:[1,0,1]
	v_pk_fma_f32 v[54:55], v[12:13], v[44:45], v[54:55] op_sel_hi:[1,0,1]
	v_pk_fma_f32 v[52:53], v[10:11], v[44:45], v[52:53] op_sel:[0,1,0]
	v_pk_fma_f32 v[44:45], v[8:9], v[44:45], v[54:55] op_sel:[0,1,0]
	v_pk_fma_f32 v[54:55], v[30:31], v[36:37], v[60:61] op_sel:[0,1,0]
	v_pk_fma_f32 v[60:61], v[28:29], v[36:37], v[70:71] op_sel:[0,1,0]
	v_pk_fma_f32 v[36:37], v[6:7], v[46:47], v[52:53] op_sel_hi:[1,0,1]
	v_pk_fma_f32 v[52:53], v[30:31], v[38:39], v[62:63] op_sel_hi:[1,0,1]
	v_pk_fma_f32 v[62:63], v[28:29], v[38:39], v[68:69] op_sel_hi:[1,0,1]
	v_mov_b32_e32 v38, v47
	v_pk_fma_f32 v[44:45], v[4:5], v[46:47], v[44:45] op_sel_hi:[1,0,1]
	v_pk_fma_f32 v[46:47], v[2:3], v[38:39], v[36:37] op_sel_hi:[1,0,1]
	v_mov_b32_e32 v36, v39
	v_pk_fma_f32 v[44:45], v[0:1], v[38:39], v[44:45] op_sel_hi:[1,0,1]
	v_pk_fma_f32 v[68:69], v[30:31], v[36:37], v[72:73] op_sel_hi:[1,0,1]
	v_pk_fma_f32 v[70:71], v[28:29], v[36:37], v[74:75] op_sel_hi:[1,0,1]
	ds_read_b128 v[28:31], v157
	ds_read_b128 v[36:39], v157 offset:4096
	v_add_co_u32_e32 v72, vcc, s0, v108
	s_mov_b32 s0, 0xb61e000
	s_nop 0
	v_addc_co_u32_e32 v73, vcc, 0, v109, vcc
	global_store_dwordx4 v[72:73], v[44:47], off nt
	s_waitcnt vmcnt(23) lgkmcnt(1)
; __device__ __forceinline__ void gla_sample_unit(const Args& a, unsigned char* lds, int unit, int tid) {
;     ...
;     f32x4 sb[2][8];
; #pragma unroll
;     for (int i = 0; i < 8; ++i) sb[0][i] = *(const f32x4*)(S0 + (size_t)(i * 4 + kq) * 512 + vc);
; #pragma unroll
;     for (int g = 0; g < 8; ++g) {
;         if (g + 1 < 8) {
; #pragma unroll
;             for (int i = 0; i < 8; ++i) sb[(g + 1) & 1][i] = *(const f32x4*)(S0 + (size_t)(((g + 1) * 8 + i) * 4 + kq) * 512 + vc); }
; #pragma unroll
;         for (int i = 0; i < 8; ++i) { const int k = (g * 8 + i) * 4 + kq; const f32x4 s = sb[g & 1][i];
;             const f32x4 qv = *(const f32x4*)(Q4 + k * 4), kd = *(const f32x4*)(KD4 + k * 4); const float dec = DECS[k];
;             f32x4 sn = s * dec;
; #pragma unroll
;             for (int t = 0; t < 4; ++t) { sn += vr[t] * kd[t]; o[t] += s * qv[t]; }
;             *(f32x4*)(SN + (size_t)k * 512 + vc) = sn; } }
	v_pk_fma_f32 v[116:117], v[22:23], v[28:29], v[78:79] op_sel_hi:[1,0,1]
	v_pk_fma_f32 v[118:119], v[20:21], v[28:29], v[112:113] op_sel_hi:[1,0,1]
	v_mov_b32_e32 v44, v77
	v_pk_mul_f32 v[46:47], v[22:23], v[44:45] op_sel_hi:[1,0]
	v_pk_mul_f32 v[44:45], v[20:21], v[44:45] op_sel_hi:[1,0]
	s_waitcnt lgkmcnt(0)
	v_pk_fma_f32 v[46:47], v[14:15], v[36:37], v[46:47] op_sel_hi:[1,0,1]
	v_pk_fma_f32 v[44:45], v[12:13], v[36:37], v[44:45] op_sel_hi:[1,0,1]
	v_pk_fma_f32 v[46:47], v[10:11], v[36:37], v[46:47] op_sel:[0,1,0]
	v_pk_fma_f32 v[36:37], v[8:9], v[36:37], v[44:45] op_sel:[0,1,0]
	v_pk_fma_f32 v[120:121], v[22:23], v[28:29], v[54:55] op_sel:[0,1,0]
	v_pk_fma_f32 v[122:123], v[20:21], v[28:29], v[60:61] op_sel:[0,1,0]
	v_pk_fma_f32 v[28:29], v[6:7], v[38:39], v[46:47] op_sel_hi:[1,0,1]
	v_pk_fma_f32 v[222:223], v[22:23], v[30:31], v[52:53] op_sel_hi:[1,0,1]
	v_pk_fma_f32 v[224:225], v[20:21], v[30:31], v[62:63] op_sel_hi:[1,0,1]
	v_mov_b32_e32 v30, v39
	v_pk_fma_f32 v[36:37], v[4:5], v[38:39], v[36:37] op_sel_hi:[1,0,1]
	v_pk_fma_f32 v[38:39], v[2:3], v[30:31], v[28:29] op_sel_hi:[1,0,1]
	v_mov_b32_e32 v28, v31
	v_pk_fma_f32 v[228:229], v[20:21], v[28:29], v[70:71] op_sel_hi:[1,0,1]
	v_add_co_u32_e32 v20, vcc, s0, v108
	v_pk_fma_f32 v[36:37], v[0:1], v[30:31], v[36:37] op_sel_hi:[1,0,1]
	s_nop 0
	v_addc_co_u32_e32 v21, vcc, 0, v109, vcc
	s_mov_b32 s0, 0x30000
	global_store_dwordx4 v[20:21], v[36:39], off nt
	v_add_co_u32_e32 v20, vcc, s0, v110
	s_mov_b32 s0, 0x32000
	s_nop 0
	v_addc_co_u32_e32 v21, vcc, 0, v111, vcc
	v_pk_fma_f32 v[226:227], v[22:23], v[28:29], v[68:69] op_sel_hi:[1,0,1]
	v_add_co_u32_e32 v22, vcc, s0, v110
	s_mov_b32 s0, 0x34000
	s_nop 0
	v_addc_co_u32_e32 v23, vcc, 0, v111, vcc
	global_load_dwordx4 v[76:79], v[20:21], off nt
	global_load_dwordx4 v[68:71], v[22:23], off nt
	v_add_co_u32_e32 v20, vcc, s0, v110
	s_mov_b32 s0, 0x36000
	s_nop 0
	v_addc_co_u32_e32 v21, vcc, 0, v111, vcc
	v_add_co_u32_e32 v22, vcc, s0, v110
	s_mov_b32 s0, 0x38000
	s_nop 0
	v_addc_co_u32_e32 v23, vcc, 0, v111, vcc
	global_load_dwordx4 v[60:63], v[20:21], off nt
	global_load_dwordx4 v[52:55], v[22:23], off nt
	v_add_co_u32_e32 v20, vcc, s0, v110
	s_mov_b32 s0, 0x3a000
	s_nop 0
	v_addc_co_u32_e32 v21, vcc, 0, v111, vcc
	v_add_co_u32_e32 v22, vcc, s0, v110
	s_mov_b32 s0, 0x3c000
	s_nop 0
	v_addc_co_u32_e32 v23, vcc, 0, v111, vcc
	global_load_dwordx4 v[44:47], v[20:21], off nt
	global_load_dwordx4 v[36:39], v[22:23], off nt
	ds_read2_b32 v[230:231], v107 offset0:64 offset1:68
	ds_read_b128 v[72:75], v158
	ds_read_b128 v[112:115], v158 offset:4096
	v_add_co_u32_e32 v20, vcc, s0, v110
	s_waitcnt vmcnt(21) lgkmcnt(2)
	v_pk_mul_f32 v[232:233], v[82:83], v[230:231] op_sel_hi:[1,0]
	v_pk_mul_f32 v[234:235], v[80:81], v[230:231] op_sel_hi:[1,0]
	s_waitcnt lgkmcnt(0)
	v_pk_fma_f32 v[232:233], v[14:15], v[112:113], v[232:233] op_sel_hi:[1,0,1]
	v_addc_co_u32_e32 v21, vcc, 0, v111, vcc
	s_mov_b32 s0, 0x3e000
	v_pk_fma_f32 v[234:235], v[12:13], v[112:113], v[234:235] op_sel_hi:[1,0,1]
	v_pk_fma_f32 v[232:233], v[10:11], v[112:113], v[232:233] op_sel:[0,1,0]
	v_add_co_u32_e32 v22, vcc, s0, v110
	v_pk_fma_f32 v[116:117], v[82:83], v[72:73], v[116:117] op_sel_hi:[1,0,1]
	v_pk_fma_f32 v[118:119], v[80:81], v[72:73], v[118:119] op_sel_hi:[1,0,1]
	v_pk_fma_f32 v[112:113], v[8:9], v[112:113], v[234:235] op_sel:[0,1,0]
	v_pk_fma_f32 v[120:121], v[82:83], v[72:73], v[120:121] op_sel:[0,1,0]
	v_pk_fma_f32 v[122:123], v[80:81], v[72:73], v[122:123] op_sel:[0,1,0]
	v_pk_fma_f32 v[72:73], v[6:7], v[114:115], v[232:233] op_sel_hi:[1,0,1]
	v_pk_fma_f32 v[222:223], v[82:83], v[74:75], v[222:223] op_sel_hi:[1,0,1]
	v_pk_fma_f32 v[224:225], v[80:81], v[74:75], v[224:225] op_sel_hi:[1,0,1]
	v_mov_b32_e32 v74, v115
	v_addc_co_u32_e32 v23, vcc, 0, v111, vcc
	v_pk_fma_f32 v[112:113], v[4:5], v[114:115], v[112:113] op_sel_hi:[1,0,1]
	v_pk_fma_f32 v[114:115], v[2:3], v[74:75], v[72:73] op_sel_hi:[1,0,1]
	v_mov_b32_e32 v72, v75
	global_load_dwordx4 v[28:31], v[20:21], off nt
	s_nop 0
	global_load_dwordx4 v[20:23], v[22:23], off nt
	v_pk_fma_f32 v[112:113], v[0:1], v[74:75], v[112:113] op_sel_hi:[1,0,1]
	v_pk_fma_f32 v[226:227], v[82:83], v[72:73], v[226:227] op_sel_hi:[1,0,1]
	v_pk_fma_f32 v[228:229], v[80:81], v[72:73], v[228:229] op_sel_hi:[1,0,1]
	s_mov_b32 s0, 0xb620000
	ds_read_b128 v[72:75], v159
	ds_read_b128 v[80:83], v159 offset:4096
	v_add_co_u32_e32 v232, vcc, s0, v108
	s_mov_b32 s0, 0xb622000
	s_nop 0
	v_addc_co_u32_e32 v233, vcc, 0, v109, vcc
	global_store_dwordx4 v[232:233], v[112:115], off nt
	s_waitcnt vmcnt(23) lgkmcnt(1)
	v_pk_fma_f32 v[116:117], v[66:67], v[72:73], v[116:117] op_sel_hi:[1,0,1]
	v_pk_fma_f32 v[118:119], v[64:65], v[72:73], v[118:119] op_sel_hi:[1,0,1]
	v_mov_b32_e32 v112, v231
	v_pk_mul_f32 v[114:115], v[66:67], v[112:113] op_sel_hi:[1,0]
	v_pk_mul_f32 v[112:113], v[64:65], v[112:113] op_sel_hi:[1,0]
	s_waitcnt lgkmcnt(0)
	v_pk_fma_f32 v[114:115], v[14:15], v[80:81], v[114:115] op_sel_hi:[1,0,1]
	v_pk_fma_f32 v[112:113], v[12:13], v[80:81], v[112:113] op_sel_hi:[1,0,1]
	v_pk_fma_f32 v[114:115], v[10:11], v[80:81], v[114:115] op_sel:[0,1,0]
	v_pk_fma_f32 v[80:81], v[8:9], v[80:81], v[112:113] op_sel:[0,1,0]
	v_pk_fma_f32 v[112:113], v[66:67], v[72:73], v[120:121] op_sel:[0,1,0]
	v_pk_fma_f32 v[120:121], v[64:65], v[72:73], v[122:123] op_sel:[0,1,0]
	v_pk_fma_f32 v[72:73], v[6:7], v[82:83], v[114:115] op_sel_hi:[1,0,1]
	v_pk_fma_f32 v[114:115], v[66:67], v[74:75], v[222:223] op_sel_hi:[1,0,1]
	v_pk_fma_f32 v[122:123], v[64:65], v[74:75], v[224:225] op_sel_hi:[1,0,1]
	v_mov_b32_e32 v74, v83
	v_pk_fma_f32 v[80:81], v[4:5], v[82:83], v[80:81] op_sel_hi:[1,0,1]
	v_pk_fma_f32 v[82:83], v[2:3], v[74:75], v[72:73] op_sel_hi:[1,0,1]
	v_mov_b32_e32 v72, v75
	v_pk_fma_f32 v[80:81], v[0:1], v[74:75], v[80:81] op_sel_hi:[1,0,1]
	v_pk_fma_f32 v[222:223], v[66:67], v[72:73], v[226:227] op_sel_hi:[1,0,1]
	v_pk_fma_f32 v[224:225], v[64:65], v[72:73], v[228:229] op_sel_hi:[1,0,1]
	ds_read_b128 v[64:67], v160
	ds_read_b128 v[72:75], v160 offset:4096
	ds_read2_b32 v[226:227], v107 offset0:72 offset1:76
	v_add_co_u32_e32 v228, vcc, s0, v108
	s_waitcnt vmcnt(22) lgkmcnt(2)
; __device__ __forceinline__ void gla_sample_unit(const Args& a, unsigned char* lds, int unit, int tid) {
;     ...
;     f32x4 sb[2][8];
; #pragma unroll
;     for (int i = 0; i < 8; ++i) sb[0][i] = *(const f32x4*)(S0 + (size_t)(i * 4 + kq) * 512 + vc);
; #pragma unroll
;     for (int g = 0; g < 8; ++g) {
;         if (g + 1 < 8) {
; #pragma unroll
;             for (int i = 0; i < 8; ++i) sb[(g + 1) & 1][i] = *(const f32x4*)(S0 + (size_t)(((g + 1) * 8 + i) * 4 + kq) * 512 + vc); }
; #pragma unroll
;         for (int i = 0; i < 8; ++i) { const int k = (g * 8 + i) * 4 + kq; const f32x4 s = sb[g & 1][i];
;             const f32x4 qv = *(const f32x4*)(Q4 + k * 4), kd = *(const f32x4*)(KD4 + k * 4); const float dec = DECS[k];
;             f32x4 sn = s * dec;
; #pragma unroll
;             for (int t = 0; t < 4; ++t) { sn += vr[t] * kd[t]; o[t] += s * qv[t]; }
;             *(f32x4*)(SN + (size_t)k * 512 + vc) = sn; } }
	v_pk_fma_f32 v[116:117], v[58:59], v[64:65], v[116:117] op_sel_hi:[1,0,1]
	v_addc_co_u32_e32 v229, vcc, 0, v109, vcc
	global_store_dwordx4 v[228:229], v[80:83], off nt
	v_pk_fma_f32 v[118:119], v[56:57], v[64:65], v[118:119] op_sel_hi:[1,0,1]
	s_mov_b32 s0, 0xb624000
	s_waitcnt lgkmcnt(0)
	v_pk_mul_f32 v[80:81], v[58:59], v[226:227] op_sel_hi:[1,0]
	v_pk_mul_f32 v[82:83], v[56:57], v[226:227] op_sel_hi:[1,0]
	v_pk_fma_f32 v[80:81], v[14:15], v[72:73], v[80:81] op_sel_hi:[1,0,1]
	v_pk_fma_f32 v[82:83], v[12:13], v[72:73], v[82:83] op_sel_hi:[1,0,1]
	v_pk_fma_f32 v[80:81], v[10:11], v[72:73], v[80:81] op_sel:[0,1,0]
	v_pk_fma_f32 v[72:73], v[8:9], v[72:73], v[82:83] op_sel:[0,1,0]
	v_pk_fma_f32 v[82:83], v[58:59], v[64:65], v[112:113] op_sel:[0,1,0]
	v_pk_fma_f32 v[112:113], v[56:57], v[64:65], v[120:121] op_sel:[0,1,0]
	v_pk_fma_f32 v[64:65], v[6:7], v[74:75], v[80:81] op_sel_hi:[1,0,1]
	v_pk_fma_f32 v[80:81], v[58:59], v[66:67], v[114:115] op_sel_hi:[1,0,1]
	v_pk_fma_f32 v[114:115], v[56:57], v[66:67], v[122:123] op_sel_hi:[1,0,1]
	v_mov_b32_e32 v66, v75
	v_pk_fma_f32 v[72:73], v[4:5], v[74:75], v[72:73] op_sel_hi:[1,0,1]
	v_pk_fma_f32 v[74:75], v[2:3], v[66:67], v[64:65] op_sel_hi:[1,0,1]
	v_mov_b32_e32 v64, v67
	v_pk_fma_f32 v[72:73], v[0:1], v[66:67], v[72:73] op_sel_hi:[1,0,1]
	v_pk_fma_f32 v[120:121], v[58:59], v[64:65], v[222:223] op_sel_hi:[1,0,1]
	v_pk_fma_f32 v[122:123], v[56:57], v[64:65], v[224:225] op_sel_hi:[1,0,1]
	ds_read_b128 v[56:59], v161
	ds_read_b128 v[64:67], v161 offset:4096
	v_add_co_u32_e32 v222, vcc, s0, v108
	s_mov_b32 s0, 0xb626000
	s_nop 0
	v_addc_co_u32_e32 v223, vcc, 0, v109, vcc
	global_store_dwordx4 v[222:223], v[72:75], off nt
	s_waitcnt vmcnt(23) lgkmcnt(1)
	v_pk_fma_f32 v[116:117], v[50:51], v[56:57], v[116:117] op_sel_hi:[1,0,1]
	v_pk_fma_f32 v[118:119], v[48:49], v[56:57], v[118:119] op_sel_hi:[1,0,1]
	v_mov_b32_e32 v72, v227
	v_pk_mul_f32 v[74:75], v[50:51], v[72:73] op_sel_hi:[1,0]
	v_pk_mul_f32 v[72:73], v[48:49], v[72:73] op_sel_hi:[1,0]
	s_waitcnt lgkmcnt(0)
	v_pk_fma_f32 v[74:75], v[14:15], v[64:65], v[74:75] op_sel_hi:[1,0,1]
	v_pk_fma_f32 v[72:73], v[12:13], v[64:65], v[72:73] op_sel_hi:[1,0,1]
	v_pk_fma_f32 v[74:75], v[10:11], v[64:65], v[74:75] op_sel:[0,1,0]
	v_pk_fma_f32 v[64:65], v[8:9], v[64:65], v[72:73] op_sel:[0,1,0]
	v_pk_fma_f32 v[72:73], v[50:51], v[56:57], v[82:83] op_sel:[0,1,0]
	v_pk_fma_f32 v[82:83], v[48:49], v[56:57], v[112:113] op_sel:[0,1,0]
	v_pk_fma_f32 v[56:57], v[6:7], v[66:67], v[74:75] op_sel_hi:[1,0,1]
	v_pk_fma_f32 v[74:75], v[50:51], v[58:59], v[80:81] op_sel_hi:[1,0,1]
	v_pk_fma_f32 v[80:81], v[48:49], v[58:59], v[114:115] op_sel_hi:[1,0,1]
	v_mov_b32_e32 v58, v67
	v_pk_fma_f32 v[64:65], v[4:5], v[66:67], v[64:65] op_sel_hi:[1,0,1]
	v_pk_fma_f32 v[66:67], v[2:3], v[58:59], v[56:57] op_sel_hi:[1,0,1]
	v_mov_b32_e32 v56, v59
	v_pk_fma_f32 v[64:65], v[0:1], v[58:59], v[64:65] op_sel_hi:[1,0,1]
	v_pk_fma_f32 v[112:113], v[50:51], v[56:57], v[120:121] op_sel_hi:[1,0,1]
	v_pk_fma_f32 v[114:115], v[48:49], v[56:57], v[122:123] op_sel_hi:[1,0,1]
	ds_read_b128 v[48:51], v162
	ds_read_b128 v[56:59], v162 offset:4096
	ds_read2_b32 v[120:121], v107 offset0:80 offset1:84
	v_add_co_u32_e32 v122, vcc, s0, v108
	s_waitcnt vmcnt(22) lgkmcnt(2)
	v_pk_fma_f32 v[116:117], v[42:43], v[48:49], v[116:117] op_sel_hi:[1,0,1]
	v_addc_co_u32_e32 v123, vcc, 0, v109, vcc
	global_store_dwordx4 v[122:123], v[64:67], off nt
	v_pk_fma_f32 v[118:119], v[40:41], v[48:49], v[118:119] op_sel_hi:[1,0,1]
	s_mov_b32 s0, 0xb628000
	s_waitcnt lgkmcnt(0)
	v_pk_mul_f32 v[64:65], v[42:43], v[120:121] op_sel_hi:[1,0]
	v_pk_mul_f32 v[66:67], v[40:41], v[120:121] op_sel_hi:[1,0]
	v_pk_fma_f32 v[64:65], v[14:15], v[56:57], v[64:65] op_sel_hi:[1,0,1]
	v_pk_fma_f32 v[66:67], v[12:13], v[56:57], v[66:67] op_sel_hi:[1,0,1]
	v_pk_fma_f32 v[64:65], v[10:11], v[56:57], v[64:65] op_sel:[0,1,0]
	v_pk_fma_f32 v[56:57], v[8:9], v[56:57], v[66:67] op_sel:[0,1,0]
	v_pk_fma_f32 v[66:67], v[42:43], v[48:49], v[72:73] op_sel:[0,1,0]
	v_pk_fma_f32 v[72:73], v[40:41], v[48:49], v[82:83] op_sel:[0,1,0]
	v_pk_fma_f32 v[48:49], v[6:7], v[58:59], v[64:65] op_sel_hi:[1,0,1]
	v_pk_fma_f32 v[64:65], v[42:43], v[50:51], v[74:75] op_sel_hi:[1,0,1]
	v_pk_fma_f32 v[74:75], v[40:41], v[50:51], v[80:81] op_sel_hi:[1,0,1]
	v_mov_b32_e32 v50, v59
	v_pk_fma_f32 v[56:57], v[4:5], v[58:59], v[56:57] op_sel_hi:[1,0,1]
	v_pk_fma_f32 v[58:59], v[2:3], v[50:51], v[48:49] op_sel_hi:[1,0,1]
	v_mov_b32_e32 v48, v51
	v_pk_fma_f32 v[56:57], v[0:1], v[50:51], v[56:57] op_sel_hi:[1,0,1]
	v_pk_fma_f32 v[80:81], v[42:43], v[48:49], v[112:113] op_sel_hi:[1,0,1]
	v_pk_fma_f32 v[82:83], v[40:41], v[48:49], v[114:115] op_sel_hi:[1,0,1]
	ds_read_b128 v[40:43], v163
	ds_read_b128 v[48:51], v163 offset:4096
	v_add_co_u32_e32 v112, vcc, s0, v108
	s_mov_b32 s0, 0xb62a000
	s_nop 0
	v_addc_co_u32_e32 v113, vcc, 0, v109, vcc
	global_store_dwordx4 v[112:113], v[56:59], off nt
	s_waitcnt vmcnt(23) lgkmcnt(1)
	v_pk_fma_f32 v[112:113], v[34:35], v[40:41], v[116:117] op_sel_hi:[1,0,1]
	v_pk_fma_f32 v[114:115], v[32:33], v[40:41], v[118:119] op_sel_hi:[1,0,1]
	v_mov_b32_e32 v56, v121
	v_pk_mul_f32 v[58:59], v[34:35], v[56:57] op_sel_hi:[1,0]
	v_pk_mul_f32 v[56:57], v[32:33], v[56:57] op_sel_hi:[1,0]
	s_waitcnt lgkmcnt(0)
; __device__ __forceinline__ void gla_sample_unit(const Args& a, unsigned char* lds, int unit, int tid) {
;     ...
;     f32x4 sb[2][8];
; #pragma unroll
;     for (int i = 0; i < 8; ++i) sb[0][i] = *(const f32x4*)(S0 + (size_t)(i * 4 + kq) * 512 + vc);
; #pragma unroll
;     for (int g = 0; g < 8; ++g) {
;         if (g + 1 < 8) {
; #pragma unroll
;             for (int i = 0; i < 8; ++i) sb[(g + 1) & 1][i] = *(const f32x4*)(S0 + (size_t)(((g + 1) * 8 + i) * 4 + kq) * 512 + vc); }
; #pragma unroll
;         for (int i = 0; i < 8; ++i) { const int k = (g * 8 + i) * 4 + kq; const f32x4 s = sb[g & 1][i];
;             const f32x4 qv = *(const f32x4*)(Q4 + k * 4), kd = *(const f32x4*)(KD4 + k * 4); const float dec = DECS[k];
;             f32x4 sn = s * dec;
; #pragma unroll
;             for (int t = 0; t < 4; ++t) { sn += vr[t] * kd[t]; o[t] += s * qv[t]; }
;             *(f32x4*)(SN + (size_t)k * 512 + vc) = sn; } }
	v_pk_fma_f32 v[58:59], v[14:15], v[48:49], v[58:59] op_sel_hi:[1,0,1]
	v_pk_fma_f32 v[56:57], v[12:13], v[48:49], v[56:57] op_sel_hi:[1,0,1]
	v_pk_fma_f32 v[58:59], v[10:11], v[48:49], v[58:59] op_sel:[0,1,0]
	v_pk_fma_f32 v[48:49], v[8:9], v[48:49], v[56:57] op_sel:[0,1,0]
	v_pk_fma_f32 v[56:57], v[34:35], v[40:41], v[66:67] op_sel:[0,1,0]
	v_pk_fma_f32 v[66:67], v[32:33], v[40:41], v[72:73] op_sel:[0,1,0]
	v_pk_fma_f32 v[40:41], v[6:7], v[50:51], v[58:59] op_sel_hi:[1,0,1]
	v_pk_fma_f32 v[58:59], v[34:35], v[42:43], v[64:65] op_sel_hi:[1,0,1]
	v_pk_fma_f32 v[64:65], v[32:33], v[42:43], v[74:75] op_sel_hi:[1,0,1]
	v_mov_b32_e32 v42, v51
	v_pk_fma_f32 v[48:49], v[4:5], v[50:51], v[48:49] op_sel_hi:[1,0,1]
	v_pk_fma_f32 v[50:51], v[2:3], v[42:43], v[40:41] op_sel_hi:[1,0,1]
	v_mov_b32_e32 v40, v43
	v_pk_fma_f32 v[48:49], v[0:1], v[42:43], v[48:49] op_sel_hi:[1,0,1]
	v_pk_fma_f32 v[72:73], v[34:35], v[40:41], v[80:81] op_sel_hi:[1,0,1]
	v_pk_fma_f32 v[74:75], v[32:33], v[40:41], v[82:83] op_sel_hi:[1,0,1]
	ds_read_b128 v[32:35], v164
	ds_read_b128 v[40:43], v164 offset:4096
	ds_read2_b32 v[80:81], v107 offset0:88 offset1:92
	v_add_co_u32_e32 v82, vcc, s0, v108
	s_mov_b32 s0, 0xb62c000
	s_nop 0
	v_addc_co_u32_e32 v83, vcc, 0, v109, vcc
	global_store_dwordx4 v[82:83], v[48:51], off nt
	s_waitcnt vmcnt(23) lgkmcnt(2)
	v_pk_fma_f32 v[82:83], v[26:27], v[32:33], v[112:113] op_sel_hi:[1,0,1]
	v_pk_fma_f32 v[112:113], v[24:25], v[32:33], v[114:115] op_sel_hi:[1,0,1]
	s_waitcnt lgkmcnt(0)
	v_pk_mul_f32 v[48:49], v[26:27], v[80:81] op_sel_hi:[1,0]
	v_pk_mul_f32 v[50:51], v[24:25], v[80:81] op_sel_hi:[1,0]
	v_pk_fma_f32 v[48:49], v[14:15], v[40:41], v[48:49] op_sel_hi:[1,0,1]
	v_pk_fma_f32 v[50:51], v[12:13], v[40:41], v[50:51] op_sel_hi:[1,0,1]
	v_pk_fma_f32 v[48:49], v[10:11], v[40:41], v[48:49] op_sel:[0,1,0]
	v_pk_fma_f32 v[40:41], v[8:9], v[40:41], v[50:51] op_sel:[0,1,0]
	v_pk_fma_f32 v[50:51], v[26:27], v[32:33], v[56:57] op_sel:[0,1,0]
	v_pk_fma_f32 v[56:57], v[24:25], v[32:33], v[66:67] op_sel:[0,1,0]
	v_pk_fma_f32 v[32:33], v[6:7], v[42:43], v[48:49] op_sel_hi:[1,0,1]
	v_pk_fma_f32 v[48:49], v[26:27], v[34:35], v[58:59] op_sel_hi:[1,0,1]
	v_pk_fma_f32 v[58:59], v[24:25], v[34:35], v[64:65] op_sel_hi:[1,0,1]
	v_mov_b32_e32 v34, v43
	v_pk_fma_f32 v[40:41], v[4:5], v[42:43], v[40:41] op_sel_hi:[1,0,1]
	v_pk_fma_f32 v[42:43], v[2:3], v[34:35], v[32:33] op_sel_hi:[1,0,1]
	v_mov_b32_e32 v32, v35
	v_pk_fma_f32 v[40:41], v[0:1], v[34:35], v[40:41] op_sel_hi:[1,0,1]
	v_pk_fma_f32 v[64:65], v[26:27], v[32:33], v[72:73] op_sel_hi:[1,0,1]
	v_pk_fma_f32 v[66:67], v[24:25], v[32:33], v[74:75] op_sel_hi:[1,0,1]
	ds_read_b128 v[24:27], v165
	ds_read_b128 v[32:35], v165 offset:4096
	v_add_co_u32_e32 v72, vcc, s0, v108
	s_mov_b32 s0, 0xb62e000
	s_nop 0
	v_addc_co_u32_e32 v73, vcc, 0, v109, vcc
	global_store_dwordx4 v[72:73], v[40:43], off nt
	s_waitcnt vmcnt(23) lgkmcnt(1)
	v_pk_fma_f32 v[114:115], v[16:17], v[24:25], v[56:57] op_sel:[0,1,0]
	v_pk_fma_f32 v[116:117], v[18:19], v[26:27], v[48:49] op_sel_hi:[1,0,1]
	v_mov_b32_e32 v40, v81
	v_pk_mul_f32 v[42:43], v[18:19], v[40:41] op_sel_hi:[1,0]
	v_pk_mul_f32 v[40:41], v[16:17], v[40:41] op_sel_hi:[1,0]
	s_waitcnt lgkmcnt(0)
	v_pk_fma_f32 v[42:43], v[14:15], v[32:33], v[42:43] op_sel_hi:[1,0,1]
	v_pk_fma_f32 v[40:41], v[12:13], v[32:33], v[40:41] op_sel_hi:[1,0,1]
	v_pk_fma_f32 v[42:43], v[10:11], v[32:33], v[42:43] op_sel:[0,1,0]
	v_pk_fma_f32 v[80:81], v[18:19], v[24:25], v[82:83] op_sel_hi:[1,0,1]
	v_pk_fma_f32 v[82:83], v[16:17], v[24:25], v[112:113] op_sel_hi:[1,0,1]
	v_pk_fma_f32 v[32:33], v[8:9], v[32:33], v[40:41] op_sel:[0,1,0]
	v_pk_fma_f32 v[112:113], v[18:19], v[24:25], v[50:51] op_sel:[0,1,0]
	v_pk_fma_f32 v[24:25], v[6:7], v[34:35], v[42:43] op_sel_hi:[1,0,1]
	v_pk_fma_f32 v[118:119], v[16:17], v[26:27], v[58:59] op_sel_hi:[1,0,1]
	v_mov_b32_e32 v26, v35
	v_pk_fma_f32 v[32:33], v[4:5], v[34:35], v[32:33] op_sel_hi:[1,0,1]
	v_pk_fma_f32 v[34:35], v[2:3], v[26:27], v[24:25] op_sel_hi:[1,0,1]
	v_mov_b32_e32 v24, v27
	v_pk_fma_f32 v[122:123], v[16:17], v[24:25], v[66:67] op_sel_hi:[1,0,1]
	v_add_co_u32_e32 v16, vcc, s0, v108
	v_pk_fma_f32 v[32:33], v[0:1], v[26:27], v[32:33] op_sel_hi:[1,0,1]
	s_nop 0
	v_addc_co_u32_e32 v17, vcc, 0, v109, vcc
	s_mov_b32 s0, 0x40000
	global_store_dwordx4 v[16:17], v[32:35], off nt
	v_add_co_u32_e32 v16, vcc, s0, v110
	s_mov_b32 s0, 0x42000
	s_nop 0
	v_addc_co_u32_e32 v17, vcc, 0, v111, vcc
	v_pk_fma_f32 v[120:121], v[18:19], v[24:25], v[64:65] op_sel_hi:[1,0,1]
	v_add_co_u32_e32 v18, vcc, s0, v110
	s_mov_b32 s0, 0x44000
	s_nop 0
	v_addc_co_u32_e32 v19, vcc, 0, v111, vcc
	global_load_dwordx4 v[72:75], v[16:17], off nt
	global_load_dwordx4 v[64:67], v[18:19], off nt
	v_add_co_u32_e32 v16, vcc, s0, v110
	s_mov_b32 s0, 0x46000
	s_nop 0
	v_addc_co_u32_e32 v17, vcc, 0, v111, vcc
	v_add_co_u32_e32 v18, vcc, s0, v110
	s_mov_b32 s0, 0x48000
	s_nop 0
	v_addc_co_u32_e32 v19, vcc, 0, v111, vcc
	global_load_dwordx4 v[56:59], v[16:17], off nt
	global_load_dwordx4 v[48:51], v[18:19], off nt
	v_add_co_u32_e32 v16, vcc, s0, v110
	s_mov_b32 s0, 0x4a000
	s_nop 0
	v_addc_co_u32_e32 v17, vcc, 0, v111, vcc
	v_add_co_u32_e32 v18, vcc, s0, v110
	s_mov_b32 s0, 0x4c000
	s_nop 0
	v_addc_co_u32_e32 v19, vcc, 0, v111, vcc
	global_load_dwordx4 v[40:43], v[16:17], off nt
	global_load_dwordx4 v[32:35], v[18:19], off nt
	ds_read2_b32 v[230:231], v107 offset0:96 offset1:100
	ds_read_b128 v[222:225], v166
	ds_read_b128 v[226:229], v166 offset:4096
	v_add_co_u32_e32 v16, vcc, s0, v110
	s_waitcnt vmcnt(21) lgkmcnt(2)
	v_pk_mul_f32 v[232:233], v[78:79], v[230:231] op_sel_hi:[1,0]
	v_pk_mul_f32 v[234:235], v[76:77], v[230:231] op_sel_hi:[1,0]
	s_waitcnt lgkmcnt(0)
; __device__ __forceinline__ void gla_sample_unit(const Args& a, unsigned char* lds, int unit, int tid) {
;     ...
;     f32x4 sb[2][8];
; #pragma unroll
;     for (int i = 0; i < 8; ++i) sb[0][i] = *(const f32x4*)(S0 + (size_t)(i * 4 + kq) * 512 + vc);
; #pragma unroll
;     for (int g = 0; g < 8; ++g) {
;         if (g + 1 < 8) {
; #pragma unroll
;             for (int i = 0; i < 8; ++i) sb[(g + 1) & 1][i] = *(const f32x4*)(S0 + (size_t)(((g + 1) * 8 + i) * 4 + kq) * 512 + vc); }
; #pragma unroll
;         for (int i = 0; i < 8; ++i) { const int k = (g * 8 + i) * 4 + kq; const f32x4 s = sb[g & 1][i];
;             const f32x4 qv = *(const f32x4*)(Q4 + k * 4), kd = *(const f32x4*)(KD4 + k * 4); const float dec = DECS[k];
;             f32x4 sn = s * dec;
; #pragma unroll
;             for (int t = 0; t < 4; ++t) { sn += vr[t] * kd[t]; o[t] += s * qv[t]; }
;             *(f32x4*)(SN + (size_t)k * 512 + vc) = sn; } }
	v_pk_fma_f32 v[232:233], v[14:15], v[226:227], v[232:233] op_sel_hi:[1,0,1]
	v_pk_fma_f32 v[234:235], v[12:13], v[226:227], v[234:235] op_sel_hi:[1,0,1]
	v_addc_co_u32_e32 v17, vcc, 0, v111, vcc
	s_mov_b32 s0, 0x4e000
	v_pk_fma_f32 v[236:237], v[78:79], v[222:223], v[80:81] op_sel_hi:[1,0,1]
	v_pk_fma_f32 v[238:239], v[76:77], v[222:223], v[82:83] op_sel_hi:[1,0,1]
	v_pk_fma_f32 v[80:81], v[10:11], v[226:227], v[232:233] op_sel:[0,1,0]
	v_pk_fma_f32 v[82:83], v[8:9], v[226:227], v[234:235] op_sel:[0,1,0]
	v_add_co_u32_e32 v18, vcc, s0, v110
	v_pk_fma_f32 v[112:113], v[78:79], v[222:223], v[112:113] op_sel:[0,1,0]
	v_pk_fma_f32 v[222:223], v[76:77], v[222:223], v[114:115] op_sel:[0,1,0]
	v_pk_fma_f32 v[80:81], v[6:7], v[228:229], v[80:81] op_sel_hi:[1,0,1]
	v_pk_fma_f32 v[114:115], v[4:5], v[228:229], v[82:83] op_sel_hi:[1,0,1]
	v_pk_fma_f32 v[226:227], v[78:79], v[224:225], v[116:117] op_sel_hi:[1,0,1]
	v_mov_b32_e32 v116, v229
	v_addc_co_u32_e32 v19, vcc, 0, v111, vcc
	v_pk_fma_f32 v[82:83], v[2:3], v[116:117], v[80:81] op_sel_hi:[1,0,1]
	v_pk_fma_f32 v[80:81], v[0:1], v[116:117], v[114:115] op_sel_hi:[1,0,1]
	v_mov_b32_e32 v114, v225
	global_load_dwordx4 v[24:27], v[16:17], off nt
	s_nop 0
	global_load_dwordx4 v[16:19], v[18:19], off nt
	v_pk_fma_f32 v[232:233], v[76:77], v[224:225], v[118:119] op_sel_hi:[1,0,1]
	v_pk_fma_f32 v[224:225], v[78:79], v[114:115], v[120:121] op_sel_hi:[1,0,1]
	v_pk_fma_f32 v[122:123], v[76:77], v[114:115], v[122:123] op_sel_hi:[1,0,1]
	s_mov_b32 s0, 0xb630000
	ds_read_b128 v[114:117], v167
	ds_read_b128 v[118:121], v167 offset:4096
	v_add_co_u32_e32 v76, vcc, s0, v108
	s_mov_b32 s0, 0xb632000
	s_nop 0
	v_addc_co_u32_e32 v77, vcc, 0, v109, vcc
	global_store_dwordx4 v[76:77], v[80:83], off nt
	v_mov_b32_e32 v76, v231
	s_waitcnt vmcnt(23)
	v_pk_mul_f32 v[78:79], v[70:71], v[76:77] op_sel_hi:[1,0]
	v_pk_mul_f32 v[76:77], v[68:69], v[76:77] op_sel_hi:[1,0]
	s_waitcnt lgkmcnt(0)
	v_pk_fma_f32 v[80:81], v[14:15], v[118:119], v[78:79] op_sel_hi:[1,0,1]
	v_pk_fma_f32 v[82:83], v[12:13], v[118:119], v[76:77] op_sel_hi:[1,0,1]
	v_pk_fma_f32 v[228:229], v[10:11], v[118:119], v[80:81] op_sel:[0,1,0]
	v_pk_fma_f32 v[118:119], v[8:9], v[118:119], v[82:83] op_sel:[0,1,0]
	v_pk_fma_f32 v[76:77], v[70:71], v[114:115], v[236:237] op_sel_hi:[1,0,1]
	v_pk_fma_f32 v[78:79], v[68:69], v[114:115], v[238:239] op_sel_hi:[1,0,1]
	v_pk_fma_f32 v[80:81], v[70:71], v[114:115], v[112:113] op_sel:[0,1,0]
	v_pk_fma_f32 v[82:83], v[68:69], v[114:115], v[222:223] op_sel:[0,1,0]
	v_pk_fma_f32 v[222:223], v[6:7], v[120:121], v[228:229] op_sel_hi:[1,0,1]
	v_pk_fma_f32 v[118:119], v[4:5], v[120:121], v[118:119] op_sel_hi:[1,0,1]
	v_pk_fma_f32 v[112:113], v[70:71], v[116:117], v[226:227] op_sel_hi:[1,0,1]
	v_pk_fma_f32 v[114:115], v[68:69], v[116:117], v[232:233] op_sel_hi:[1,0,1]
	v_mov_b32_e32 v116, v121
	v_pk_fma_f32 v[120:121], v[2:3], v[116:117], v[222:223] op_sel_hi:[1,0,1]
	v_pk_fma_f32 v[118:119], v[0:1], v[116:117], v[118:119] op_sel_hi:[1,0,1]
	v_mov_b32_e32 v116, v117
	v_pk_fma_f32 v[70:71], v[70:71], v[116:117], v[224:225] op_sel_hi:[1,0,1]
	v_pk_fma_f32 v[68:69], v[68:69], v[116:117], v[122:123] op_sel_hi:[1,0,1]
	ds_read_b128 v[222:225], v168
	ds_read_b128 v[226:229], v168 offset:4096
	ds_read2_b32 v[116:117], v107 offset0:104 offset1:108
	v_add_co_u32_e32 v122, vcc, s0, v108
	s_waitcnt vmcnt(22) lgkmcnt(2)
	v_pk_fma_f32 v[230:231], v[60:61], v[222:223], v[78:79] op_sel_hi:[1,0,1]
	v_addc_co_u32_e32 v123, vcc, 0, v109, vcc
	global_store_dwordx4 v[122:123], v[118:121], off nt
	v_pk_fma_f32 v[122:123], v[62:63], v[222:223], v[76:77] op_sel_hi:[1,0,1]
	v_pk_fma_f32 v[80:81], v[62:63], v[222:223], v[80:81] op_sel:[0,1,0]
	s_waitcnt lgkmcnt(0)
	v_pk_mul_f32 v[118:119], v[62:63], v[116:117] op_sel_hi:[1,0]
	v_pk_mul_f32 v[120:121], v[60:61], v[116:117] op_sel_hi:[1,0]
	v_pk_fma_f32 v[118:119], v[14:15], v[226:227], v[118:119] op_sel_hi:[1,0,1]
	v_pk_fma_f32 v[120:121], v[12:13], v[226:227], v[120:121] op_sel_hi:[1,0,1]
	v_pk_fma_f32 v[76:77], v[10:11], v[226:227], v[118:119] op_sel:[0,1,0]
	v_pk_fma_f32 v[78:79], v[8:9], v[226:227], v[120:121] op_sel:[0,1,0]
	v_pk_fma_f32 v[76:77], v[6:7], v[228:229], v[76:77] op_sel_hi:[1,0,1]
	v_pk_fma_f32 v[118:119], v[4:5], v[228:229], v[78:79] op_sel_hi:[1,0,1]
	v_mov_b32_e32 v116, v229
	v_pk_fma_f32 v[78:79], v[2:3], v[116:117], v[76:77] op_sel_hi:[1,0,1]
	v_pk_fma_f32 v[76:77], v[0:1], v[116:117], v[118:119] op_sel_hi:[1,0,1]
	v_mov_b32_e32 v116, v225
	v_pk_fma_f32 v[82:83], v[60:61], v[222:223], v[82:83] op_sel:[0,1,0]
	v_pk_fma_f32 v[112:113], v[62:63], v[224:225], v[112:113] op_sel_hi:[1,0,1]
	v_pk_fma_f32 v[114:115], v[60:61], v[224:225], v[114:115] op_sel_hi:[1,0,1]
	v_pk_fma_f32 v[118:119], v[62:63], v[116:117], v[70:71] op_sel_hi:[1,0,1]
	v_pk_fma_f32 v[120:121], v[60:61], v[116:117], v[68:69] op_sel_hi:[1,0,1]
	s_mov_b32 s0, 0xb634000
	ds_read_b128 v[60:63], v169
	ds_read_b128 v[68:71], v169 offset:4096
	v_add_co_u32_e32 v222, vcc, s0, v108
	s_mov_b32 s0, 0xb636000
	s_nop 0
	v_addc_co_u32_e32 v223, vcc, 0, v109, vcc
	global_store_dwordx4 v[222:223], v[76:79], off nt
	s_nop 1
	v_mov_b32_e32 v76, v117
	s_waitcnt vmcnt(23)
	v_pk_mul_f32 v[78:79], v[54:55], v[76:77] op_sel_hi:[1,0]
	v_pk_mul_f32 v[76:77], v[52:53], v[76:77] op_sel_hi:[1,0]
	s_waitcnt lgkmcnt(0)
; __device__ __forceinline__ void gla_sample_unit(const Args& a, unsigned char* lds, int unit, int tid) {
;     ...
;     f32x4 sb[2][8];
; #pragma unroll
;     for (int i = 0; i < 8; ++i) sb[0][i] = *(const f32x4*)(S0 + (size_t)(i * 4 + kq) * 512 + vc);
; #pragma unroll
;     for (int g = 0; g < 8; ++g) {
;         if (g + 1 < 8) {
; #pragma unroll
;             for (int i = 0; i < 8; ++i) sb[(g + 1) & 1][i] = *(const f32x4*)(S0 + (size_t)(((g + 1) * 8 + i) * 4 + kq) * 512 + vc); }
; #pragma unroll
;         for (int i = 0; i < 8; ++i) { const int k = (g * 8 + i) * 4 + kq; const f32x4 s = sb[g & 1][i];
;             const f32x4 qv = *(const f32x4*)(Q4 + k * 4), kd = *(const f32x4*)(KD4 + k * 4); const float dec = DECS[k];
;             f32x4 sn = s * dec;
; #pragma unroll
;             for (int t = 0; t < 4; ++t) { sn += vr[t] * kd[t]; o[t] += s * qv[t]; }
;             *(f32x4*)(SN + (size_t)k * 512 + vc) = sn; } }
	v_pk_fma_f32 v[78:79], v[14:15], v[68:69], v[78:79] op_sel_hi:[1,0,1]
	v_pk_fma_f32 v[76:77], v[12:13], v[68:69], v[76:77] op_sel_hi:[1,0,1]
	v_pk_fma_f32 v[78:79], v[10:11], v[68:69], v[78:79] op_sel:[0,1,0]
	v_pk_fma_f32 v[116:117], v[54:55], v[60:61], v[122:123] op_sel_hi:[1,0,1]
	v_pk_fma_f32 v[122:123], v[52:53], v[60:61], v[230:231] op_sel_hi:[1,0,1]
	v_pk_fma_f32 v[68:69], v[8:9], v[68:69], v[76:77] op_sel:[0,1,0]
	v_pk_fma_f32 v[76:77], v[54:55], v[60:61], v[80:81] op_sel:[0,1,0]
	v_pk_fma_f32 v[80:81], v[52:53], v[60:61], v[82:83] op_sel:[0,1,0]
	v_pk_fma_f32 v[60:61], v[6:7], v[70:71], v[78:79] op_sel_hi:[1,0,1]
	v_pk_fma_f32 v[78:79], v[54:55], v[62:63], v[112:113] op_sel_hi:[1,0,1]
	v_pk_fma_f32 v[82:83], v[52:53], v[62:63], v[114:115] op_sel_hi:[1,0,1]
	v_mov_b32_e32 v62, v71
	v_pk_fma_f32 v[68:69], v[4:5], v[70:71], v[68:69] op_sel_hi:[1,0,1]
	v_pk_fma_f32 v[70:71], v[2:3], v[62:63], v[60:61] op_sel_hi:[1,0,1]
	v_mov_b32_e32 v60, v63
	v_pk_fma_f32 v[68:69], v[0:1], v[62:63], v[68:69] op_sel_hi:[1,0,1]
	v_pk_fma_f32 v[112:113], v[54:55], v[60:61], v[118:119] op_sel_hi:[1,0,1]
	v_pk_fma_f32 v[114:115], v[52:53], v[60:61], v[120:121] op_sel_hi:[1,0,1]
	ds_read_b128 v[52:55], v170
	ds_read_b128 v[60:63], v170 offset:4096
	ds_read2_b32 v[118:119], v107 offset0:112 offset1:116
	v_add_co_u32_e32 v120, vcc, s0, v108
	s_waitcnt vmcnt(22) lgkmcnt(2)
	v_pk_fma_f32 v[116:117], v[46:47], v[52:53], v[116:117] op_sel_hi:[1,0,1]
	v_addc_co_u32_e32 v121, vcc, 0, v109, vcc
	global_store_dwordx4 v[120:121], v[68:71], off nt
	v_pk_fma_f32 v[120:121], v[44:45], v[52:53], v[122:123] op_sel_hi:[1,0,1]
	s_mov_b32 s0, 0xb638000
	s_waitcnt lgkmcnt(0)
	v_pk_mul_f32 v[68:69], v[46:47], v[118:119] op_sel_hi:[1,0]
	v_pk_mul_f32 v[70:71], v[44:45], v[118:119] op_sel_hi:[1,0]
	v_pk_fma_f32 v[68:69], v[14:15], v[60:61], v[68:69] op_sel_hi:[1,0,1]
	v_pk_fma_f32 v[70:71], v[12:13], v[60:61], v[70:71] op_sel_hi:[1,0,1]
	v_pk_fma_f32 v[68:69], v[10:11], v[60:61], v[68:69] op_sel:[0,1,0]
	v_pk_fma_f32 v[60:61], v[8:9], v[60:61], v[70:71] op_sel:[0,1,0]
	v_pk_fma_f32 v[70:71], v[46:47], v[52:53], v[76:77] op_sel:[0,1,0]
	v_pk_fma_f32 v[76:77], v[44:45], v[52:53], v[80:81] op_sel:[0,1,0]
	v_pk_fma_f32 v[52:53], v[6:7], v[62:63], v[68:69] op_sel_hi:[1,0,1]
	v_pk_fma_f32 v[68:69], v[46:47], v[54:55], v[78:79] op_sel_hi:[1,0,1]
	v_pk_fma_f32 v[78:79], v[44:45], v[54:55], v[82:83] op_sel_hi:[1,0,1]
	v_mov_b32_e32 v54, v63
	v_pk_fma_f32 v[60:61], v[4:5], v[62:63], v[60:61] op_sel_hi:[1,0,1]
	v_pk_fma_f32 v[62:63], v[2:3], v[54:55], v[52:53] op_sel_hi:[1,0,1]
	v_mov_b32_e32 v52, v55
	v_pk_fma_f32 v[60:61], v[0:1], v[54:55], v[60:61] op_sel_hi:[1,0,1]
	v_pk_fma_f32 v[80:81], v[46:47], v[52:53], v[112:113] op_sel_hi:[1,0,1]
	v_pk_fma_f32 v[82:83], v[44:45], v[52:53], v[114:115] op_sel_hi:[1,0,1]
	ds_read_b128 v[44:47], v171
	ds_read_b128 v[52:55], v171 offset:4096
	v_add_co_u32_e32 v112, vcc, s0, v108
	s_mov_b32 s0, 0xb63a000
	s_nop 0
	v_addc_co_u32_e32 v113, vcc, 0, v109, vcc
	global_store_dwordx4 v[112:113], v[60:63], off nt
	s_waitcnt vmcnt(23) lgkmcnt(1)
	v_pk_fma_f32 v[112:113], v[38:39], v[44:45], v[116:117] op_sel_hi:[1,0,1]
	v_pk_fma_f32 v[114:115], v[36:37], v[44:45], v[120:121] op_sel_hi:[1,0,1]
	v_mov_b32_e32 v60, v119
	v_pk_mul_f32 v[62:63], v[38:39], v[60:61] op_sel_hi:[1,0]
	v_pk_mul_f32 v[60:61], v[36:37], v[60:61] op_sel_hi:[1,0]
	s_waitcnt lgkmcnt(0)
	v_pk_fma_f32 v[62:63], v[14:15], v[52:53], v[62:63] op_sel_hi:[1,0,1]
	v_pk_fma_f32 v[60:61], v[12:13], v[52:53], v[60:61] op_sel_hi:[1,0,1]
	v_pk_fma_f32 v[62:63], v[10:11], v[52:53], v[62:63] op_sel:[0,1,0]
	v_pk_fma_f32 v[52:53], v[8:9], v[52:53], v[60:61] op_sel:[0,1,0]
	v_pk_fma_f32 v[60:61], v[38:39], v[44:45], v[70:71] op_sel:[0,1,0]
	v_pk_fma_f32 v[70:71], v[36:37], v[44:45], v[76:77] op_sel:[0,1,0]
	v_pk_fma_f32 v[44:45], v[6:7], v[54:55], v[62:63] op_sel_hi:[1,0,1]
	v_pk_fma_f32 v[62:63], v[38:39], v[46:47], v[68:69] op_sel_hi:[1,0,1]
	v_pk_fma_f32 v[68:69], v[36:37], v[46:47], v[78:79] op_sel_hi:[1,0,1]
	v_mov_b32_e32 v46, v55
	v_pk_fma_f32 v[52:53], v[4:5], v[54:55], v[52:53] op_sel_hi:[1,0,1]
	v_pk_fma_f32 v[54:55], v[2:3], v[46:47], v[44:45] op_sel_hi:[1,0,1]
	v_mov_b32_e32 v44, v47
	v_pk_fma_f32 v[52:53], v[0:1], v[46:47], v[52:53] op_sel_hi:[1,0,1]
	v_pk_fma_f32 v[76:77], v[38:39], v[44:45], v[80:81] op_sel_hi:[1,0,1]
	v_pk_fma_f32 v[78:79], v[36:37], v[44:45], v[82:83] op_sel_hi:[1,0,1]
	ds_read_b128 v[36:39], v172
	ds_read_b128 v[44:47], v172 offset:4096
	ds_read2_b32 v[80:81], v107 offset0:120 offset1:124
	v_add_co_u32_e32 v82, vcc, s0, v108
	s_mov_b32 s0, 0xb63c000
	s_nop 0
	v_addc_co_u32_e32 v83, vcc, 0, v109, vcc
	global_store_dwordx4 v[82:83], v[52:55], off nt
	s_waitcnt vmcnt(23) lgkmcnt(2)
	v_pk_fma_f32 v[82:83], v[30:31], v[36:37], v[112:113] op_sel_hi:[1,0,1]
	v_pk_fma_f32 v[112:113], v[28:29], v[36:37], v[114:115] op_sel_hi:[1,0,1]
	s_waitcnt lgkmcnt(0)
	v_pk_mul_f32 v[52:53], v[30:31], v[80:81] op_sel_hi:[1,0]
	v_pk_mul_f32 v[54:55], v[28:29], v[80:81] op_sel_hi:[1,0]
	v_pk_fma_f32 v[52:53], v[14:15], v[44:45], v[52:53] op_sel_hi:[1,0,1]
	v_pk_fma_f32 v[54:55], v[12:13], v[44:45], v[54:55] op_sel_hi:[1,0,1]
	v_pk_fma_f32 v[52:53], v[10:11], v[44:45], v[52:53] op_sel:[0,1,0]
	v_pk_fma_f32 v[44:45], v[8:9], v[44:45], v[54:55] op_sel:[0,1,0]
	v_pk_fma_f32 v[54:55], v[30:31], v[36:37], v[60:61] op_sel:[0,1,0]
	v_pk_fma_f32 v[60:61], v[28:29], v[36:37], v[70:71] op_sel:[0,1,0]
	v_pk_fma_f32 v[36:37], v[6:7], v[46:47], v[52:53] op_sel_hi:[1,0,1]
	v_pk_fma_f32 v[52:53], v[30:31], v[38:39], v[62:63] op_sel_hi:[1,0,1]
	v_pk_fma_f32 v[62:63], v[28:29], v[38:39], v[68:69] op_sel_hi:[1,0,1]
	v_mov_b32_e32 v38, v47
	v_pk_fma_f32 v[44:45], v[4:5], v[46:47], v[44:45] op_sel_hi:[1,0,1]
	v_pk_fma_f32 v[46:47], v[2:3], v[38:39], v[36:37] op_sel_hi:[1,0,1]
	v_mov_b32_e32 v36, v39
	v_pk_fma_f32 v[44:45], v[0:1], v[38:39], v[44:45] op_sel_hi:[1,0,1]
	v_pk_fma_f32 v[68:69], v[30:31], v[36:37], v[76:77] op_sel_hi:[1,0,1]
	v_pk_fma_f32 v[70:71], v[28:29], v[36:37], v[78:79] op_sel_hi:[1,0,1]
	ds_read_b128 v[28:31], v173
	ds_read_b128 v[36:39], v173 offset:4096
	v_add_co_u32_e32 v76, vcc, s0, v108
	s_mov_b32 s0, 0xb63e000
	s_nop 0
	v_addc_co_u32_e32 v77, vcc, 0, v109, vcc
	global_store_dwordx4 v[76:77], v[44:47], off nt
	s_waitcnt vmcnt(23) lgkmcnt(1)
; __device__ __forceinline__ void gla_sample_unit(const Args& a, unsigned char* lds, int unit, int tid) {
;     ...
;     f32x4 sb[2][8];
; #pragma unroll
;     for (int i = 0; i < 8; ++i) sb[0][i] = *(const f32x4*)(S0 + (size_t)(i * 4 + kq) * 512 + vc);
; #pragma unroll
;     for (int g = 0; g < 8; ++g) {
;         if (g + 1 < 8) {
; #pragma unroll
;             for (int i = 0; i < 8; ++i) sb[(g + 1) & 1][i] = *(const f32x4*)(S0 + (size_t)(((g + 1) * 8 + i) * 4 + kq) * 512 + vc); }
; #pragma unroll
;         for (int i = 0; i < 8; ++i) { const int k = (g * 8 + i) * 4 + kq; const f32x4 s = sb[g & 1][i];
;             const f32x4 qv = *(const f32x4*)(Q4 + k * 4), kd = *(const f32x4*)(KD4 + k * 4); const float dec = DECS[k];
;             f32x4 sn = s * dec;
; #pragma unroll
;             for (int t = 0; t < 4; ++t) { sn += vr[t] * kd[t]; o[t] += s * qv[t]; }
;             *(f32x4*)(SN + (size_t)k * 512 + vc) = sn; } }
	v_pk_fma_f32 v[114:115], v[20:21], v[28:29], v[60:61] op_sel:[0,1,0]
	v_pk_fma_f32 v[116:117], v[22:23], v[30:31], v[52:53] op_sel_hi:[1,0,1]
	v_mov_b32_e32 v44, v81
	v_pk_mul_f32 v[46:47], v[22:23], v[44:45] op_sel_hi:[1,0]
	v_pk_mul_f32 v[44:45], v[20:21], v[44:45] op_sel_hi:[1,0]
	s_waitcnt lgkmcnt(0)
	v_pk_fma_f32 v[46:47], v[14:15], v[36:37], v[46:47] op_sel_hi:[1,0,1]
	v_pk_fma_f32 v[44:45], v[12:13], v[36:37], v[44:45] op_sel_hi:[1,0,1]
	v_pk_fma_f32 v[46:47], v[10:11], v[36:37], v[46:47] op_sel:[0,1,0]
	v_pk_fma_f32 v[80:81], v[22:23], v[28:29], v[82:83] op_sel_hi:[1,0,1]
	v_pk_fma_f32 v[82:83], v[20:21], v[28:29], v[112:113] op_sel_hi:[1,0,1]
	v_pk_fma_f32 v[36:37], v[8:9], v[36:37], v[44:45] op_sel:[0,1,0]
	v_pk_fma_f32 v[112:113], v[22:23], v[28:29], v[54:55] op_sel:[0,1,0]
	v_pk_fma_f32 v[28:29], v[6:7], v[38:39], v[46:47] op_sel_hi:[1,0,1]
	v_pk_fma_f32 v[118:119], v[20:21], v[30:31], v[62:63] op_sel_hi:[1,0,1]
	v_mov_b32_e32 v30, v39
	v_pk_fma_f32 v[36:37], v[4:5], v[38:39], v[36:37] op_sel_hi:[1,0,1]
	v_pk_fma_f32 v[38:39], v[2:3], v[30:31], v[28:29] op_sel_hi:[1,0,1]
	v_mov_b32_e32 v28, v31
	v_pk_fma_f32 v[122:123], v[20:21], v[28:29], v[70:71] op_sel_hi:[1,0,1]
	v_add_co_u32_e32 v20, vcc, s0, v108
	v_pk_fma_f32 v[36:37], v[0:1], v[30:31], v[36:37] op_sel_hi:[1,0,1]
	s_nop 0
	v_addc_co_u32_e32 v21, vcc, 0, v109, vcc
	s_mov_b32 s0, 0x50000
	global_store_dwordx4 v[20:21], v[36:39], off nt
	v_add_co_u32_e32 v20, vcc, s0, v110
	s_mov_b32 s0, 0x52000
	s_nop 0
	v_addc_co_u32_e32 v21, vcc, 0, v111, vcc
	v_pk_fma_f32 v[120:121], v[22:23], v[28:29], v[68:69] op_sel_hi:[1,0,1]
	v_add_co_u32_e32 v22, vcc, s0, v110
	s_mov_b32 s0, 0x54000
	s_nop 0
	v_addc_co_u32_e32 v23, vcc, 0, v111, vcc
	global_load_dwordx4 v[76:79], v[20:21], off nt
	global_load_dwordx4 v[68:71], v[22:23], off nt
	v_add_co_u32_e32 v20, vcc, s0, v110
	s_mov_b32 s0, 0x56000
	s_nop 0
	v_addc_co_u32_e32 v21, vcc, 0, v111, vcc
	v_add_co_u32_e32 v22, vcc, s0, v110
	s_mov_b32 s0, 0x58000
	s_nop 0
	v_addc_co_u32_e32 v23, vcc, 0, v111, vcc
	global_load_dwordx4 v[60:63], v[20:21], off nt
	global_load_dwordx4 v[52:55], v[22:23], off nt
	v_add_co_u32_e32 v20, vcc, s0, v110
	s_mov_b32 s0, 0x5a000
	s_nop 0
	v_addc_co_u32_e32 v21, vcc, 0, v111, vcc
	v_add_co_u32_e32 v22, vcc, s0, v110
	s_mov_b32 s0, 0x5c000
	s_nop 0
	v_addc_co_u32_e32 v23, vcc, 0, v111, vcc
	global_load_dwordx4 v[44:47], v[20:21], off nt
	global_load_dwordx4 v[36:39], v[22:23], off nt
	ds_read2_b32 v[230:231], v107 offset0:128 offset1:132
	ds_read_b128 v[222:225], v174
	ds_read_b128 v[226:229], v174 offset:4096
	v_add_co_u32_e32 v20, vcc, s0, v110
	s_waitcnt vmcnt(21) lgkmcnt(2)
	v_pk_mul_f32 v[232:233], v[74:75], v[230:231] op_sel_hi:[1,0]
	v_pk_mul_f32 v[234:235], v[72:73], v[230:231] op_sel_hi:[1,0]
	s_waitcnt lgkmcnt(0)
	v_pk_fma_f32 v[232:233], v[14:15], v[226:227], v[232:233] op_sel_hi:[1,0,1]
	v_pk_fma_f32 v[234:235], v[12:13], v[226:227], v[234:235] op_sel_hi:[1,0,1]
	v_addc_co_u32_e32 v21, vcc, 0, v111, vcc
	s_mov_b32 s0, 0x5e000
	v_pk_fma_f32 v[236:237], v[74:75], v[222:223], v[80:81] op_sel_hi:[1,0,1]
	v_pk_fma_f32 v[238:239], v[72:73], v[222:223], v[82:83] op_sel_hi:[1,0,1]
	v_pk_fma_f32 v[80:81], v[10:11], v[226:227], v[232:233] op_sel:[0,1,0]
	v_pk_fma_f32 v[82:83], v[8:9], v[226:227], v[234:235] op_sel:[0,1,0]
	v_add_co_u32_e32 v22, vcc, s0, v110
	v_pk_fma_f32 v[112:113], v[74:75], v[222:223], v[112:113] op_sel:[0,1,0]
	v_pk_fma_f32 v[222:223], v[72:73], v[222:223], v[114:115] op_sel:[0,1,0]
	v_pk_fma_f32 v[80:81], v[6:7], v[228:229], v[80:81] op_sel_hi:[1,0,1]
	v_pk_fma_f32 v[114:115], v[4:5], v[228:229], v[82:83] op_sel_hi:[1,0,1]
	v_pk_fma_f32 v[226:227], v[74:75], v[224:225], v[116:117] op_sel_hi:[1,0,1]
	v_mov_b32_e32 v116, v229
	v_addc_co_u32_e32 v23, vcc, 0, v111, vcc
	v_pk_fma_f32 v[82:83], v[2:3], v[116:117], v[80:81] op_sel_hi:[1,0,1]
	v_pk_fma_f32 v[80:81], v[0:1], v[116:117], v[114:115] op_sel_hi:[1,0,1]
	v_mov_b32_e32 v114, v225
	global_load_dwordx4 v[28:31], v[20:21], off nt
	s_nop 0
	global_load_dwordx4 v[20:23], v[22:23], off nt
	v_pk_fma_f32 v[232:233], v[72:73], v[224:225], v[118:119] op_sel_hi:[1,0,1]
	v_pk_fma_f32 v[224:225], v[74:75], v[114:115], v[120:121] op_sel_hi:[1,0,1]
	v_pk_fma_f32 v[122:123], v[72:73], v[114:115], v[122:123] op_sel_hi:[1,0,1]
	s_mov_b32 s0, 0xb640000
	ds_read_b128 v[114:117], v175
	ds_read_b128 v[118:121], v175 offset:4096
	v_add_co_u32_e32 v72, vcc, s0, v108
	s_mov_b32 s0, 0xb642000
	s_nop 0
	v_addc_co_u32_e32 v73, vcc, 0, v109, vcc
	global_store_dwordx4 v[72:73], v[80:83], off nt
	v_mov_b32_e32 v72, v231
	s_waitcnt vmcnt(23)
	v_pk_mul_f32 v[74:75], v[66:67], v[72:73] op_sel_hi:[1,0]
	v_pk_mul_f32 v[72:73], v[64:65], v[72:73] op_sel_hi:[1,0]
	s_waitcnt lgkmcnt(0)
	v_pk_fma_f32 v[80:81], v[14:15], v[118:119], v[74:75] op_sel_hi:[1,0,1]
	v_pk_fma_f32 v[82:83], v[12:13], v[118:119], v[72:73] op_sel_hi:[1,0,1]
	v_pk_fma_f32 v[228:229], v[10:11], v[118:119], v[80:81] op_sel:[0,1,0]
	v_pk_fma_f32 v[118:119], v[8:9], v[118:119], v[82:83] op_sel:[0,1,0]
	v_pk_fma_f32 v[72:73], v[66:67], v[114:115], v[236:237] op_sel_hi:[1,0,1]
	v_pk_fma_f32 v[74:75], v[64:65], v[114:115], v[238:239] op_sel_hi:[1,0,1]
	v_pk_fma_f32 v[80:81], v[66:67], v[114:115], v[112:113] op_sel:[0,1,0]
	v_pk_fma_f32 v[82:83], v[64:65], v[114:115], v[222:223] op_sel:[0,1,0]
	v_pk_fma_f32 v[222:223], v[6:7], v[120:121], v[228:229] op_sel_hi:[1,0,1]
	v_pk_fma_f32 v[118:119], v[4:5], v[120:121], v[118:119] op_sel_hi:[1,0,1]
	v_pk_fma_f32 v[112:113], v[66:67], v[116:117], v[226:227] op_sel_hi:[1,0,1]
	v_pk_fma_f32 v[114:115], v[64:65], v[116:117], v[232:233] op_sel_hi:[1,0,1]
	v_mov_b32_e32 v116, v121
	v_pk_fma_f32 v[120:121], v[2:3], v[116:117], v[222:223] op_sel_hi:[1,0,1]
	v_pk_fma_f32 v[118:119], v[0:1], v[116:117], v[118:119] op_sel_hi:[1,0,1]
	v_mov_b32_e32 v116, v117
	v_pk_fma_f32 v[66:67], v[66:67], v[116:117], v[224:225] op_sel_hi:[1,0,1]
	v_pk_fma_f32 v[64:65], v[64:65], v[116:117], v[122:123] op_sel_hi:[1,0,1]
	ds_read_b128 v[222:225], v176
	ds_read_b128 v[226:229], v176 offset:4096
	ds_read2_b32 v[116:117], v107 offset0:136 offset1:140
	v_add_co_u32_e32 v122, vcc, s0, v108
	s_waitcnt vmcnt(22) lgkmcnt(2)
; __device__ __forceinline__ void gla_sample_unit(const Args& a, unsigned char* lds, int unit, int tid) {
;     ...
;     f32x4 sb[2][8];
; #pragma unroll
;     for (int i = 0; i < 8; ++i) sb[0][i] = *(const f32x4*)(S0 + (size_t)(i * 4 + kq) * 512 + vc);
; #pragma unroll
;     for (int g = 0; g < 8; ++g) {
;         if (g + 1 < 8) {
; #pragma unroll
;             for (int i = 0; i < 8; ++i) sb[(g + 1) & 1][i] = *(const f32x4*)(S0 + (size_t)(((g + 1) * 8 + i) * 4 + kq) * 512 + vc); }
; #pragma unroll
;         for (int i = 0; i < 8; ++i) { const int k = (g * 8 + i) * 4 + kq; const f32x4 s = sb[g & 1][i];
;             const f32x4 qv = *(const f32x4*)(Q4 + k * 4), kd = *(const f32x4*)(KD4 + k * 4); const float dec = DECS[k];
;             f32x4 sn = s * dec;
; #pragma unroll
;             for (int t = 0; t < 4; ++t) { sn += vr[t] * kd[t]; o[t] += s * qv[t]; }
;             *(f32x4*)(SN + (size_t)k * 512 + vc) = sn; } }
	v_pk_fma_f32 v[230:231], v[56:57], v[222:223], v[74:75] op_sel_hi:[1,0,1]
	v_addc_co_u32_e32 v123, vcc, 0, v109, vcc
	global_store_dwordx4 v[122:123], v[118:121], off nt
	v_pk_fma_f32 v[122:123], v[58:59], v[222:223], v[72:73] op_sel_hi:[1,0,1]
	v_pk_fma_f32 v[80:81], v[58:59], v[222:223], v[80:81] op_sel:[0,1,0]
	s_waitcnt lgkmcnt(0)
	v_pk_mul_f32 v[118:119], v[58:59], v[116:117] op_sel_hi:[1,0]
	v_pk_mul_f32 v[120:121], v[56:57], v[116:117] op_sel_hi:[1,0]
	v_pk_fma_f32 v[118:119], v[14:15], v[226:227], v[118:119] op_sel_hi:[1,0,1]
	v_pk_fma_f32 v[120:121], v[12:13], v[226:227], v[120:121] op_sel_hi:[1,0,1]
	v_pk_fma_f32 v[72:73], v[10:11], v[226:227], v[118:119] op_sel:[0,1,0]
	v_pk_fma_f32 v[74:75], v[8:9], v[226:227], v[120:121] op_sel:[0,1,0]
	v_pk_fma_f32 v[72:73], v[6:7], v[228:229], v[72:73] op_sel_hi:[1,0,1]
	v_pk_fma_f32 v[118:119], v[4:5], v[228:229], v[74:75] op_sel_hi:[1,0,1]
	v_mov_b32_e32 v116, v229
	v_pk_fma_f32 v[74:75], v[2:3], v[116:117], v[72:73] op_sel_hi:[1,0,1]
	v_pk_fma_f32 v[72:73], v[0:1], v[116:117], v[118:119] op_sel_hi:[1,0,1]
	v_mov_b32_e32 v116, v225
	v_pk_fma_f32 v[82:83], v[56:57], v[222:223], v[82:83] op_sel:[0,1,0]
	v_pk_fma_f32 v[112:113], v[58:59], v[224:225], v[112:113] op_sel_hi:[1,0,1]
	v_pk_fma_f32 v[114:115], v[56:57], v[224:225], v[114:115] op_sel_hi:[1,0,1]
	v_pk_fma_f32 v[118:119], v[58:59], v[116:117], v[66:67] op_sel_hi:[1,0,1]
	v_pk_fma_f32 v[120:121], v[56:57], v[116:117], v[64:65] op_sel_hi:[1,0,1]
	s_mov_b32 s0, 0xb644000
	ds_read_b128 v[56:59], v177
	ds_read_b128 v[64:67], v177 offset:4096
	v_add_co_u32_e32 v222, vcc, s0, v108
	s_mov_b32 s0, 0xb646000
	s_nop 0
	v_addc_co_u32_e32 v223, vcc, 0, v109, vcc
	global_store_dwordx4 v[222:223], v[72:75], off nt
	s_nop 1
	v_mov_b32_e32 v72, v117
	s_waitcnt vmcnt(23)
	v_pk_mul_f32 v[74:75], v[50:51], v[72:73] op_sel_hi:[1,0]
	v_pk_mul_f32 v[72:73], v[48:49], v[72:73] op_sel_hi:[1,0]
	s_waitcnt lgkmcnt(0)
	v_pk_fma_f32 v[74:75], v[14:15], v[64:65], v[74:75] op_sel_hi:[1,0,1]
	v_pk_fma_f32 v[72:73], v[12:13], v[64:65], v[72:73] op_sel_hi:[1,0,1]
	v_pk_fma_f32 v[74:75], v[10:11], v[64:65], v[74:75] op_sel:[0,1,0]
	v_pk_fma_f32 v[116:117], v[50:51], v[56:57], v[122:123] op_sel_hi:[1,0,1]
	v_pk_fma_f32 v[122:123], v[48:49], v[56:57], v[230:231] op_sel_hi:[1,0,1]
	v_pk_fma_f32 v[64:65], v[8:9], v[64:65], v[72:73] op_sel:[0,1,0]
	v_pk_fma_f32 v[72:73], v[50:51], v[56:57], v[80:81] op_sel:[0,1,0]
	v_pk_fma_f32 v[80:81], v[48:49], v[56:57], v[82:83] op_sel:[0,1,0]
	v_pk_fma_f32 v[56:57], v[6:7], v[66:67], v[74:75] op_sel_hi:[1,0,1]
	v_pk_fma_f32 v[74:75], v[50:51], v[58:59], v[112:113] op_sel_hi:[1,0,1]
	v_pk_fma_f32 v[82:83], v[48:49], v[58:59], v[114:115] op_sel_hi:[1,0,1]
	v_mov_b32_e32 v58, v67
	v_pk_fma_f32 v[64:65], v[4:5], v[66:67], v[64:65] op_sel_hi:[1,0,1]
	v_pk_fma_f32 v[66:67], v[2:3], v[58:59], v[56:57] op_sel_hi:[1,0,1]
	v_mov_b32_e32 v56, v59
	v_pk_fma_f32 v[64:65], v[0:1], v[58:59], v[64:65] op_sel_hi:[1,0,1]
	v_pk_fma_f32 v[112:113], v[50:51], v[56:57], v[118:119] op_sel_hi:[1,0,1]
	v_pk_fma_f32 v[114:115], v[48:49], v[56:57], v[120:121] op_sel_hi:[1,0,1]
	ds_read_b128 v[48:51], v178
	ds_read_b128 v[56:59], v178 offset:4096
	ds_read2_b32 v[118:119], v107 offset0:144 offset1:148
	v_add_co_u32_e32 v120, vcc, s0, v108
	s_waitcnt vmcnt(22) lgkmcnt(2)
	v_pk_fma_f32 v[116:117], v[42:43], v[48:49], v[116:117] op_sel_hi:[1,0,1]
	v_addc_co_u32_e32 v121, vcc, 0, v109, vcc
	global_store_dwordx4 v[120:121], v[64:67], off nt
	v_pk_fma_f32 v[120:121], v[40:41], v[48:49], v[122:123] op_sel_hi:[1,0,1]
	s_mov_b32 s0, 0xb648000
	s_waitcnt lgkmcnt(0)
	v_pk_mul_f32 v[64:65], v[42:43], v[118:119] op_sel_hi:[1,0]
	v_pk_mul_f32 v[66:67], v[40:41], v[118:119] op_sel_hi:[1,0]
	v_pk_fma_f32 v[64:65], v[14:15], v[56:57], v[64:65] op_sel_hi:[1,0,1]
	v_pk_fma_f32 v[66:67], v[12:13], v[56:57], v[66:67] op_sel_hi:[1,0,1]
	v_pk_fma_f32 v[64:65], v[10:11], v[56:57], v[64:65] op_sel:[0,1,0]
	v_pk_fma_f32 v[56:57], v[8:9], v[56:57], v[66:67] op_sel:[0,1,0]
	v_pk_fma_f32 v[66:67], v[42:43], v[48:49], v[72:73] op_sel:[0,1,0]
	v_pk_fma_f32 v[72:73], v[40:41], v[48:49], v[80:81] op_sel:[0,1,0]
	v_pk_fma_f32 v[48:49], v[6:7], v[58:59], v[64:65] op_sel_hi:[1,0,1]
	v_pk_fma_f32 v[64:65], v[42:43], v[50:51], v[74:75] op_sel_hi:[1,0,1]
	v_pk_fma_f32 v[74:75], v[40:41], v[50:51], v[82:83] op_sel_hi:[1,0,1]
	v_mov_b32_e32 v50, v59
	v_pk_fma_f32 v[56:57], v[4:5], v[58:59], v[56:57] op_sel_hi:[1,0,1]
	v_pk_fma_f32 v[58:59], v[2:3], v[50:51], v[48:49] op_sel_hi:[1,0,1]
	v_mov_b32_e32 v48, v51
	v_pk_fma_f32 v[56:57], v[0:1], v[50:51], v[56:57] op_sel_hi:[1,0,1]
	v_pk_fma_f32 v[80:81], v[42:43], v[48:49], v[112:113] op_sel_hi:[1,0,1]
	v_pk_fma_f32 v[82:83], v[40:41], v[48:49], v[114:115] op_sel_hi:[1,0,1]
	ds_read_b128 v[40:43], v179
	ds_read_b128 v[48:51], v179 offset:4096
	v_add_co_u32_e32 v112, vcc, s0, v108
	s_mov_b32 s0, 0xb64a000
	s_nop 0
	v_addc_co_u32_e32 v113, vcc, 0, v109, vcc
	global_store_dwordx4 v[112:113], v[56:59], off nt
	s_waitcnt vmcnt(23) lgkmcnt(1)
	v_pk_fma_f32 v[112:113], v[34:35], v[40:41], v[116:117] op_sel_hi:[1,0,1]
	v_pk_fma_f32 v[114:115], v[32:33], v[40:41], v[120:121] op_sel_hi:[1,0,1]
	v_mov_b32_e32 v56, v119
	v_pk_mul_f32 v[58:59], v[34:35], v[56:57] op_sel_hi:[1,0]
	v_pk_mul_f32 v[56:57], v[32:33], v[56:57] op_sel_hi:[1,0]
	s_waitcnt lgkmcnt(0)
; __device__ __forceinline__ void gla_sample_unit(const Args& a, unsigned char* lds, int unit, int tid) {
;     ...
;     f32x4 sb[2][8];
; #pragma unroll
;     for (int i = 0; i < 8; ++i) sb[0][i] = *(const f32x4*)(S0 + (size_t)(i * 4 + kq) * 512 + vc);
; #pragma unroll
;     for (int g = 0; g < 8; ++g) {
;         if (g + 1 < 8) {
; #pragma unroll
;             for (int i = 0; i < 8; ++i) sb[(g + 1) & 1][i] = *(const f32x4*)(S0 + (size_t)(((g + 1) * 8 + i) * 4 + kq) * 512 + vc); }
; #pragma unroll
;         for (int i = 0; i < 8; ++i) { const int k = (g * 8 + i) * 4 + kq; const f32x4 s = sb[g & 1][i];
;             const f32x4 qv = *(const f32x4*)(Q4 + k * 4), kd = *(const f32x4*)(KD4 + k * 4); const float dec = DECS[k];
;             f32x4 sn = s * dec;
; #pragma unroll
;             for (int t = 0; t < 4; ++t) { sn += vr[t] * kd[t]; o[t] += s * qv[t]; }
;             *(f32x4*)(SN + (size_t)k * 512 + vc) = sn; } }
	v_pk_fma_f32 v[58:59], v[14:15], v[48:49], v[58:59] op_sel_hi:[1,0,1]
	v_pk_fma_f32 v[56:57], v[12:13], v[48:49], v[56:57] op_sel_hi:[1,0,1]
	v_pk_fma_f32 v[58:59], v[10:11], v[48:49], v[58:59] op_sel:[0,1,0]
	v_pk_fma_f32 v[48:49], v[8:9], v[48:49], v[56:57] op_sel:[0,1,0]
	v_pk_fma_f32 v[56:57], v[34:35], v[40:41], v[66:67] op_sel:[0,1,0]
	v_pk_fma_f32 v[66:67], v[32:33], v[40:41], v[72:73] op_sel:[0,1,0]
	v_pk_fma_f32 v[40:41], v[6:7], v[50:51], v[58:59] op_sel_hi:[1,0,1]
	v_pk_fma_f32 v[58:59], v[34:35], v[42:43], v[64:65] op_sel_hi:[1,0,1]
	v_pk_fma_f32 v[64:65], v[32:33], v[42:43], v[74:75] op_sel_hi:[1,0,1]
	v_mov_b32_e32 v42, v51
	v_pk_fma_f32 v[48:49], v[4:5], v[50:51], v[48:49] op_sel_hi:[1,0,1]
	v_pk_fma_f32 v[50:51], v[2:3], v[42:43], v[40:41] op_sel_hi:[1,0,1]
	v_mov_b32_e32 v40, v43
	v_pk_fma_f32 v[48:49], v[0:1], v[42:43], v[48:49] op_sel_hi:[1,0,1]
	v_pk_fma_f32 v[72:73], v[34:35], v[40:41], v[80:81] op_sel_hi:[1,0,1]
	v_pk_fma_f32 v[74:75], v[32:33], v[40:41], v[82:83] op_sel_hi:[1,0,1]
	ds_read_b128 v[32:35], v180
	ds_read_b128 v[40:43], v180 offset:4096
	ds_read2_b32 v[80:81], v107 offset0:152 offset1:156
	v_add_co_u32_e32 v82, vcc, s0, v108
	s_mov_b32 s0, 0xb64c000
	s_nop 0
	v_addc_co_u32_e32 v83, vcc, 0, v109, vcc
	global_store_dwordx4 v[82:83], v[48:51], off nt
	s_waitcnt vmcnt(23) lgkmcnt(2)
	v_pk_fma_f32 v[82:83], v[26:27], v[32:33], v[112:113] op_sel_hi:[1,0,1]
	v_pk_fma_f32 v[112:113], v[24:25], v[32:33], v[114:115] op_sel_hi:[1,0,1]
	s_waitcnt lgkmcnt(0)
	v_pk_mul_f32 v[48:49], v[26:27], v[80:81] op_sel_hi:[1,0]
	v_pk_mul_f32 v[50:51], v[24:25], v[80:81] op_sel_hi:[1,0]
	v_pk_fma_f32 v[48:49], v[14:15], v[40:41], v[48:49] op_sel_hi:[1,0,1]
	v_pk_fma_f32 v[50:51], v[12:13], v[40:41], v[50:51] op_sel_hi:[1,0,1]
	v_pk_fma_f32 v[48:49], v[10:11], v[40:41], v[48:49] op_sel:[0,1,0]
	v_pk_fma_f32 v[40:41], v[8:9], v[40:41], v[50:51] op_sel:[0,1,0]
	v_pk_fma_f32 v[50:51], v[26:27], v[32:33], v[56:57] op_sel:[0,1,0]
	v_pk_fma_f32 v[56:57], v[24:25], v[32:33], v[66:67] op_sel:[0,1,0]
	v_pk_fma_f32 v[32:33], v[6:7], v[42:43], v[48:49] op_sel_hi:[1,0,1]
	v_pk_fma_f32 v[48:49], v[26:27], v[34:35], v[58:59] op_sel_hi:[1,0,1]
	v_pk_fma_f32 v[58:59], v[24:25], v[34:35], v[64:65] op_sel_hi:[1,0,1]
	v_mov_b32_e32 v34, v43
	v_pk_fma_f32 v[40:41], v[4:5], v[42:43], v[40:41] op_sel_hi:[1,0,1]
	v_pk_fma_f32 v[42:43], v[2:3], v[34:35], v[32:33] op_sel_hi:[1,0,1]
	v_mov_b32_e32 v32, v35
	v_pk_fma_f32 v[40:41], v[0:1], v[34:35], v[40:41] op_sel_hi:[1,0,1]
	v_pk_fma_f32 v[64:65], v[26:27], v[32:33], v[72:73] op_sel_hi:[1,0,1]
	v_pk_fma_f32 v[66:67], v[24:25], v[32:33], v[74:75] op_sel_hi:[1,0,1]
	ds_read_b128 v[24:27], v181
	ds_read_b128 v[32:35], v181 offset:4096
	v_add_co_u32_e32 v72, vcc, s0, v108
	s_mov_b32 s0, 0xb64e000
	s_nop 0
	v_addc_co_u32_e32 v73, vcc, 0, v109, vcc
	global_store_dwordx4 v[72:73], v[40:43], off nt
	s_waitcnt vmcnt(23) lgkmcnt(1)
	v_pk_fma_f32 v[114:115], v[16:17], v[24:25], v[56:57] op_sel:[0,1,0]
	v_pk_fma_f32 v[116:117], v[18:19], v[26:27], v[48:49] op_sel_hi:[1,0,1]
	v_mov_b32_e32 v40, v81
	v_pk_mul_f32 v[42:43], v[18:19], v[40:41] op_sel_hi:[1,0]
	v_pk_mul_f32 v[40:41], v[16:17], v[40:41] op_sel_hi:[1,0]
	s_waitcnt lgkmcnt(0)
	v_pk_fma_f32 v[42:43], v[14:15], v[32:33], v[42:43] op_sel_hi:[1,0,1]
	v_pk_fma_f32 v[40:41], v[12:13], v[32:33], v[40:41] op_sel_hi:[1,0,1]
	v_pk_fma_f32 v[42:43], v[10:11], v[32:33], v[42:43] op_sel:[0,1,0]
	v_pk_fma_f32 v[80:81], v[18:19], v[24:25], v[82:83] op_sel_hi:[1,0,1]
	v_pk_fma_f32 v[82:83], v[16:17], v[24:25], v[112:113] op_sel_hi:[1,0,1]
	v_pk_fma_f32 v[32:33], v[8:9], v[32:33], v[40:41] op_sel:[0,1,0]
	v_pk_fma_f32 v[112:113], v[18:19], v[24:25], v[50:51] op_sel:[0,1,0]
	v_pk_fma_f32 v[24:25], v[6:7], v[34:35], v[42:43] op_sel_hi:[1,0,1]
	v_pk_fma_f32 v[118:119], v[16:17], v[26:27], v[58:59] op_sel_hi:[1,0,1]
	v_mov_b32_e32 v26, v35
	v_pk_fma_f32 v[32:33], v[4:5], v[34:35], v[32:33] op_sel_hi:[1,0,1]
	v_pk_fma_f32 v[34:35], v[2:3], v[26:27], v[24:25] op_sel_hi:[1,0,1]
	v_mov_b32_e32 v24, v27
	v_pk_fma_f32 v[122:123], v[16:17], v[24:25], v[66:67] op_sel_hi:[1,0,1]
	v_add_co_u32_e32 v16, vcc, s0, v108
	v_pk_fma_f32 v[32:33], v[0:1], v[26:27], v[32:33] op_sel_hi:[1,0,1]
	s_nop 0
	v_addc_co_u32_e32 v17, vcc, 0, v109, vcc
	s_mov_b32 s0, 0x60000
	global_store_dwordx4 v[16:17], v[32:35], off nt
	v_add_co_u32_e32 v16, vcc, s0, v110
	s_mov_b32 s0, 0x62000
	s_nop 0
	v_addc_co_u32_e32 v17, vcc, 0, v111, vcc
	v_pk_fma_f32 v[120:121], v[18:19], v[24:25], v[64:65] op_sel_hi:[1,0,1]
	v_add_co_u32_e32 v18, vcc, s0, v110
	s_mov_b32 s0, 0x64000
	s_nop 0
	v_addc_co_u32_e32 v19, vcc, 0, v111, vcc
	global_load_dwordx4 v[72:75], v[16:17], off nt
	global_load_dwordx4 v[64:67], v[18:19], off nt
	v_add_co_u32_e32 v16, vcc, s0, v110
	s_mov_b32 s0, 0x66000
	s_nop 0
	v_addc_co_u32_e32 v17, vcc, 0, v111, vcc
	v_add_co_u32_e32 v18, vcc, s0, v110
	s_mov_b32 s0, 0x68000
	s_nop 0
	v_addc_co_u32_e32 v19, vcc, 0, v111, vcc
	global_load_dwordx4 v[56:59], v[16:17], off nt
	global_load_dwordx4 v[48:51], v[18:19], off nt
	v_add_co_u32_e32 v16, vcc, s0, v110
	s_mov_b32 s0, 0x6a000
	s_nop 0
	v_addc_co_u32_e32 v17, vcc, 0, v111, vcc
	v_add_co_u32_e32 v18, vcc, s0, v110
	s_mov_b32 s0, 0x6c000
	s_nop 0
	v_addc_co_u32_e32 v19, vcc, 0, v111, vcc
	global_load_dwordx4 v[40:43], v[16:17], off nt
	global_load_dwordx4 v[32:35], v[18:19], off nt
	ds_read2_b32 v[230:231], v107 offset0:160 offset1:164
	ds_read_b128 v[222:225], v182
	ds_read_b128 v[226:229], v182 offset:4096
	v_add_co_u32_e32 v16, vcc, s0, v110
	s_waitcnt vmcnt(21) lgkmcnt(2)
	v_pk_mul_f32 v[232:233], v[78:79], v[230:231] op_sel_hi:[1,0]
	v_pk_mul_f32 v[234:235], v[76:77], v[230:231] op_sel_hi:[1,0]
	s_waitcnt lgkmcnt(0)
; __device__ __forceinline__ void gla_sample_unit(const Args& a, unsigned char* lds, int unit, int tid) {
;     ...
;     f32x4 sb[2][8];
; #pragma unroll
;     for (int i = 0; i < 8; ++i) sb[0][i] = *(const f32x4*)(S0 + (size_t)(i * 4 + kq) * 512 + vc);
; #pragma unroll
;     for (int g = 0; g < 8; ++g) {
;         if (g + 1 < 8) {
; #pragma unroll
;             for (int i = 0; i < 8; ++i) sb[(g + 1) & 1][i] = *(const f32x4*)(S0 + (size_t)(((g + 1) * 8 + i) * 4 + kq) * 512 + vc); }
; #pragma unroll
;         for (int i = 0; i < 8; ++i) { const int k = (g * 8 + i) * 4 + kq; const f32x4 s = sb[g & 1][i];
;             const f32x4 qv = *(const f32x4*)(Q4 + k * 4), kd = *(const f32x4*)(KD4 + k * 4); const float dec = DECS[k];
;             f32x4 sn = s * dec;
; #pragma unroll
;             for (int t = 0; t < 4; ++t) { sn += vr[t] * kd[t]; o[t] += s * qv[t]; }
;             *(f32x4*)(SN + (size_t)k * 512 + vc) = sn; } }
	v_pk_fma_f32 v[232:233], v[14:15], v[226:227], v[232:233] op_sel_hi:[1,0,1]
	v_pk_fma_f32 v[234:235], v[12:13], v[226:227], v[234:235] op_sel_hi:[1,0,1]
	v_addc_co_u32_e32 v17, vcc, 0, v111, vcc
	s_mov_b32 s0, 0x6e000
	v_pk_fma_f32 v[236:237], v[78:79], v[222:223], v[80:81] op_sel_hi:[1,0,1]
	v_pk_fma_f32 v[238:239], v[76:77], v[222:223], v[82:83] op_sel_hi:[1,0,1]
	v_pk_fma_f32 v[80:81], v[10:11], v[226:227], v[232:233] op_sel:[0,1,0]
	v_pk_fma_f32 v[82:83], v[8:9], v[226:227], v[234:235] op_sel:[0,1,0]
	v_add_co_u32_e32 v18, vcc, s0, v110
	v_pk_fma_f32 v[112:113], v[78:79], v[222:223], v[112:113] op_sel:[0,1,0]
	v_pk_fma_f32 v[222:223], v[76:77], v[222:223], v[114:115] op_sel:[0,1,0]
	v_pk_fma_f32 v[80:81], v[6:7], v[228:229], v[80:81] op_sel_hi:[1,0,1]
	v_pk_fma_f32 v[114:115], v[4:5], v[228:229], v[82:83] op_sel_hi:[1,0,1]
	v_pk_fma_f32 v[226:227], v[78:79], v[224:225], v[116:117] op_sel_hi:[1,0,1]
	v_mov_b32_e32 v116, v229
	v_addc_co_u32_e32 v19, vcc, 0, v111, vcc
	v_pk_fma_f32 v[82:83], v[2:3], v[116:117], v[80:81] op_sel_hi:[1,0,1]
	v_pk_fma_f32 v[80:81], v[0:1], v[116:117], v[114:115] op_sel_hi:[1,0,1]
	v_mov_b32_e32 v114, v225
	global_load_dwordx4 v[24:27], v[16:17], off nt
	s_nop 0
	global_load_dwordx4 v[16:19], v[18:19], off nt
	v_pk_fma_f32 v[232:233], v[76:77], v[224:225], v[118:119] op_sel_hi:[1,0,1]
	v_pk_fma_f32 v[224:225], v[78:79], v[114:115], v[120:121] op_sel_hi:[1,0,1]
	v_pk_fma_f32 v[122:123], v[76:77], v[114:115], v[122:123] op_sel_hi:[1,0,1]
	s_mov_b32 s0, 0xb650000
	ds_read_b128 v[114:117], v183
	ds_read_b128 v[118:121], v183 offset:4096
	v_add_co_u32_e32 v76, vcc, s0, v108
	s_mov_b32 s0, 0xb652000
	s_nop 0
	v_addc_co_u32_e32 v77, vcc, 0, v109, vcc
	global_store_dwordx4 v[76:77], v[80:83], off nt
	v_mov_b32_e32 v76, v231
	s_waitcnt vmcnt(23)
	v_pk_mul_f32 v[78:79], v[70:71], v[76:77] op_sel_hi:[1,0]
	v_pk_mul_f32 v[76:77], v[68:69], v[76:77] op_sel_hi:[1,0]
	s_waitcnt lgkmcnt(0)
	v_pk_fma_f32 v[80:81], v[14:15], v[118:119], v[78:79] op_sel_hi:[1,0,1]
	v_pk_fma_f32 v[82:83], v[12:13], v[118:119], v[76:77] op_sel_hi:[1,0,1]
	v_pk_fma_f32 v[228:229], v[10:11], v[118:119], v[80:81] op_sel:[0,1,0]
	v_pk_fma_f32 v[118:119], v[8:9], v[118:119], v[82:83] op_sel:[0,1,0]
	v_pk_fma_f32 v[76:77], v[70:71], v[114:115], v[236:237] op_sel_hi:[1,0,1]
	v_pk_fma_f32 v[78:79], v[68:69], v[114:115], v[238:239] op_sel_hi:[1,0,1]
	v_pk_fma_f32 v[80:81], v[70:71], v[114:115], v[112:113] op_sel:[0,1,0]
	v_pk_fma_f32 v[82:83], v[68:69], v[114:115], v[222:223] op_sel:[0,1,0]
	v_pk_fma_f32 v[222:223], v[6:7], v[120:121], v[228:229] op_sel_hi:[1,0,1]
	v_pk_fma_f32 v[118:119], v[4:5], v[120:121], v[118:119] op_sel_hi:[1,0,1]
	v_pk_fma_f32 v[112:113], v[70:71], v[116:117], v[226:227] op_sel_hi:[1,0,1]
	v_pk_fma_f32 v[114:115], v[68:69], v[116:117], v[232:233] op_sel_hi:[1,0,1]
	v_mov_b32_e32 v116, v121
	v_pk_fma_f32 v[120:121], v[2:3], v[116:117], v[222:223] op_sel_hi:[1,0,1]
	v_pk_fma_f32 v[118:119], v[0:1], v[116:117], v[118:119] op_sel_hi:[1,0,1]
	v_mov_b32_e32 v116, v117
	v_pk_fma_f32 v[70:71], v[70:71], v[116:117], v[224:225] op_sel_hi:[1,0,1]
	v_pk_fma_f32 v[68:69], v[68:69], v[116:117], v[122:123] op_sel_hi:[1,0,1]
	ds_read_b128 v[222:225], v185
	ds_read_b128 v[226:229], v185 offset:4096
	ds_read2_b32 v[116:117], v107 offset0:168 offset1:172
	v_add_co_u32_e32 v122, vcc, s0, v108
	s_waitcnt vmcnt(22) lgkmcnt(2)
	v_pk_fma_f32 v[230:231], v[60:61], v[222:223], v[78:79] op_sel_hi:[1,0,1]
	v_addc_co_u32_e32 v123, vcc, 0, v109, vcc
	global_store_dwordx4 v[122:123], v[118:121], off nt
	v_pk_fma_f32 v[122:123], v[62:63], v[222:223], v[76:77] op_sel_hi:[1,0,1]
	v_pk_fma_f32 v[80:81], v[62:63], v[222:223], v[80:81] op_sel:[0,1,0]
	s_waitcnt lgkmcnt(0)
	v_pk_mul_f32 v[118:119], v[62:63], v[116:117] op_sel_hi:[1,0]
	v_pk_mul_f32 v[120:121], v[60:61], v[116:117] op_sel_hi:[1,0]
	v_pk_fma_f32 v[118:119], v[14:15], v[226:227], v[118:119] op_sel_hi:[1,0,1]
	v_pk_fma_f32 v[120:121], v[12:13], v[226:227], v[120:121] op_sel_hi:[1,0,1]
	v_pk_fma_f32 v[76:77], v[10:11], v[226:227], v[118:119] op_sel:[0,1,0]
	v_pk_fma_f32 v[78:79], v[8:9], v[226:227], v[120:121] op_sel:[0,1,0]
	v_pk_fma_f32 v[76:77], v[6:7], v[228:229], v[76:77] op_sel_hi:[1,0,1]
	v_pk_fma_f32 v[118:119], v[4:5], v[228:229], v[78:79] op_sel_hi:[1,0,1]
	v_mov_b32_e32 v116, v229
	v_pk_fma_f32 v[78:79], v[2:3], v[116:117], v[76:77] op_sel_hi:[1,0,1]
	v_pk_fma_f32 v[76:77], v[0:1], v[116:117], v[118:119] op_sel_hi:[1,0,1]
	v_mov_b32_e32 v116, v225
	v_pk_fma_f32 v[82:83], v[60:61], v[222:223], v[82:83] op_sel:[0,1,0]
	v_pk_fma_f32 v[112:113], v[62:63], v[224:225], v[112:113] op_sel_hi:[1,0,1]
	v_pk_fma_f32 v[114:115], v[60:61], v[224:225], v[114:115] op_sel_hi:[1,0,1]
	v_pk_fma_f32 v[118:119], v[62:63], v[116:117], v[70:71] op_sel_hi:[1,0,1]
	v_pk_fma_f32 v[120:121], v[60:61], v[116:117], v[68:69] op_sel_hi:[1,0,1]
	s_mov_b32 s0, 0xb654000
	ds_read_b128 v[60:63], v187
	ds_read_b128 v[68:71], v187 offset:4096
	v_add_co_u32_e32 v222, vcc, s0, v108
	s_mov_b32 s0, 0xb656000
	s_nop 0
	v_addc_co_u32_e32 v223, vcc, 0, v109, vcc
	global_store_dwordx4 v[222:223], v[76:79], off nt
	s_nop 1
	v_mov_b32_e32 v76, v117
	s_waitcnt vmcnt(23)
	v_pk_mul_f32 v[78:79], v[54:55], v[76:77] op_sel_hi:[1,0]
	v_pk_mul_f32 v[76:77], v[52:53], v[76:77] op_sel_hi:[1,0]
	s_waitcnt lgkmcnt(0)
; __device__ __forceinline__ void gla_sample_unit(const Args& a, unsigned char* lds, int unit, int tid) {
;     ...
;     f32x4 sb[2][8];
; #pragma unroll
;     for (int i = 0; i < 8; ++i) sb[0][i] = *(const f32x4*)(S0 + (size_t)(i * 4 + kq) * 512 + vc);
; #pragma unroll
;     for (int g = 0; g < 8; ++g) {
;         if (g + 1 < 8) {
; #pragma unroll
;             for (int i = 0; i < 8; ++i) sb[(g + 1) & 1][i] = *(const f32x4*)(S0 + (size_t)(((g + 1) * 8 + i) * 4 + kq) * 512 + vc); }
; #pragma unroll
;         for (int i = 0; i < 8; ++i) { const int k = (g * 8 + i) * 4 + kq; const f32x4 s = sb[g & 1][i];
;             const f32x4 qv = *(const f32x4*)(Q4 + k * 4), kd = *(const f32x4*)(KD4 + k * 4); const float dec = DECS[k];
;             f32x4 sn = s * dec;
; #pragma unroll
;             for (int t = 0; t < 4; ++t) { sn += vr[t] * kd[t]; o[t] += s * qv[t]; }
;             *(f32x4*)(SN + (size_t)k * 512 + vc) = sn; } }
	v_pk_fma_f32 v[78:79], v[14:15], v[68:69], v[78:79] op_sel_hi:[1,0,1]
	v_pk_fma_f32 v[76:77], v[12:13], v[68:69], v[76:77] op_sel_hi:[1,0,1]
	v_pk_fma_f32 v[78:79], v[10:11], v[68:69], v[78:79] op_sel:[0,1,0]
	v_pk_fma_f32 v[116:117], v[54:55], v[60:61], v[122:123] op_sel_hi:[1,0,1]
	v_pk_fma_f32 v[122:123], v[52:53], v[60:61], v[230:231] op_sel_hi:[1,0,1]
	v_pk_fma_f32 v[68:69], v[8:9], v[68:69], v[76:77] op_sel:[0,1,0]
	v_pk_fma_f32 v[76:77], v[54:55], v[60:61], v[80:81] op_sel:[0,1,0]
	v_pk_fma_f32 v[80:81], v[52:53], v[60:61], v[82:83] op_sel:[0,1,0]
	v_pk_fma_f32 v[60:61], v[6:7], v[70:71], v[78:79] op_sel_hi:[1,0,1]
	v_pk_fma_f32 v[78:79], v[54:55], v[62:63], v[112:113] op_sel_hi:[1,0,1]
	v_pk_fma_f32 v[82:83], v[52:53], v[62:63], v[114:115] op_sel_hi:[1,0,1]
	v_mov_b32_e32 v62, v71
	v_pk_fma_f32 v[68:69], v[4:5], v[70:71], v[68:69] op_sel_hi:[1,0,1]
	v_pk_fma_f32 v[70:71], v[2:3], v[62:63], v[60:61] op_sel_hi:[1,0,1]
	v_mov_b32_e32 v60, v63
	v_pk_fma_f32 v[68:69], v[0:1], v[62:63], v[68:69] op_sel_hi:[1,0,1]
	v_pk_fma_f32 v[112:113], v[54:55], v[60:61], v[118:119] op_sel_hi:[1,0,1]
	v_pk_fma_f32 v[114:115], v[52:53], v[60:61], v[120:121] op_sel_hi:[1,0,1]
	ds_read_b128 v[52:55], v190
	ds_read_b128 v[60:63], v190 offset:4096
	ds_read2_b32 v[118:119], v107 offset0:176 offset1:180
	v_add_co_u32_e32 v120, vcc, s0, v108
	s_waitcnt vmcnt(22) lgkmcnt(2)
	v_pk_fma_f32 v[116:117], v[46:47], v[52:53], v[116:117] op_sel_hi:[1,0,1]
	v_addc_co_u32_e32 v121, vcc, 0, v109, vcc
	global_store_dwordx4 v[120:121], v[68:71], off nt
	v_pk_fma_f32 v[120:121], v[44:45], v[52:53], v[122:123] op_sel_hi:[1,0,1]
	s_mov_b32 s0, 0xb658000
	s_waitcnt lgkmcnt(0)
	v_pk_mul_f32 v[68:69], v[46:47], v[118:119] op_sel_hi:[1,0]
	v_pk_mul_f32 v[70:71], v[44:45], v[118:119] op_sel_hi:[1,0]
	v_pk_fma_f32 v[68:69], v[14:15], v[60:61], v[68:69] op_sel_hi:[1,0,1]
	v_pk_fma_f32 v[70:71], v[12:13], v[60:61], v[70:71] op_sel_hi:[1,0,1]
	v_pk_fma_f32 v[68:69], v[10:11], v[60:61], v[68:69] op_sel:[0,1,0]
	v_pk_fma_f32 v[60:61], v[8:9], v[60:61], v[70:71] op_sel:[0,1,0]
	v_pk_fma_f32 v[70:71], v[46:47], v[52:53], v[76:77] op_sel:[0,1,0]
	v_pk_fma_f32 v[76:77], v[44:45], v[52:53], v[80:81] op_sel:[0,1,0]
	v_pk_fma_f32 v[52:53], v[6:7], v[62:63], v[68:69] op_sel_hi:[1,0,1]
	v_pk_fma_f32 v[68:69], v[46:47], v[54:55], v[78:79] op_sel_hi:[1,0,1]
	v_pk_fma_f32 v[78:79], v[44:45], v[54:55], v[82:83] op_sel_hi:[1,0,1]
	v_mov_b32_e32 v54, v63
	v_pk_fma_f32 v[60:61], v[4:5], v[62:63], v[60:61] op_sel_hi:[1,0,1]
	v_pk_fma_f32 v[62:63], v[2:3], v[54:55], v[52:53] op_sel_hi:[1,0,1]
	v_mov_b32_e32 v52, v55
	v_pk_fma_f32 v[60:61], v[0:1], v[54:55], v[60:61] op_sel_hi:[1,0,1]
	v_pk_fma_f32 v[80:81], v[46:47], v[52:53], v[112:113] op_sel_hi:[1,0,1]
	v_pk_fma_f32 v[82:83], v[44:45], v[52:53], v[114:115] op_sel_hi:[1,0,1]
	ds_read_b128 v[44:47], v191
	ds_read_b128 v[52:55], v191 offset:4096
	v_add_co_u32_e32 v112, vcc, s0, v108
	s_mov_b32 s0, 0xb65a000
	s_nop 0
	v_addc_co_u32_e32 v113, vcc, 0, v109, vcc
	global_store_dwordx4 v[112:113], v[60:63], off nt
	s_waitcnt vmcnt(23) lgkmcnt(1)
	v_pk_fma_f32 v[112:113], v[38:39], v[44:45], v[116:117] op_sel_hi:[1,0,1]
	v_pk_fma_f32 v[114:115], v[36:37], v[44:45], v[120:121] op_sel_hi:[1,0,1]
	v_mov_b32_e32 v60, v119
	v_pk_mul_f32 v[62:63], v[38:39], v[60:61] op_sel_hi:[1,0]
	v_pk_mul_f32 v[60:61], v[36:37], v[60:61] op_sel_hi:[1,0]
	s_waitcnt lgkmcnt(0)
	v_pk_fma_f32 v[62:63], v[14:15], v[52:53], v[62:63] op_sel_hi:[1,0,1]
	v_pk_fma_f32 v[60:61], v[12:13], v[52:53], v[60:61] op_sel_hi:[1,0,1]
	v_pk_fma_f32 v[62:63], v[10:11], v[52:53], v[62:63] op_sel:[0,1,0]
	v_pk_fma_f32 v[52:53], v[8:9], v[52:53], v[60:61] op_sel:[0,1,0]
	v_pk_fma_f32 v[60:61], v[38:39], v[44:45], v[70:71] op_sel:[0,1,0]
	v_pk_fma_f32 v[70:71], v[36:37], v[44:45], v[76:77] op_sel:[0,1,0]
	v_pk_fma_f32 v[44:45], v[6:7], v[54:55], v[62:63] op_sel_hi:[1,0,1]
	v_pk_fma_f32 v[62:63], v[38:39], v[46:47], v[68:69] op_sel_hi:[1,0,1]
	v_pk_fma_f32 v[68:69], v[36:37], v[46:47], v[78:79] op_sel_hi:[1,0,1]
	v_mov_b32_e32 v46, v55
	v_pk_fma_f32 v[52:53], v[4:5], v[54:55], v[52:53] op_sel_hi:[1,0,1]
	v_pk_fma_f32 v[54:55], v[2:3], v[46:47], v[44:45] op_sel_hi:[1,0,1]
	v_mov_b32_e32 v44, v47
	v_pk_fma_f32 v[52:53], v[0:1], v[46:47], v[52:53] op_sel_hi:[1,0,1]
	v_pk_fma_f32 v[76:77], v[38:39], v[44:45], v[80:81] op_sel_hi:[1,0,1]
	v_pk_fma_f32 v[78:79], v[36:37], v[44:45], v[82:83] op_sel_hi:[1,0,1]
	ds_read_b128 v[36:39], v192
	ds_read_b128 v[44:47], v192 offset:4096
	ds_read2_b32 v[80:81], v107 offset0:184 offset1:188
	v_add_co_u32_e32 v82, vcc, s0, v108
	s_mov_b32 s0, 0xb65c000
	s_nop 0
	v_addc_co_u32_e32 v83, vcc, 0, v109, vcc
	global_store_dwordx4 v[82:83], v[52:55], off nt
	s_waitcnt vmcnt(23) lgkmcnt(2)
	v_pk_fma_f32 v[82:83], v[30:31], v[36:37], v[112:113] op_sel_hi:[1,0,1]
	v_pk_fma_f32 v[112:113], v[28:29], v[36:37], v[114:115] op_sel_hi:[1,0,1]
	s_waitcnt lgkmcnt(0)
	v_pk_mul_f32 v[52:53], v[30:31], v[80:81] op_sel_hi:[1,0]
	v_pk_mul_f32 v[54:55], v[28:29], v[80:81] op_sel_hi:[1,0]
	v_pk_fma_f32 v[52:53], v[14:15], v[44:45], v[52:53] op_sel_hi:[1,0,1]
	v_pk_fma_f32 v[54:55], v[12:13], v[44:45], v[54:55] op_sel_hi:[1,0,1]
	v_pk_fma_f32 v[52:53], v[10:11], v[44:45], v[52:53] op_sel:[0,1,0]
	v_pk_fma_f32 v[44:45], v[8:9], v[44:45], v[54:55] op_sel:[0,1,0]
	v_pk_fma_f32 v[54:55], v[30:31], v[36:37], v[60:61] op_sel:[0,1,0]
	v_pk_fma_f32 v[60:61], v[28:29], v[36:37], v[70:71] op_sel:[0,1,0]
	v_pk_fma_f32 v[36:37], v[6:7], v[46:47], v[52:53] op_sel_hi:[1,0,1]
	v_pk_fma_f32 v[52:53], v[30:31], v[38:39], v[62:63] op_sel_hi:[1,0,1]
	v_pk_fma_f32 v[62:63], v[28:29], v[38:39], v[68:69] op_sel_hi:[1,0,1]
	v_mov_b32_e32 v38, v47
	v_pk_fma_f32 v[44:45], v[4:5], v[46:47], v[44:45] op_sel_hi:[1,0,1]
	v_pk_fma_f32 v[46:47], v[2:3], v[38:39], v[36:37] op_sel_hi:[1,0,1]
	v_mov_b32_e32 v36, v39
	v_pk_fma_f32 v[44:45], v[0:1], v[38:39], v[44:45] op_sel_hi:[1,0,1]
	v_pk_fma_f32 v[68:69], v[30:31], v[36:37], v[76:77] op_sel_hi:[1,0,1]
	v_pk_fma_f32 v[70:71], v[28:29], v[36:37], v[78:79] op_sel_hi:[1,0,1]
	ds_read_b128 v[28:31], v193
	ds_read_b128 v[36:39], v193 offset:4096
	v_add_co_u32_e32 v76, vcc, s0, v108
	s_mov_b32 s0, 0xb65e000
	s_nop 0
	v_addc_co_u32_e32 v77, vcc, 0, v109, vcc
	global_store_dwordx4 v[76:77], v[44:47], off nt
	s_waitcnt vmcnt(23) lgkmcnt(1)
; __device__ __forceinline__ void gla_sample_unit(const Args& a, unsigned char* lds, int unit, int tid) {
;     ...
;     f32x4 sb[2][8];
; #pragma unroll
;     for (int i = 0; i < 8; ++i) sb[0][i] = *(const f32x4*)(S0 + (size_t)(i * 4 + kq) * 512 + vc);
; #pragma unroll
;     for (int g = 0; g < 8; ++g) {
;         if (g + 1 < 8) {
; #pragma unroll
;             for (int i = 0; i < 8; ++i) sb[(g + 1) & 1][i] = *(const f32x4*)(S0 + (size_t)(((g + 1) * 8 + i) * 4 + kq) * 512 + vc); }
; #pragma unroll
;         for (int i = 0; i < 8; ++i) { const int k = (g * 8 + i) * 4 + kq; const f32x4 s = sb[g & 1][i];
;             const f32x4 qv = *(const f32x4*)(Q4 + k * 4), kd = *(const f32x4*)(KD4 + k * 4); const float dec = DECS[k];
;             f32x4 sn = s * dec;
; #pragma unroll
;             for (int t = 0; t < 4; ++t) { sn += vr[t] * kd[t]; o[t] += s * qv[t]; }
;             *(f32x4*)(SN + (size_t)k * 512 + vc) = sn; } }
	v_pk_fma_f32 v[114:115], v[20:21], v[28:29], v[60:61] op_sel:[0,1,0]
	v_pk_fma_f32 v[116:117], v[22:23], v[30:31], v[52:53] op_sel_hi:[1,0,1]
	v_mov_b32_e32 v44, v81
	v_pk_mul_f32 v[46:47], v[22:23], v[44:45] op_sel_hi:[1,0]
	v_pk_mul_f32 v[44:45], v[20:21], v[44:45] op_sel_hi:[1,0]
	s_waitcnt lgkmcnt(0)
	v_pk_fma_f32 v[46:47], v[14:15], v[36:37], v[46:47] op_sel_hi:[1,0,1]
	v_pk_fma_f32 v[44:45], v[12:13], v[36:37], v[44:45] op_sel_hi:[1,0,1]
	v_pk_fma_f32 v[46:47], v[10:11], v[36:37], v[46:47] op_sel:[0,1,0]
	v_pk_fma_f32 v[80:81], v[22:23], v[28:29], v[82:83] op_sel_hi:[1,0,1]
	v_pk_fma_f32 v[82:83], v[20:21], v[28:29], v[112:113] op_sel_hi:[1,0,1]
	v_pk_fma_f32 v[36:37], v[8:9], v[36:37], v[44:45] op_sel:[0,1,0]
	v_pk_fma_f32 v[112:113], v[22:23], v[28:29], v[54:55] op_sel:[0,1,0]
	v_pk_fma_f32 v[28:29], v[6:7], v[38:39], v[46:47] op_sel_hi:[1,0,1]
	v_pk_fma_f32 v[118:119], v[20:21], v[30:31], v[62:63] op_sel_hi:[1,0,1]
	v_mov_b32_e32 v30, v39
	v_pk_fma_f32 v[36:37], v[4:5], v[38:39], v[36:37] op_sel_hi:[1,0,1]
	v_pk_fma_f32 v[38:39], v[2:3], v[30:31], v[28:29] op_sel_hi:[1,0,1]
	v_mov_b32_e32 v28, v31
	v_pk_fma_f32 v[122:123], v[20:21], v[28:29], v[70:71] op_sel_hi:[1,0,1]
	v_add_co_u32_e32 v20, vcc, s0, v108
	v_pk_fma_f32 v[36:37], v[0:1], v[30:31], v[36:37] op_sel_hi:[1,0,1]
	s_nop 0
	v_addc_co_u32_e32 v21, vcc, 0, v109, vcc
	s_mov_b32 s0, 0x70000
	global_store_dwordx4 v[20:21], v[36:39], off nt
	v_add_co_u32_e32 v20, vcc, s0, v110
	s_mov_b32 s0, 0x72000
	s_nop 0
	v_addc_co_u32_e32 v21, vcc, 0, v111, vcc
	v_pk_fma_f32 v[120:121], v[22:23], v[28:29], v[68:69] op_sel_hi:[1,0,1]
	v_add_co_u32_e32 v22, vcc, s0, v110
	s_mov_b32 s0, 0x74000
	s_nop 0
	v_addc_co_u32_e32 v23, vcc, 0, v111, vcc
	global_load_dwordx4 v[76:79], v[20:21], off nt
	global_load_dwordx4 v[68:71], v[22:23], off nt
	v_add_co_u32_e32 v20, vcc, s0, v110
	s_mov_b32 s0, 0x76000
	s_nop 0
	v_addc_co_u32_e32 v21, vcc, 0, v111, vcc
	v_add_co_u32_e32 v22, vcc, s0, v110
	s_mov_b32 s0, 0x78000
	s_nop 0
	v_addc_co_u32_e32 v23, vcc, 0, v111, vcc
	global_load_dwordx4 v[60:63], v[20:21], off nt
	global_load_dwordx4 v[52:55], v[22:23], off nt
	v_add_co_u32_e32 v20, vcc, s0, v110
	s_mov_b32 s0, 0x7a000
	s_nop 0
	v_addc_co_u32_e32 v21, vcc, 0, v111, vcc
	v_add_co_u32_e32 v22, vcc, s0, v110
	s_mov_b32 s0, 0x7c000
	s_nop 0
	v_addc_co_u32_e32 v23, vcc, 0, v111, vcc
	global_load_dwordx4 v[44:47], v[20:21], off nt
	global_load_dwordx4 v[36:39], v[22:23], off nt
	ds_read2_b32 v[230:231], v107 offset0:192 offset1:196
	ds_read_b128 v[222:225], v194
	ds_read_b128 v[226:229], v194 offset:4096
	v_add_co_u32_e32 v20, vcc, s0, v110
	s_mov_b32 s0, 0x7e000
	s_nop 0
	v_addc_co_u32_e32 v21, vcc, 0, v111, vcc
	v_add_co_u32_e32 v22, vcc, s0, v110
	s_waitcnt vmcnt(21) lgkmcnt(2)
	v_pk_mul_f32 v[232:233], v[72:73], v[230:231] op_sel_hi:[1,0]
	v_addc_co_u32_e32 v23, vcc, 0, v111, vcc
	v_pk_mul_f32 v[110:111], v[74:75], v[230:231] op_sel_hi:[1,0]
	s_waitcnt lgkmcnt(0)
	v_pk_fma_f32 v[232:233], v[12:13], v[226:227], v[232:233] op_sel_hi:[1,0,1]
	v_pk_fma_f32 v[110:111], v[14:15], v[226:227], v[110:111] op_sel_hi:[1,0,1]
	v_pk_fma_f32 v[234:235], v[74:75], v[222:223], v[80:81] op_sel_hi:[1,0,1]
	v_pk_fma_f32 v[236:237], v[72:73], v[222:223], v[82:83] op_sel_hi:[1,0,1]
	v_pk_fma_f32 v[80:81], v[10:11], v[226:227], v[110:111] op_sel:[0,1,0]
	v_pk_fma_f32 v[82:83], v[8:9], v[226:227], v[232:233] op_sel:[0,1,0]
	v_pk_fma_f32 v[226:227], v[74:75], v[222:223], v[112:113] op_sel:[0,1,0]
	v_pk_fma_f32 v[80:81], v[6:7], v[228:229], v[80:81] op_sel_hi:[1,0,1]
	v_pk_fma_f32 v[110:111], v[4:5], v[228:229], v[82:83] op_sel_hi:[1,0,1]
	v_mov_b32_e32 v112, v229
	v_pk_fma_f32 v[82:83], v[2:3], v[112:113], v[80:81] op_sel_hi:[1,0,1]
	v_pk_fma_f32 v[80:81], v[0:1], v[112:113], v[110:111] op_sel_hi:[1,0,1]
	v_mov_b32_e32 v110, v225
	global_load_dwordx4 v[28:31], v[20:21], off nt
	s_nop 0
	global_load_dwordx4 v[20:23], v[22:23], off nt
	v_pk_fma_f32 v[114:115], v[72:73], v[222:223], v[114:115] op_sel:[0,1,0]
	v_pk_fma_f32 v[116:117], v[74:75], v[224:225], v[116:117] op_sel_hi:[1,0,1]
	v_pk_fma_f32 v[118:119], v[72:73], v[224:225], v[118:119] op_sel_hi:[1,0,1]
	v_pk_fma_f32 v[120:121], v[74:75], v[110:111], v[120:121] op_sel_hi:[1,0,1]
	v_pk_fma_f32 v[122:123], v[72:73], v[110:111], v[122:123] op_sel_hi:[1,0,1]
	s_mov_b32 s0, 0xb660000
	ds_read_b128 v[72:75], v195
	ds_read_b128 v[110:113], v195 offset:4096
	v_add_co_u32_e32 v222, vcc, s0, v108
	s_mov_b32 s0, 0xb662000
	s_nop 0
	v_addc_co_u32_e32 v223, vcc, 0, v109, vcc
	global_store_dwordx4 v[222:223], v[80:83], off nt
	s_waitcnt vmcnt(23) lgkmcnt(1)
	v_pk_fma_f32 v[222:223], v[66:67], v[72:73], v[234:235] op_sel_hi:[1,0,1]
	v_pk_fma_f32 v[224:225], v[64:65], v[72:73], v[236:237] op_sel_hi:[1,0,1]
	v_mov_b32_e32 v80, v231
	v_pk_mul_f32 v[82:83], v[66:67], v[80:81] op_sel_hi:[1,0]
	v_pk_mul_f32 v[80:81], v[64:65], v[80:81] op_sel_hi:[1,0]
	s_waitcnt lgkmcnt(0)
	v_pk_fma_f32 v[82:83], v[14:15], v[110:111], v[82:83] op_sel_hi:[1,0,1]
	v_pk_fma_f32 v[80:81], v[12:13], v[110:111], v[80:81] op_sel_hi:[1,0,1]
	v_pk_fma_f32 v[82:83], v[10:11], v[110:111], v[82:83] op_sel:[0,1,0]
	v_pk_fma_f32 v[226:227], v[66:67], v[72:73], v[226:227] op_sel:[0,1,0]
	v_pk_fma_f32 v[228:229], v[64:65], v[72:73], v[114:115] op_sel:[0,1,0]
	v_pk_fma_f32 v[72:73], v[6:7], v[112:113], v[82:83] op_sel_hi:[1,0,1]
	v_pk_fma_f32 v[230:231], v[66:67], v[74:75], v[116:117] op_sel_hi:[1,0,1]
	v_pk_fma_f32 v[118:119], v[64:65], v[74:75], v[118:119] op_sel_hi:[1,0,1]
	v_mov_b32_e32 v74, v113
	v_pk_fma_f32 v[80:81], v[8:9], v[110:111], v[80:81] op_sel:[0,1,0]
	v_pk_fma_f32 v[82:83], v[2:3], v[74:75], v[72:73] op_sel_hi:[1,0,1]
	v_mov_b32_e32 v72, v75
	v_pk_fma_f32 v[80:81], v[4:5], v[112:113], v[80:81] op_sel_hi:[1,0,1]
	v_pk_fma_f32 v[122:123], v[64:65], v[72:73], v[122:123] op_sel_hi:[1,0,1]
	ds_read_b128 v[110:113], v196
	ds_read_b128 v[114:117], v196 offset:4096
	ds_read2_b32 v[64:65], v107 offset0:200 offset1:204
	v_pk_fma_f32 v[120:121], v[66:67], v[72:73], v[120:121] op_sel_hi:[1,0,1]
	v_add_co_u32_e32 v66, vcc, s0, v108
	v_pk_fma_f32 v[80:81], v[0:1], v[74:75], v[80:81] op_sel_hi:[1,0,1]
	s_nop 0
	v_addc_co_u32_e32 v67, vcc, 0, v109, vcc
	global_store_dwordx4 v[66:67], v[80:83], off nt
	s_waitcnt vmcnt(23) lgkmcnt(0)
; __device__ __forceinline__ void gla_sample_unit(const Args& a, unsigned char* lds, int unit, int tid) {
;     ...
;     f32x4 sb[2][8];
; #pragma unroll
;     for (int i = 0; i < 8; ++i) sb[0][i] = *(const f32x4*)(S0 + (size_t)(i * 4 + kq) * 512 + vc);
; #pragma unroll
;     for (int g = 0; g < 8; ++g) {
;         if (g + 1 < 8) {
; #pragma unroll
;             for (int i = 0; i < 8; ++i) sb[(g + 1) & 1][i] = *(const f32x4*)(S0 + (size_t)(((g + 1) * 8 + i) * 4 + kq) * 512 + vc); }
; #pragma unroll
;         for (int i = 0; i < 8; ++i) { const int k = (g * 8 + i) * 4 + kq; const f32x4 s = sb[g & 1][i];
;             const f32x4 qv = *(const f32x4*)(Q4 + k * 4), kd = *(const f32x4*)(KD4 + k * 4); const float dec = DECS[k];
;             f32x4 sn = s * dec;
; #pragma unroll
;             for (int t = 0; t < 4; ++t) { sn += vr[t] * kd[t]; o[t] += s * qv[t]; }
;             *(f32x4*)(SN + (size_t)k * 512 + vc) = sn; } }
	v_pk_mul_f32 v[66:67], v[58:59], v[64:65] op_sel_hi:[1,0]
	v_pk_mul_f32 v[72:73], v[56:57], v[64:65] op_sel_hi:[1,0]
	v_pk_fma_f32 v[74:75], v[14:15], v[114:115], v[66:67] op_sel_hi:[1,0,1]
	v_pk_fma_f32 v[80:81], v[12:13], v[114:115], v[72:73] op_sel_hi:[1,0,1]
	v_pk_fma_f32 v[82:83], v[10:11], v[114:115], v[74:75] op_sel:[0,1,0]
	v_pk_fma_f32 v[114:115], v[8:9], v[114:115], v[80:81] op_sel:[0,1,0]
	v_pk_fma_f32 v[66:67], v[58:59], v[110:111], v[222:223] op_sel_hi:[1,0,1]
	v_pk_fma_f32 v[222:223], v[6:7], v[116:117], v[82:83] op_sel_hi:[1,0,1]
	v_pk_fma_f32 v[114:115], v[4:5], v[116:117], v[114:115] op_sel_hi:[1,0,1]
	v_mov_b32_e32 v64, v117
	v_pk_fma_f32 v[116:117], v[2:3], v[64:65], v[222:223] op_sel_hi:[1,0,1]
	v_pk_fma_f32 v[114:115], v[0:1], v[64:65], v[114:115] op_sel_hi:[1,0,1]
	v_mov_b32_e32 v64, v113
	v_pk_fma_f32 v[72:73], v[56:57], v[110:111], v[224:225] op_sel_hi:[1,0,1]
	v_pk_fma_f32 v[74:75], v[58:59], v[110:111], v[226:227] op_sel:[0,1,0]
	v_pk_fma_f32 v[80:81], v[56:57], v[110:111], v[228:229] op_sel:[0,1,0]
	v_pk_fma_f32 v[82:83], v[58:59], v[112:113], v[230:231] op_sel_hi:[1,0,1]
	v_pk_fma_f32 v[110:111], v[56:57], v[112:113], v[118:119] op_sel_hi:[1,0,1]
	v_pk_fma_f32 v[58:59], v[58:59], v[64:65], v[120:121] op_sel_hi:[1,0,1]
	ds_read_b128 v[118:121], v197
	ds_read_b128 v[222:225], v197 offset:4096
	s_mov_b32 s0, 0xb664000
	v_add_co_u32_e32 v112, vcc, s0, v108
	v_pk_fma_f32 v[56:57], v[56:57], v[64:65], v[122:123] op_sel_hi:[1,0,1]
	s_nop 0
	v_addc_co_u32_e32 v113, vcc, 0, v109, vcc
	v_mov_b32_e32 v64, v65
	global_store_dwordx4 v[112:113], v[114:117], off nt
	s_waitcnt vmcnt(23)
	v_pk_mul_f32 v[112:113], v[50:51], v[64:65] op_sel_hi:[1,0]
	v_pk_mul_f32 v[64:65], v[48:49], v[64:65] op_sel_hi:[1,0]
	s_waitcnt lgkmcnt(0)
	v_pk_fma_f32 v[112:113], v[14:15], v[222:223], v[112:113] op_sel_hi:[1,0,1]
	v_pk_fma_f32 v[64:65], v[12:13], v[222:223], v[64:65] op_sel_hi:[1,0,1]
	v_pk_fma_f32 v[114:115], v[50:51], v[118:119], v[66:67] op_sel_hi:[1,0,1]
	v_pk_fma_f32 v[66:67], v[10:11], v[222:223], v[112:113] op_sel:[0,1,0]
	v_pk_fma_f32 v[64:65], v[8:9], v[222:223], v[64:65] op_sel:[0,1,0]
	v_pk_fma_f32 v[66:67], v[6:7], v[224:225], v[66:67] op_sel_hi:[1,0,1]
	v_pk_fma_f32 v[64:65], v[4:5], v[224:225], v[64:65] op_sel_hi:[1,0,1]
	v_mov_b32_e32 v112, v225
	v_pk_fma_f32 v[66:67], v[2:3], v[112:113], v[66:67] op_sel_hi:[1,0,1]
	v_pk_fma_f32 v[64:65], v[0:1], v[112:113], v[64:65] op_sel_hi:[1,0,1]
	v_mov_b32_e32 v112, v121
	v_pk_fma_f32 v[72:73], v[48:49], v[118:119], v[72:73] op_sel_hi:[1,0,1]
	v_pk_fma_f32 v[74:75], v[50:51], v[118:119], v[74:75] op_sel:[0,1,0]
	v_pk_fma_f32 v[80:81], v[48:49], v[118:119], v[80:81] op_sel:[0,1,0]
	v_pk_fma_f32 v[82:83], v[50:51], v[120:121], v[82:83] op_sel_hi:[1,0,1]
	v_pk_fma_f32 v[110:111], v[48:49], v[120:121], v[110:111] op_sel_hi:[1,0,1]
	v_pk_fma_f32 v[116:117], v[50:51], v[112:113], v[58:59] op_sel_hi:[1,0,1]
	v_pk_fma_f32 v[112:113], v[48:49], v[112:113], v[56:57] op_sel_hi:[1,0,1]
	ds_read_b128 v[48:51], v198
	ds_read_b128 v[56:59], v198 offset:4096
	ds_read2_b32 v[118:119], v107 offset0:208 offset1:212
	s_mov_b32 s0, 0xb666000
	v_add_co_u32_e32 v120, vcc, s0, v108
	s_waitcnt vmcnt(22) lgkmcnt(2)
	v_pk_fma_f32 v[114:115], v[42:43], v[48:49], v[114:115] op_sel_hi:[1,0,1]
	v_addc_co_u32_e32 v121, vcc, 0, v109, vcc
	global_store_dwordx4 v[120:121], v[64:67], off nt
	v_pk_fma_f32 v[72:73], v[40:41], v[48:49], v[72:73] op_sel_hi:[1,0,1]
	s_waitcnt lgkmcnt(0)
	v_pk_mul_f32 v[64:65], v[42:43], v[118:119] op_sel_hi:[1,0]
	v_pk_mul_f32 v[66:67], v[40:41], v[118:119] op_sel_hi:[1,0]
	v_pk_fma_f32 v[64:65], v[14:15], v[56:57], v[64:65] op_sel_hi:[1,0,1]
	v_pk_fma_f32 v[66:67], v[12:13], v[56:57], v[66:67] op_sel_hi:[1,0,1]
	v_pk_fma_f32 v[64:65], v[10:11], v[56:57], v[64:65] op_sel:[0,1,0]
	v_pk_fma_f32 v[56:57], v[8:9], v[56:57], v[66:67] op_sel:[0,1,0]
	v_pk_fma_f32 v[66:67], v[42:43], v[48:49], v[74:75] op_sel:[0,1,0]
	v_pk_fma_f32 v[74:75], v[40:41], v[48:49], v[80:81] op_sel:[0,1,0]
	v_pk_fma_f32 v[48:49], v[6:7], v[58:59], v[64:65] op_sel_hi:[1,0,1]
	v_pk_fma_f32 v[64:65], v[42:43], v[50:51], v[82:83] op_sel_hi:[1,0,1]
	v_pk_fma_f32 v[80:81], v[40:41], v[50:51], v[110:111] op_sel_hi:[1,0,1]
	v_mov_b32_e32 v50, v59
	v_pk_fma_f32 v[56:57], v[4:5], v[58:59], v[56:57] op_sel_hi:[1,0,1]
	v_pk_fma_f32 v[58:59], v[2:3], v[50:51], v[48:49] op_sel_hi:[1,0,1]
	v_mov_b32_e32 v48, v51
	v_pk_fma_f32 v[56:57], v[0:1], v[50:51], v[56:57] op_sel_hi:[1,0,1]
	v_pk_fma_f32 v[82:83], v[42:43], v[48:49], v[116:117] op_sel_hi:[1,0,1]
	v_pk_fma_f32 v[110:111], v[40:41], v[48:49], v[112:113] op_sel_hi:[1,0,1]
	ds_read_b128 v[40:43], v199
	ds_read_b128 v[48:51], v199 offset:4096
	v_add_co_u32_e32 v112, vcc, s34, v108
	s_waitcnt vmcnt(22) lgkmcnt(1)
	v_pk_fma_f32 v[72:73], v[32:33], v[40:41], v[72:73] op_sel_hi:[1,0,1]
	v_addc_co_u32_e32 v113, vcc, 0, v109, vcc
	global_store_dwordx4 v[112:113], v[56:59], off nt
	v_pk_fma_f32 v[112:113], v[34:35], v[40:41], v[114:115] op_sel_hi:[1,0,1]
	s_nop 0
	v_mov_b32_e32 v56, v119
	v_pk_mul_f32 v[58:59], v[34:35], v[56:57] op_sel_hi:[1,0]
	v_pk_mul_f32 v[56:57], v[32:33], v[56:57] op_sel_hi:[1,0]
	s_waitcnt lgkmcnt(0)
; __device__ __forceinline__ void gla_sample_unit(const Args& a, unsigned char* lds, int unit, int tid) {
;     ...
;     f32x4 sb[2][8];
; #pragma unroll
;     for (int i = 0; i < 8; ++i) sb[0][i] = *(const f32x4*)(S0 + (size_t)(i * 4 + kq) * 512 + vc);
; #pragma unroll
;     for (int g = 0; g < 8; ++g) {
;         if (g + 1 < 8) {
; #pragma unroll
;             for (int i = 0; i < 8; ++i) sb[(g + 1) & 1][i] = *(const f32x4*)(S0 + (size_t)(((g + 1) * 8 + i) * 4 + kq) * 512 + vc); }
; #pragma unroll
;         for (int i = 0; i < 8; ++i) { const int k = (g * 8 + i) * 4 + kq; const f32x4 s = sb[g & 1][i];
;             const f32x4 qv = *(const f32x4*)(Q4 + k * 4), kd = *(const f32x4*)(KD4 + k * 4); const float dec = DECS[k];
;             f32x4 sn = s * dec;
; #pragma unroll
;             for (int t = 0; t < 4; ++t) { sn += vr[t] * kd[t]; o[t] += s * qv[t]; }
;             *(f32x4*)(SN + (size_t)k * 512 + vc) = sn; } }
	v_pk_fma_f32 v[58:59], v[14:15], v[48:49], v[58:59] op_sel_hi:[1,0,1]
	v_pk_fma_f32 v[56:57], v[12:13], v[48:49], v[56:57] op_sel_hi:[1,0,1]
	v_pk_fma_f32 v[58:59], v[10:11], v[48:49], v[58:59] op_sel:[0,1,0]
	v_pk_fma_f32 v[48:49], v[8:9], v[48:49], v[56:57] op_sel:[0,1,0]
	v_pk_fma_f32 v[56:57], v[34:35], v[40:41], v[66:67] op_sel:[0,1,0]
	v_pk_fma_f32 v[66:67], v[32:33], v[40:41], v[74:75] op_sel:[0,1,0]
	v_pk_fma_f32 v[40:41], v[6:7], v[50:51], v[58:59] op_sel_hi:[1,0,1]
	v_pk_fma_f32 v[58:59], v[34:35], v[42:43], v[64:65] op_sel_hi:[1,0,1]
	v_pk_fma_f32 v[64:65], v[32:33], v[42:43], v[80:81] op_sel_hi:[1,0,1]
	v_mov_b32_e32 v42, v51
	v_pk_fma_f32 v[48:49], v[4:5], v[50:51], v[48:49] op_sel_hi:[1,0,1]
	v_pk_fma_f32 v[50:51], v[2:3], v[42:43], v[40:41] op_sel_hi:[1,0,1]
	v_mov_b32_e32 v40, v43
	v_pk_fma_f32 v[48:49], v[0:1], v[42:43], v[48:49] op_sel_hi:[1,0,1]
	v_pk_fma_f32 v[74:75], v[34:35], v[40:41], v[82:83] op_sel_hi:[1,0,1]
	v_pk_fma_f32 v[80:81], v[32:33], v[40:41], v[110:111] op_sel_hi:[1,0,1]
	ds_read_b128 v[32:35], v200
	ds_read_b128 v[40:43], v200 offset:4096
	ds_read2_b32 v[82:83], v107 offset0:216 offset1:220
	v_add_co_u32_e32 v110, vcc, s35, v108
	s_waitcnt vmcnt(22) lgkmcnt(2)
	v_pk_fma_f32 v[72:73], v[24:25], v[32:33], v[72:73] op_sel_hi:[1,0,1]
	v_addc_co_u32_e32 v111, vcc, 0, v109, vcc
	global_store_dwordx4 v[110:111], v[48:51], off nt
	v_pk_fma_f32 v[110:111], v[26:27], v[32:33], v[112:113] op_sel_hi:[1,0,1]
	s_waitcnt lgkmcnt(0)
	v_pk_mul_f32 v[48:49], v[26:27], v[82:83] op_sel_hi:[1,0]
	v_pk_mul_f32 v[50:51], v[24:25], v[82:83] op_sel_hi:[1,0]
	v_pk_fma_f32 v[48:49], v[14:15], v[40:41], v[48:49] op_sel_hi:[1,0,1]
	v_pk_fma_f32 v[50:51], v[12:13], v[40:41], v[50:51] op_sel_hi:[1,0,1]
	v_pk_fma_f32 v[48:49], v[10:11], v[40:41], v[48:49] op_sel:[0,1,0]
	v_pk_fma_f32 v[40:41], v[8:9], v[40:41], v[50:51] op_sel:[0,1,0]
	v_pk_fma_f32 v[50:51], v[26:27], v[32:33], v[56:57] op_sel:[0,1,0]
	v_pk_fma_f32 v[56:57], v[24:25], v[32:33], v[66:67] op_sel:[0,1,0]
	v_pk_fma_f32 v[32:33], v[6:7], v[42:43], v[48:49] op_sel_hi:[1,0,1]
	v_pk_fma_f32 v[48:49], v[26:27], v[34:35], v[58:59] op_sel_hi:[1,0,1]
	v_pk_fma_f32 v[58:59], v[24:25], v[34:35], v[64:65] op_sel_hi:[1,0,1]
	v_mov_b32_e32 v34, v43
	v_pk_fma_f32 v[40:41], v[4:5], v[42:43], v[40:41] op_sel_hi:[1,0,1]
	v_pk_fma_f32 v[42:43], v[2:3], v[34:35], v[32:33] op_sel_hi:[1,0,1]
	v_mov_b32_e32 v32, v35
	v_pk_fma_f32 v[40:41], v[0:1], v[34:35], v[40:41] op_sel_hi:[1,0,1]
	v_pk_fma_f32 v[64:65], v[26:27], v[32:33], v[74:75] op_sel_hi:[1,0,1]
	v_pk_fma_f32 v[66:67], v[24:25], v[32:33], v[80:81] op_sel_hi:[1,0,1]
	ds_read_b128 v[24:27], v201
	ds_read_b128 v[32:35], v201 offset:4096
	v_add_co_u32_e32 v74, vcc, s36, v108
	s_waitcnt vmcnt(22) lgkmcnt(1)
	v_pk_fma_f32 v[72:73], v[16:17], v[24:25], v[72:73] op_sel_hi:[1,0,1]
	v_addc_co_u32_e32 v75, vcc, 0, v109, vcc
	global_store_dwordx4 v[74:75], v[40:43], off nt
	v_pk_fma_f32 v[74:75], v[18:19], v[24:25], v[110:111] op_sel_hi:[1,0,1]
	s_nop 0
	v_mov_b32_e32 v40, v83
	v_pk_mul_f32 v[42:43], v[18:19], v[40:41] op_sel_hi:[1,0]
	v_pk_mul_f32 v[40:41], v[16:17], v[40:41] op_sel_hi:[1,0]
	s_waitcnt lgkmcnt(0)
	v_pk_fma_f32 v[42:43], v[14:15], v[32:33], v[42:43] op_sel_hi:[1,0,1]
	v_pk_fma_f32 v[40:41], v[12:13], v[32:33], v[40:41] op_sel_hi:[1,0,1]
	v_pk_fma_f32 v[42:43], v[10:11], v[32:33], v[42:43] op_sel:[0,1,0]
	v_pk_fma_f32 v[32:33], v[8:9], v[32:33], v[40:41] op_sel:[0,1,0]
	v_pk_fma_f32 v[40:41], v[18:19], v[24:25], v[50:51] op_sel:[0,1,0]
	v_pk_fma_f32 v[50:51], v[16:17], v[24:25], v[56:57] op_sel:[0,1,0]
	v_pk_fma_f32 v[24:25], v[6:7], v[34:35], v[42:43] op_sel_hi:[1,0,1]
	v_pk_fma_f32 v[42:43], v[18:19], v[26:27], v[48:49] op_sel_hi:[1,0,1]
	v_pk_fma_f32 v[48:49], v[16:17], v[26:27], v[58:59] op_sel_hi:[1,0,1]
	v_mov_b32_e32 v26, v35
	v_pk_fma_f32 v[32:33], v[4:5], v[34:35], v[32:33] op_sel_hi:[1,0,1]
	v_pk_fma_f32 v[34:35], v[2:3], v[26:27], v[24:25] op_sel_hi:[1,0,1]
	v_mov_b32_e32 v24, v27
	v_pk_fma_f32 v[32:33], v[0:1], v[26:27], v[32:33] op_sel_hi:[1,0,1]
	v_pk_fma_f32 v[56:57], v[18:19], v[24:25], v[64:65] op_sel_hi:[1,0,1]
	v_pk_fma_f32 v[58:59], v[16:17], v[24:25], v[66:67] op_sel_hi:[1,0,1]
	ds_read_b128 v[16:19], v202
	ds_read_b128 v[24:27], v202 offset:4096
	ds_read2_b32 v[64:65], v107 offset0:224 offset1:228
	v_add_co_u32_e32 v66, vcc, s37, v108
	s_waitcnt vmcnt(14) lgkmcnt(2)
	v_pk_fma_f32 v[72:73], v[76:77], v[16:17], v[72:73] op_sel_hi:[1,0,1]
	v_addc_co_u32_e32 v67, vcc, 0, v109, vcc
	global_store_dwordx4 v[66:67], v[32:35], off nt
	v_pk_fma_f32 v[66:67], v[78:79], v[16:17], v[74:75] op_sel_hi:[1,0,1]
	v_pk_fma_f32 v[40:41], v[78:79], v[16:17], v[40:41] op_sel:[0,1,0]
	s_waitcnt lgkmcnt(0)
	v_pk_mul_f32 v[32:33], v[78:79], v[64:65] op_sel_hi:[1,0]
	v_pk_mul_f32 v[34:35], v[76:77], v[64:65] op_sel_hi:[1,0]
	v_pk_fma_f32 v[32:33], v[14:15], v[24:25], v[32:33] op_sel_hi:[1,0,1]
	v_pk_fma_f32 v[34:35], v[12:13], v[24:25], v[34:35] op_sel_hi:[1,0,1]
	v_pk_fma_f32 v[32:33], v[10:11], v[24:25], v[32:33] op_sel:[0,1,0]
	v_pk_fma_f32 v[24:25], v[8:9], v[24:25], v[34:35] op_sel:[0,1,0]
	v_pk_fma_f32 v[50:51], v[76:77], v[16:17], v[50:51] op_sel:[0,1,0]
	v_pk_fma_f32 v[16:17], v[6:7], v[26:27], v[32:33] op_sel_hi:[1,0,1]
	v_pk_fma_f32 v[42:43], v[78:79], v[18:19], v[42:43] op_sel_hi:[1,0,1]
	v_pk_fma_f32 v[48:49], v[76:77], v[18:19], v[48:49] op_sel_hi:[1,0,1]
	v_mov_b32_e32 v18, v27
	v_pk_fma_f32 v[24:25], v[4:5], v[26:27], v[24:25] op_sel_hi:[1,0,1]
	v_pk_fma_f32 v[26:27], v[2:3], v[18:19], v[16:17] op_sel_hi:[1,0,1]
	v_mov_b32_e32 v16, v19
	v_pk_fma_f32 v[24:25], v[0:1], v[18:19], v[24:25] op_sel_hi:[1,0,1]
	v_pk_fma_f32 v[56:57], v[78:79], v[16:17], v[56:57] op_sel_hi:[1,0,1]
	v_pk_fma_f32 v[58:59], v[76:77], v[16:17], v[58:59] op_sel_hi:[1,0,1]
	ds_read_b128 v[16:19], v203
	ds_read_b128 v[32:35], v203 offset:4096
	v_add_co_u32_e32 v74, vcc, s38, v108
	s_waitcnt vmcnt(14) lgkmcnt(1)
; __device__ __forceinline__ void gla_sample_unit(const Args& a, unsigned char* lds, int unit, int tid) {
;     ...
;     f32x4 sb[2][8];
; #pragma unroll
;     for (int i = 0; i < 8; ++i) sb[0][i] = *(const f32x4*)(S0 + (size_t)(i * 4 + kq) * 512 + vc);
; #pragma unroll
;     for (int g = 0; g < 8; ++g) {
;         if (g + 1 < 8) {
; #pragma unroll
;             for (int i = 0; i < 8; ++i) sb[(g + 1) & 1][i] = *(const f32x4*)(S0 + (size_t)(((g + 1) * 8 + i) * 4 + kq) * 512 + vc); }
; #pragma unroll
;         for (int i = 0; i < 8; ++i) { const int k = (g * 8 + i) * 4 + kq; const f32x4 s = sb[g & 1][i];
;             const f32x4 qv = *(const f32x4*)(Q4 + k * 4), kd = *(const f32x4*)(KD4 + k * 4); const float dec = DECS[k];
;             f32x4 sn = s * dec;
; #pragma unroll
;             for (int t = 0; t < 4; ++t) { sn += vr[t] * kd[t]; o[t] += s * qv[t]; }
;             *(f32x4*)(SN + (size_t)k * 512 + vc) = sn; } }
	v_pk_fma_f32 v[40:41], v[70:71], v[16:17], v[40:41] op_sel:[0,1,0]
	v_addc_co_u32_e32 v75, vcc, 0, v109, vcc
	global_store_dwordx4 v[74:75], v[24:27], off nt
	v_pk_fma_f32 v[50:51], v[68:69], v[16:17], v[50:51] op_sel:[0,1,0]
	v_pk_fma_f32 v[42:43], v[70:71], v[18:19], v[42:43] op_sel_hi:[1,0,1]
	v_mov_b32_e32 v24, v65
	v_pk_mul_f32 v[26:27], v[70:71], v[24:25] op_sel_hi:[1,0]
	v_pk_mul_f32 v[24:25], v[68:69], v[24:25] op_sel_hi:[1,0]
	s_waitcnt lgkmcnt(0)
	v_pk_fma_f32 v[26:27], v[14:15], v[32:33], v[26:27] op_sel_hi:[1,0,1]
	v_pk_fma_f32 v[24:25], v[12:13], v[32:33], v[24:25] op_sel_hi:[1,0,1]
	v_pk_fma_f32 v[26:27], v[10:11], v[32:33], v[26:27] op_sel:[0,1,0]
	v_pk_fma_f32 v[64:65], v[70:71], v[16:17], v[66:67] op_sel_hi:[1,0,1]
	v_pk_fma_f32 v[66:67], v[68:69], v[16:17], v[72:73] op_sel_hi:[1,0,1]
	v_pk_fma_f32 v[24:25], v[8:9], v[32:33], v[24:25] op_sel:[0,1,0]
	v_pk_fma_f32 v[16:17], v[6:7], v[34:35], v[26:27] op_sel_hi:[1,0,1]
	v_pk_fma_f32 v[48:49], v[68:69], v[18:19], v[48:49] op_sel_hi:[1,0,1]
	v_mov_b32_e32 v18, v35
	v_pk_fma_f32 v[24:25], v[4:5], v[34:35], v[24:25] op_sel_hi:[1,0,1]
	v_pk_fma_f32 v[26:27], v[2:3], v[18:19], v[16:17] op_sel_hi:[1,0,1]
	v_mov_b32_e32 v16, v19
	v_pk_fma_f32 v[24:25], v[0:1], v[18:19], v[24:25] op_sel_hi:[1,0,1]
	v_pk_fma_f32 v[56:57], v[70:71], v[16:17], v[56:57] op_sel_hi:[1,0,1]
	v_pk_fma_f32 v[58:59], v[68:69], v[16:17], v[58:59] op_sel_hi:[1,0,1]
	ds_read_b128 v[16:19], v204
	ds_read_b128 v[32:35], v204 offset:4096
	ds_read2_b32 v[68:69], v107 offset0:232 offset1:236
	v_add_co_u32_e32 v70, vcc, s39, v108
	s_waitcnt vmcnt(14) lgkmcnt(2)
	v_pk_fma_f32 v[64:65], v[62:63], v[16:17], v[64:65] op_sel_hi:[1,0,1]
	v_addc_co_u32_e32 v71, vcc, 0, v109, vcc
	global_store_dwordx4 v[70:71], v[24:27], off nt
	v_pk_fma_f32 v[66:67], v[60:61], v[16:17], v[66:67] op_sel_hi:[1,0,1]
	v_pk_fma_f32 v[40:41], v[62:63], v[16:17], v[40:41] op_sel:[0,1,0]
	s_waitcnt lgkmcnt(0)
	v_pk_mul_f32 v[24:25], v[62:63], v[68:69] op_sel_hi:[1,0]
	v_pk_mul_f32 v[26:27], v[60:61], v[68:69] op_sel_hi:[1,0]
	v_pk_fma_f32 v[24:25], v[14:15], v[32:33], v[24:25] op_sel_hi:[1,0,1]
	v_pk_fma_f32 v[26:27], v[12:13], v[32:33], v[26:27] op_sel_hi:[1,0,1]
	v_pk_fma_f32 v[24:25], v[10:11], v[32:33], v[24:25] op_sel:[0,1,0]
	v_pk_fma_f32 v[26:27], v[8:9], v[32:33], v[26:27] op_sel:[0,1,0]
	v_pk_fma_f32 v[50:51], v[60:61], v[16:17], v[50:51] op_sel:[0,1,0]
	v_pk_fma_f32 v[16:17], v[6:7], v[34:35], v[24:25] op_sel_hi:[1,0,1]
	v_pk_fma_f32 v[42:43], v[62:63], v[18:19], v[42:43] op_sel_hi:[1,0,1]
	v_pk_fma_f32 v[48:49], v[60:61], v[18:19], v[48:49] op_sel_hi:[1,0,1]
	v_mov_b32_e32 v18, v35
	v_pk_fma_f32 v[24:25], v[4:5], v[34:35], v[26:27] op_sel_hi:[1,0,1]
	v_pk_fma_f32 v[26:27], v[2:3], v[18:19], v[16:17] op_sel_hi:[1,0,1]
	v_mov_b32_e32 v16, v19
	v_pk_fma_f32 v[24:25], v[0:1], v[18:19], v[24:25] op_sel_hi:[1,0,1]
	v_pk_fma_f32 v[56:57], v[62:63], v[16:17], v[56:57] op_sel_hi:[1,0,1]
	v_pk_fma_f32 v[58:59], v[60:61], v[16:17], v[58:59] op_sel_hi:[1,0,1]
	ds_read_b128 v[16:19], v205
	ds_read_b128 v[32:35], v205 offset:4096
	v_add_co_u32_e32 v60, vcc, s40, v108
	s_waitcnt vmcnt(14) lgkmcnt(1)
	v_pk_fma_f32 v[62:63], v[52:53], v[16:17], v[66:67] op_sel_hi:[1,0,1]
	v_addc_co_u32_e32 v61, vcc, 0, v109, vcc
	global_store_dwordx4 v[60:61], v[24:27], off nt
	v_pk_fma_f32 v[60:61], v[54:55], v[16:17], v[64:65] op_sel_hi:[1,0,1]
	v_pk_fma_f32 v[40:41], v[54:55], v[16:17], v[40:41] op_sel:[0,1,0]
	v_mov_b32_e32 v24, v69
	v_pk_mul_f32 v[26:27], v[54:55], v[24:25] op_sel_hi:[1,0]
	v_pk_mul_f32 v[24:25], v[52:53], v[24:25] op_sel_hi:[1,0]
	s_waitcnt lgkmcnt(0)
	v_pk_fma_f32 v[26:27], v[14:15], v[32:33], v[26:27] op_sel_hi:[1,0,1]
	v_pk_fma_f32 v[24:25], v[12:13], v[32:33], v[24:25] op_sel_hi:[1,0,1]
	v_pk_fma_f32 v[26:27], v[10:11], v[32:33], v[26:27] op_sel:[0,1,0]
	v_pk_fma_f32 v[24:25], v[8:9], v[32:33], v[24:25] op_sel:[0,1,0]
	v_pk_fma_f32 v[50:51], v[52:53], v[16:17], v[50:51] op_sel:[0,1,0]
	v_pk_fma_f32 v[16:17], v[6:7], v[34:35], v[26:27] op_sel_hi:[1,0,1]
	v_pk_fma_f32 v[42:43], v[54:55], v[18:19], v[42:43] op_sel_hi:[1,0,1]
	v_pk_fma_f32 v[48:49], v[52:53], v[18:19], v[48:49] op_sel_hi:[1,0,1]
	v_mov_b32_e32 v18, v35
	v_pk_fma_f32 v[24:25], v[4:5], v[34:35], v[24:25] op_sel_hi:[1,0,1]
	v_pk_fma_f32 v[26:27], v[2:3], v[18:19], v[16:17] op_sel_hi:[1,0,1]
	v_mov_b32_e32 v16, v19
	v_pk_fma_f32 v[24:25], v[0:1], v[18:19], v[24:25] op_sel_hi:[1,0,1]
	v_pk_fma_f32 v[54:55], v[54:55], v[16:17], v[56:57] op_sel_hi:[1,0,1]
	v_pk_fma_f32 v[52:53], v[52:53], v[16:17], v[58:59] op_sel_hi:[1,0,1]
	ds_read_b128 v[16:19], v206
	ds_read_b128 v[32:35], v206 offset:4096
	ds_read2_b32 v[56:57], v107 offset0:240 offset1:244
	v_add_co_u32_e32 v58, vcc, s41, v108
	s_waitcnt vmcnt(14) lgkmcnt(2)
	v_pk_fma_f32 v[40:41], v[46:47], v[16:17], v[40:41] op_sel:[0,1,0]
	v_addc_co_u32_e32 v59, vcc, 0, v109, vcc
	global_store_dwordx4 v[58:59], v[24:27], off nt
	v_pk_fma_f32 v[58:59], v[46:47], v[16:17], v[60:61] op_sel_hi:[1,0,1]
	v_pk_fma_f32 v[60:61], v[44:45], v[16:17], v[62:63] op_sel_hi:[1,0,1]
	s_waitcnt lgkmcnt(0)
; __device__ __forceinline__ void gla_sample_unit(const Args& a, unsigned char* lds, int unit, int tid) {
;     ...
;     for (int g = 0; g < 8; ++g) {
;         if (g + 1 < 8) {
; #pragma unroll
;             for (int i = 0; i < 8; ++i) sb[(g + 1) & 1][i] = *(const f32x4*)(S0 + (size_t)(((g + 1) * 8 + i) * 4 + kq) * 512 + vc); }
; #pragma unroll
;         for (int i = 0; i < 8; ++i) { const int k = (g * 8 + i) * 4 + kq; const f32x4 s = sb[g & 1][i];
;             const f32x4 qv = *(const f32x4*)(Q4 + k * 4), kd = *(const f32x4*)(KD4 + k * 4); const float dec = DECS[k];
;             f32x4 sn = s * dec;
; #pragma unroll
;             for (int t = 0; t < 4; ++t) { sn += vr[t] * kd[t]; o[t] += s * qv[t]; }
;             *(f32x4*)(SN + (size_t)k * 512 + vc) = sn; } }
; #pragma unroll
;     for (int t = 0; t < 4; ++t) *(f32x4*)(ORED + (kq * 4 + t) * 512 + vc) = o[t];
;     __syncthreads();
	v_pk_mul_f32 v[24:25], v[46:47], v[56:57] op_sel_hi:[1,0]
	v_pk_mul_f32 v[26:27], v[44:45], v[56:57] op_sel_hi:[1,0]
	v_pk_fma_f32 v[24:25], v[14:15], v[32:33], v[24:25] op_sel_hi:[1,0,1]
	v_pk_fma_f32 v[26:27], v[12:13], v[32:33], v[26:27] op_sel_hi:[1,0,1]
	v_pk_fma_f32 v[24:25], v[10:11], v[32:33], v[24:25] op_sel:[0,1,0]
	v_pk_fma_f32 v[26:27], v[8:9], v[32:33], v[26:27] op_sel:[0,1,0]
	v_pk_fma_f32 v[50:51], v[44:45], v[16:17], v[50:51] op_sel:[0,1,0]
	v_pk_fma_f32 v[16:17], v[6:7], v[34:35], v[24:25] op_sel_hi:[1,0,1]
	v_pk_fma_f32 v[42:43], v[46:47], v[18:19], v[42:43] op_sel_hi:[1,0,1]
	v_pk_fma_f32 v[48:49], v[44:45], v[18:19], v[48:49] op_sel_hi:[1,0,1]
	v_mov_b32_e32 v18, v35
	v_pk_fma_f32 v[24:25], v[4:5], v[34:35], v[26:27] op_sel_hi:[1,0,1]
	v_pk_fma_f32 v[26:27], v[2:3], v[18:19], v[16:17] op_sel_hi:[1,0,1]
	v_mov_b32_e32 v16, v19
	v_pk_fma_f32 v[24:25], v[0:1], v[18:19], v[24:25] op_sel_hi:[1,0,1]
	v_pk_fma_f32 v[46:47], v[46:47], v[16:17], v[54:55] op_sel_hi:[1,0,1]
	v_pk_fma_f32 v[44:45], v[44:45], v[16:17], v[52:53] op_sel_hi:[1,0,1]
	ds_read_b128 v[16:19], v207
	ds_read_b128 v[32:35], v207 offset:4096
	v_add_co_u32_e32 v52, vcc, s42, v108
	s_waitcnt vmcnt(14) lgkmcnt(1)
	v_pk_fma_f32 v[54:55], v[36:37], v[16:17], v[60:61] op_sel_hi:[1,0,1]
	v_addc_co_u32_e32 v53, vcc, 0, v109, vcc
	global_store_dwordx4 v[52:53], v[24:27], off nt
	v_pk_fma_f32 v[52:53], v[38:39], v[16:17], v[58:59] op_sel_hi:[1,0,1]
	v_pk_fma_f32 v[40:41], v[38:39], v[16:17], v[40:41] op_sel:[0,1,0]
	v_mov_b32_e32 v24, v57
	v_pk_mul_f32 v[26:27], v[38:39], v[24:25] op_sel_hi:[1,0]
	v_pk_mul_f32 v[24:25], v[36:37], v[24:25] op_sel_hi:[1,0]
	s_waitcnt lgkmcnt(0)
	v_pk_fma_f32 v[26:27], v[14:15], v[32:33], v[26:27] op_sel_hi:[1,0,1]
	v_pk_fma_f32 v[24:25], v[12:13], v[32:33], v[24:25] op_sel_hi:[1,0,1]
	v_pk_fma_f32 v[26:27], v[10:11], v[32:33], v[26:27] op_sel:[0,1,0]
	v_pk_fma_f32 v[24:25], v[8:9], v[32:33], v[24:25] op_sel:[0,1,0]
	v_pk_fma_f32 v[50:51], v[36:37], v[16:17], v[50:51] op_sel:[0,1,0]
	v_pk_fma_f32 v[16:17], v[6:7], v[34:35], v[26:27] op_sel_hi:[1,0,1]
	v_pk_fma_f32 v[42:43], v[38:39], v[18:19], v[42:43] op_sel_hi:[1,0,1]
	v_pk_fma_f32 v[48:49], v[36:37], v[18:19], v[48:49] op_sel_hi:[1,0,1]
	v_mov_b32_e32 v18, v35
	v_pk_fma_f32 v[24:25], v[4:5], v[34:35], v[24:25] op_sel_hi:[1,0,1]
	v_pk_fma_f32 v[26:27], v[2:3], v[18:19], v[16:17] op_sel_hi:[1,0,1]
	v_mov_b32_e32 v16, v19
	v_pk_fma_f32 v[24:25], v[0:1], v[18:19], v[24:25] op_sel_hi:[1,0,1]
	v_pk_fma_f32 v[38:39], v[38:39], v[16:17], v[46:47] op_sel_hi:[1,0,1]
	v_pk_fma_f32 v[36:37], v[36:37], v[16:17], v[44:45] op_sel_hi:[1,0,1]
	ds_read_b128 v[16:19], v208
	ds_read_b128 v[32:35], v208 offset:4096
	ds_read2_b32 v[44:45], v107 offset0:248 offset1:252
	v_add_co_u32_e32 v46, vcc, s43, v108
	s_waitcnt vmcnt(14) lgkmcnt(2)
	v_pk_fma_f32 v[42:43], v[30:31], v[18:19], v[42:43] op_sel_hi:[1,0,1]
	v_addc_co_u32_e32 v47, vcc, 0, v109, vcc
	global_store_dwordx4 v[46:47], v[24:27], off nt
	v_pk_fma_f32 v[46:47], v[30:31], v[16:17], v[52:53] op_sel_hi:[1,0,1]
	v_pk_fma_f32 v[52:53], v[28:29], v[16:17], v[54:55] op_sel_hi:[1,0,1]
	s_waitcnt lgkmcnt(0)
	v_pk_mul_f32 v[24:25], v[30:31], v[44:45] op_sel_hi:[1,0]
	v_pk_mul_f32 v[26:27], v[28:29], v[44:45] op_sel_hi:[1,0]
	v_pk_fma_f32 v[24:25], v[14:15], v[32:33], v[24:25] op_sel_hi:[1,0,1]
	v_pk_fma_f32 v[26:27], v[12:13], v[32:33], v[26:27] op_sel_hi:[1,0,1]
	v_pk_fma_f32 v[24:25], v[10:11], v[32:33], v[24:25] op_sel:[0,1,0]
	v_pk_fma_f32 v[26:27], v[8:9], v[32:33], v[26:27] op_sel:[0,1,0]
	v_pk_fma_f32 v[32:33], v[30:31], v[16:17], v[40:41] op_sel:[0,1,0]
	v_pk_fma_f32 v[40:41], v[28:29], v[16:17], v[50:51] op_sel:[0,1,0]
	v_pk_fma_f32 v[16:17], v[6:7], v[34:35], v[24:25] op_sel_hi:[1,0,1]
	v_pk_fma_f32 v[48:49], v[28:29], v[18:19], v[48:49] op_sel_hi:[1,0,1]
	v_mov_b32_e32 v18, v35
	v_pk_fma_f32 v[24:25], v[4:5], v[34:35], v[26:27] op_sel_hi:[1,0,1]
	v_pk_fma_f32 v[26:27], v[2:3], v[18:19], v[16:17] op_sel_hi:[1,0,1]
	v_mov_b32_e32 v16, v19
	v_pk_fma_f32 v[24:25], v[0:1], v[18:19], v[24:25] op_sel_hi:[1,0,1]
	v_pk_fma_f32 v[34:35], v[30:31], v[16:17], v[38:39] op_sel_hi:[1,0,1]
	v_pk_fma_f32 v[36:37], v[28:29], v[16:17], v[36:37] op_sel_hi:[1,0,1]
	ds_read_b128 v[28:31], v209
	ds_read_b128 v[16:19], v209 offset:4096
	v_add_co_u32_e32 v38, vcc, s44, v108
	s_nop 1
	v_addc_co_u32_e32 v39, vcc, 0, v109, vcc
	global_store_dwordx4 v[38:39], v[24:27], off nt
	s_nop 1
	v_mov_b32_e32 v24, v45
	s_waitcnt vmcnt(15)
	v_pk_mul_f32 v[26:27], v[22:23], v[24:25] op_sel_hi:[1,0]
	v_pk_mul_f32 v[24:25], v[20:21], v[24:25] op_sel_hi:[1,0]
	s_waitcnt lgkmcnt(0)
	v_pk_fma_f32 v[26:27], v[14:15], v[16:17], v[26:27] op_sel_hi:[1,0,1]
	v_pk_fma_f32 v[24:25], v[12:13], v[16:17], v[24:25] op_sel_hi:[1,0,1]
	v_pk_fma_f32 v[26:27], v[10:11], v[16:17], v[26:27] op_sel:[0,1,0]
	v_pk_fma_f32 v[16:17], v[8:9], v[16:17], v[24:25] op_sel:[0,1,0]
	v_pk_fma_f32 v[24:25], v[6:7], v[18:19], v[26:27] op_sel_hi:[1,0,1]
	v_pk_fma_f32 v[16:17], v[4:5], v[18:19], v[16:17] op_sel_hi:[1,0,1]
	v_mov_b32_e32 v26, v19
	v_pk_fma_f32 v[16:17], v[0:1], v[26:27], v[16:17] op_sel_hi:[1,0,1]
	v_mov_b32_e32 v0, v31
	v_pk_fma_f32 v[12:13], v[20:21], v[28:29], v[52:53] op_sel_hi:[1,0,1]
	v_pk_fma_f32 v[8:9], v[20:21], v[28:29], v[40:41] op_sel:[0,1,0]
	v_pk_fma_f32 v[4:5], v[20:21], v[30:31], v[48:49] op_sel_hi:[1,0,1]
	v_pk_fma_f32 v[18:19], v[2:3], v[26:27], v[24:25] op_sel_hi:[1,0,1]
	v_pk_fma_f32 v[2:3], v[22:23], v[0:1], v[34:35] op_sel_hi:[1,0,1]
	v_pk_fma_f32 v[0:1], v[20:21], v[0:1], v[36:37] op_sel_hi:[1,0,1]
	v_add_co_u32_e32 v20, vcc, s45, v108
	v_pk_fma_f32 v[14:15], v[22:23], v[28:29], v[46:47] op_sel_hi:[1,0,1]
	v_pk_fma_f32 v[10:11], v[22:23], v[28:29], v[32:33] op_sel:[0,1,0]
	v_pk_fma_f32 v[6:7], v[22:23], v[30:31], v[42:43] op_sel_hi:[1,0,1]
	v_addc_co_u32_e32 v21, vcc, 0, v109, vcc
	global_store_dwordx4 v[20:21], v[16:19], off nt
	ds_write_b128 v210, v[12:15] offset:21632
	ds_write_b128 v210, v[8:11] offset:23680
	ds_write_b128 v210, v[4:7] offset:25728
	ds_write_b128 v210, v[0:3] offset:27776
	s_waitcnt lgkmcnt(0)
	s_barrier
; __device__ __forceinline__ void gla_sample_unit(const Args& a, unsigned char* lds, int unit, int tid) {
;     ...
;     { const int t = tid >> 7, v4 = (tid & 127) * 4; f32x4 ov = (f32x4){0.f, 0.f, 0.f, 0.f};
; #pragma unroll
;       for (int q = 0; q < 4; ++q) ov += *(const f32x4*)(ORED + (q * 4 + t) * 512 + v4);
; #pragma unroll
;       for (int m = 0; m < 4; ++m) ov += *(const f32x4*)(VS + m * 512 + v4) * AS[t * 4 + m];
;       float ss = (ov[0] * ov[0] + ov[1] * ov[1]) + (ov[2] * ov[2] + ov[3] * ov[3]); ss = wave_sum(ss);
;       if (lane == 0) RED[wave] = ss;
	ds_read_b128 v[0:3], v211 offset:21632
	ds_read_b128 v[4:7], v211 offset:29824
	ds_read_b128 v[8:11], v211 offset:46208
	ds_read_b128 v[12:15], v211 offset:38016
	s_waitcnt lgkmcnt(3)
	v_pk_add_f32 v[2:3], v[2:3], 0 op_sel_hi:[1,0]
	v_pk_add_f32 v[0:1], v[0:1], 0 op_sel_hi:[1,0]
	s_waitcnt lgkmcnt(2)
	v_pk_add_f32 v[6:7], v[2:3], v[6:7]
	v_pk_add_f32 v[4:5], v[0:1], v[4:5]
	ds_read_b128 v[0:3], v140 offset:19584
	s_waitcnt lgkmcnt(1)
	v_pk_add_f32 v[16:17], v[6:7], v[14:15]
	v_pk_add_f32 v[20:21], v[4:5], v[12:13]
	ds_read_b128 v[4:7], v140 offset:13440
	ds_read_b128 v[12:15], v138 offset:13312
	v_pk_add_f32 v[22:23], v[16:17], v[10:11]
	ds_read_b128 v[16:19], v140 offset:15488
	v_pk_add_f32 v[20:21], v[20:21], v[8:9]
	ds_read_b128 v[8:11], v140 offset:17536
	s_waitcnt lgkmcnt(2)
	v_pk_fma_f32 v[6:7], v[6:7], v[12:13], v[22:23] op_sel_hi:[1,0,1]
	v_pk_fma_f32 v[4:5], v[4:5], v[12:13], v[20:21] op_sel_hi:[1,0,1]
	s_waitcnt lgkmcnt(1)
	v_pk_fma_f32 v[6:7], v[18:19], v[12:13], v[6:7] op_sel:[0,1,0]
	v_pk_fma_f32 v[4:5], v[16:17], v[12:13], v[4:5] op_sel:[0,1,0]
	s_waitcnt lgkmcnt(0)
	v_pk_fma_f32 v[6:7], v[10:11], v[14:15], v[6:7] op_sel_hi:[1,0,1]
	v_pk_fma_f32 v[4:5], v[8:9], v[14:15], v[4:5] op_sel_hi:[1,0,1]
	v_mov_b32_e32 v8, v15
	v_pk_fma_f32 v[6:7], v[2:3], v[8:9], v[6:7] op_sel_hi:[1,0,1]
	v_pk_fma_f32 v[8:9], v[0:1], v[8:9], v[4:5] op_sel_hi:[1,0,1]
	v_mul_f32_e32 v1, v7, v7
	v_mul_f32_e32 v0, v9, v9
	v_fmac_f32_e32 v0, v8, v8
	v_fmac_f32_e32 v1, v6, v6
	v_add_f32_e32 v0, v0, v1
	ds_bpermute_b32 v1, v129, v0
	s_waitcnt lgkmcnt(0)
	v_add_f32_e32 v0, v0, v1
	ds_bpermute_b32 v1, v130, v0
	s_waitcnt lgkmcnt(0)
	v_add_f32_e32 v0, v0, v1
	ds_bpermute_b32 v1, v131, v0
	s_waitcnt lgkmcnt(0)
	v_add_f32_e32 v0, v0, v1
	ds_bpermute_b32 v1, v132, v0
	s_waitcnt lgkmcnt(0)
	v_add_f32_e32 v0, v0, v1
	ds_bpermute_b32 v1, v85, v0
	s_waitcnt lgkmcnt(0)
	v_add_f32_e32 v0, v0, v1
	ds_bpermute_b32 v1, v128, v0
	s_and_saveexec_b64 s[0:1], s[12:13]
	s_cbranch_execz .LBB0_383
	s_waitcnt lgkmcnt(0)
	v_add_f32_e32 v0, v0, v1
	ds_write_b32 v212, v0 offset:13376
	s_branch .LBB0_383
